# write-through (sc1) global stores on the large epilogue output streams (MLP1 hidden, residual out/hb) so the grid barrier release has less dirty L2 to write back
# speedup vs baseline: 1.0239x; 1.0001x over previous
.LBB0_1141:
	v_readfirstlane_b32 s40, v204
	s_lshr_b32 s40, s40, 6
	s_and_b32 s41, s40, 1
	s_bfe_u32 s42, s40, 0x10001
	s_lshr_b32 s43, s40, 2
	s_lshl_b32 s44, s4, 1
	s_add_i32 s44, s44, s42
	s_lshl_b32 s45, s44, 7
	s_lshl_b32 s46, s41, 6
	s_add_i32 s45, s45, s46
	s_lshl_b32 s46, s43, 7
	s_add_i32 s46, s46, s2
	s_lshl_b32 s47, s44, 1
	s_add_i32 s47, s47, s41
	v_readlane_b32 s36, v251, 50
	v_readlane_b32 s37, v251, 51
	v_readlane_b32 s38, v250, 9
	v_readlane_b32 s39, v250, 10
	v_readlane_b32 s50, v250, 11
	v_readlane_b32 s51, v250, 12
	s_add_u32 s34, s50, 0xf900000
	s_addc_u32 s35, s51, 0
	s_add_u32 s50, s50, 0x5800000
	s_addc_u32 s51, s51, 0
	s_lshl_b32 s48, s46, 12
	s_lshl_b32 s49, s45, 2
	s_add_u32 s48, s48, s49
	s_add_u32 s36, s36, s48
	s_addc_u32 s37, s37, 0
	s_add_u32 s38, s38, s48
	s_addc_u32 s39, s39, 0
	s_lshr_b32 s48, s48, 1
	s_add_u32 s50, s50, s48
	s_addc_u32 s51, s51, 0
	s_lshl_b32 s48, s46, 6
	s_lshl_b32 s49, s47, 2
	s_add_u32 s48, s48, s49
	s_add_u32 s34, s34, s48
	s_addc_u32 s35, s35, 0
	v_and_b32_e32 v249, 63, v204
	v_and_b32_e32 v198, 31, v249
	v_lshrrev_b32_e32 v199, 5, v249
	v_and_b32_e32 v208, 15, v249
	v_lshrrev_b32_e32 v209, 4, v249
	s_lshl_b32 s40, s40, 14
	v_and_b32_e32 v238, 15, v198
	v_xor_b32_e32 v238, v238, v199
	v_lshl_add_u32 v239, v198, 8, s40
	v_xor_b32_e32 v228, 0, v238
	v_lshl_add_u32 v228, v228, 4, v239
	v_xor_b32_e32 v229, 2, v238
	v_lshl_add_u32 v229, v229, 4, v239
	v_xor_b32_e32 v230, 4, v238
	v_lshl_add_u32 v230, v230, 4, v239
	v_xor_b32_e32 v231, 6, v238
	v_lshl_add_u32 v231, v231, 4, v239
	v_xor_b32_e32 v232, 8, v238
	v_lshl_add_u32 v232, v232, 4, v239
	v_xor_b32_e32 v233, 10, v238
	v_lshl_add_u32 v233, v233, 4, v239
	v_xor_b32_e32 v234, 12, v238
	v_lshl_add_u32 v234, v234, 4, v239
	v_xor_b32_e32 v235, 14, v238
	v_lshl_add_u32 v235, v235, 4, v239
	v_lshl_add_u32 v239, v209, 8, s40
	v_add_u32_e32 v210, 0, v209
	v_xor_b32_e32 v210, v210, v208
	v_lshl_add_u32 v210, v210, 4, v239
	v_add_u32_e32 v211, 4, v209
	v_xor_b32_e32 v211, v211, v208
	v_lshl_add_u32 v211, v211, 4, v239
	v_add_u32_e32 v215, 8, v209
	v_xor_b32_e32 v215, v215, v208
	v_lshl_add_u32 v215, v215, 4, v239
	v_add_u32_e32 v237, 12, v209
	v_xor_b32_e32 v237, v237, v208
	v_lshl_add_u32 v237, v237, 4, v239
	v_lshlrev_b32_e32 v247, 12, v209
	v_lshl_add_u32 v247, v208, 4, v247
	v_lshrrev_b32_e32 v248, 1, v247
	v_lshlrev_b32_e32 v249, 6, v209
	s_mov_b32 s48, 0x00010001
	s_mov_b32 s49, 0x00010001
	global_load_dwordx4 v[130:133], v247, s[36:37]
	s_add_u32 s36, s36, 0x4000
	s_addc_u32 s37, s37, 0
	global_load_dwordx4 v[134:137], v247, s[36:37]
	s_add_u32 s36, s36, 0x4000
	s_addc_u32 s37, s37, 0
	global_load_dwordx4 v[138:141], v247, s[36:37]
	s_add_u32 s36, s36, 0x4000
	s_addc_u32 s37, s37, 0
	global_load_dwordx4 v[142:145], v247, s[36:37]
	s_add_u32 s36, s36, 0x4000
	s_addc_u32 s37, s37, 0
	global_load_dwordx4 v[146:149], v247, s[36:37]
	s_add_u32 s36, s36, 0x4000
	s_addc_u32 s37, s37, 0
	global_load_dwordx4 v[150:153], v247, s[36:37]
	s_add_u32 s36, s36, 0x4000
	s_addc_u32 s37, s37, 0
	global_load_dwordx4 v[154:157], v247, s[36:37]
	s_add_u32 s36, s36, 0x4000
	s_addc_u32 s37, s37, 0
	global_load_dwordx4 v[158:161], v247, s[36:37]
	s_add_u32 s36, s36, 0x4000
	s_addc_u32 s37, s37, 0
	global_load_dwordx4 v[162:165], v247, s[36:37]
	s_add_u32 s36, s36, 0x4000
	s_addc_u32 s37, s37, 0
	global_load_dwordx4 v[166:169], v247, s[36:37]
	s_add_u32 s36, s36, 0x4000
	s_addc_u32 s37, s37, 0
	global_load_dwordx4 v[170:173], v247, s[36:37]
	s_add_u32 s36, s36, 0x4000
	s_addc_u32 s37, s37, 0
	global_load_dwordx4 v[174:177], v247, s[36:37]
	s_add_u32 s36, s36, 0x4000
	s_addc_u32 s37, s37, 0
	global_load_dwordx4 v[200:203], v247, s[36:37]
	s_add_u32 s36, s36, 0x4000
	s_addc_u32 s37, s37, 0
	global_load_dwordx4 v[216:219], v247, s[36:37]
	s_add_u32 s36, s36, 0x4000
	s_addc_u32 s37, s37, 0
	global_load_dwordx4 v[220:223], v247, s[36:37]
	s_add_u32 s36, s36, 0x4000
	s_addc_u32 s37, s37, 0
	global_load_dwordx4 v[224:227], v247, s[36:37]
	s_add_u32 s36, s36, 0x4000
	s_addc_u32 s37, s37, 0
	ds_write_b128 v228, v[82:85]
	ds_write_b128 v229, v[86:89]
	ds_write_b128 v230, v[90:93]
	ds_write_b128 v231, v[94:97]
	ds_write_b128 v232, v[114:117]
	ds_write_b128 v233, v[118:121]
	ds_write_b128 v234, v[122:125]
	ds_write_b128 v235, v[126:129]
	ds_write_b128 v228, v[66:69] offset:8192
	ds_write_b128 v229, v[70:73] offset:8192
	ds_write_b128 v230, v[74:77] offset:8192
	ds_write_b128 v231, v[78:81] offset:8192
	ds_write_b128 v232, v[98:101] offset:8192
	ds_write_b128 v233, v[102:105] offset:8192
	ds_write_b128 v234, v[106:109] offset:8192
	ds_write_b128 v235, v[110:113] offset:8192
	global_load_dwordx4 v[82:85], v247, s[36:37]
	s_add_u32 s36, s36, 0x4000
	s_addc_u32 s37, s37, 0
	global_load_dwordx4 v[86:89], v247, s[36:37]
	s_add_u32 s36, s36, 0x4000
	s_addc_u32 s37, s37, 0
	global_load_dwordx4 v[90:93], v247, s[36:37]
	s_add_u32 s36, s36, 0x4000
	s_addc_u32 s37, s37, 0
	global_load_dwordx4 v[94:97], v247, s[36:37]
	s_add_u32 s36, s36, 0x4000
	s_addc_u32 s37, s37, 0
	global_load_dwordx4 v[114:117], v247, s[36:37]
	s_add_u32 s36, s36, 0x4000
	s_addc_u32 s37, s37, 0
	global_load_dwordx4 v[118:121], v247, s[36:37]
	s_add_u32 s36, s36, 0x4000
	s_addc_u32 s37, s37, 0
	global_load_dwordx4 v[122:125], v247, s[36:37]
	s_add_u32 s36, s36, 0x4000
	s_addc_u32 s37, s37, 0
	global_load_dwordx4 v[126:129], v247, s[36:37]
	s_add_u32 s36, s36, 0x4000
	s_addc_u32 s37, s37, 0
	global_load_dwordx4 v[66:69], v247, s[36:37]
	s_add_u32 s36, s36, 0x4000
	s_addc_u32 s37, s37, 0
	global_load_dwordx4 v[70:73], v247, s[36:37]
	s_add_u32 s36, s36, 0x4000
	s_addc_u32 s37, s37, 0
	global_load_dwordx4 v[74:77], v247, s[36:37]
	s_add_u32 s36, s36, 0x4000
	s_addc_u32 s37, s37, 0
	global_load_dwordx4 v[78:81], v247, s[36:37]
	s_add_u32 s36, s36, 0x4000
	s_addc_u32 s37, s37, 0
	global_load_dwordx4 v[98:101], v247, s[36:37]
	s_add_u32 s36, s36, 0x4000
	s_addc_u32 s37, s37, 0
	global_load_dwordx4 v[102:105], v247, s[36:37]
	s_add_u32 s36, s36, 0x4000
	s_addc_u32 s37, s37, 0
	global_load_dwordx4 v[106:109], v247, s[36:37]
	s_add_u32 s36, s36, 0x4000
	s_addc_u32 s37, s37, 0
	global_load_dwordx4 v[110:113], v247, s[36:37]
	s_add_u32 s36, s36, 0x4000
	s_addc_u32 s37, s37, 0
	s_waitcnt lgkmcnt(0)
	ds_read_b128 v[228:231], v210 offset:0
	ds_read_b128 v[238:241], v211 offset:1024
	s_waitcnt vmcnt(31) lgkmcnt(1)
	v_pk_add_f32 v[130:131], v[228:229], v[130:131]
	v_pk_add_f32 v[132:133], v[230:231], v[132:133]
	v_pk_mul_f32 v[232:233], v[130:131], v[130:131]
	v_pk_mul_f32 v[234:235], v[132:133], v[132:133]
	ds_read_b128 v[228:231], v215 offset:2048
	v_add_f32_e32 v236, v232, v233
	v_add_f32_e32 v236, v234, v236
	v_add_f32_e32 v236, v235, v236
	global_store_dwordx4 v247, v[130:133], s[38:39] sc1
	v_cvt_pk_bf16_f32 v232, v130, v131
	v_cvt_pk_bf16_f32 v233, v132, v133
	v_add_f32_dpp v236, v236, v236 quad_perm:[1,0,3,2] row_mask:0xf bank_mask:0xf
	global_store_dwordx2 v248, v[232:233], s[50:51] sc1
	s_add_u32 s38, s38, 0x4000
	s_addc_u32 s39, s39, 0
	v_add_f32_dpp v236, v236, v236 quad_perm:[2,3,0,1] row_mask:0xf bank_mask:0xf
	s_add_u32 s50, s50, 0x2000
	s_addc_u32 s51, s51, 0
	v_add_f32_dpp v236, v236, v236 row_half_mirror row_mask:0xf bank_mask:0xf
	s_nop 1
	v_add_f32_dpp v236, v236, v236 row_mirror row_mask:0xf bank_mask:0xf
	s_mov_b64 exec, s[48:49]
	global_store_dword v249, v236, s[34:35] offset:0
	s_mov_b64 exec, -1
	s_waitcnt vmcnt(33) lgkmcnt(1)
	v_pk_add_f32 v[134:135], v[238:239], v[134:135]
	v_pk_add_f32 v[136:137], v[240:241], v[136:137]
	v_pk_mul_f32 v[242:243], v[134:135], v[134:135]
	v_pk_mul_f32 v[244:245], v[136:137], v[136:137]
	ds_read_b128 v[238:241], v237 offset:3072
	v_add_f32_e32 v246, v242, v243
	v_add_f32_e32 v246, v244, v246
	v_add_f32_e32 v246, v245, v246
	global_store_dwordx4 v247, v[134:137], s[38:39] sc1
	v_cvt_pk_bf16_f32 v242, v134, v135
	v_cvt_pk_bf16_f32 v243, v136, v137
	v_add_f32_dpp v246, v246, v246 quad_perm:[1,0,3,2] row_mask:0xf bank_mask:0xf
	global_store_dwordx2 v248, v[242:243], s[50:51] sc1
	s_add_u32 s38, s38, 0x4000
	s_addc_u32 s39, s39, 0
	v_add_f32_dpp v246, v246, v246 quad_perm:[2,3,0,1] row_mask:0xf bank_mask:0xf
	s_add_u32 s50, s50, 0x2000
	s_addc_u32 s51, s51, 0
	v_add_f32_dpp v246, v246, v246 row_half_mirror row_mask:0xf bank_mask:0xf
	s_nop 1
	v_add_f32_dpp v246, v246, v246 row_mirror row_mask:0xf bank_mask:0xf
	s_mov_b64 exec, s[48:49]
	global_store_dword v249, v246, s[34:35] offset:256
	s_mov_b64 exec, -1
	s_waitcnt vmcnt(35) lgkmcnt(1)
	v_pk_add_f32 v[138:139], v[228:229], v[138:139]
	v_pk_add_f32 v[140:141], v[230:231], v[140:141]
	v_pk_mul_f32 v[232:233], v[138:139], v[138:139]
	v_pk_mul_f32 v[234:235], v[140:141], v[140:141]
	ds_read_b128 v[228:231], v210 offset:4096
	v_add_f32_e32 v236, v232, v233
	v_add_f32_e32 v236, v234, v236
	v_add_f32_e32 v236, v235, v236
	global_store_dwordx4 v247, v[138:141], s[38:39] sc1
	v_cvt_pk_bf16_f32 v232, v138, v139
	v_cvt_pk_bf16_f32 v233, v140, v141
	v_add_f32_dpp v236, v236, v236 quad_perm:[1,0,3,2] row_mask:0xf bank_mask:0xf
	global_store_dwordx2 v248, v[232:233], s[50:51] sc1
	s_add_u32 s38, s38, 0x4000
	s_addc_u32 s39, s39, 0
	v_add_f32_dpp v236, v236, v236 quad_perm:[2,3,0,1] row_mask:0xf bank_mask:0xf
	s_add_u32 s50, s50, 0x2000
	s_addc_u32 s51, s51, 0
	v_add_f32_dpp v236, v236, v236 row_half_mirror row_mask:0xf bank_mask:0xf
	s_nop 1
	v_add_f32_dpp v236, v236, v236 row_mirror row_mask:0xf bank_mask:0xf
	s_mov_b64 exec, s[48:49]
	global_store_dword v249, v236, s[34:35] offset:512
	s_mov_b64 exec, -1
	s_waitcnt vmcnt(37) lgkmcnt(1)
	v_pk_add_f32 v[142:143], v[238:239], v[142:143]
	v_pk_add_f32 v[144:145], v[240:241], v[144:145]
	v_pk_mul_f32 v[242:243], v[142:143], v[142:143]
	v_pk_mul_f32 v[244:245], v[144:145], v[144:145]
	ds_read_b128 v[238:241], v211 offset:5120
	v_add_f32_e32 v246, v242, v243
	v_add_f32_e32 v246, v244, v246
	v_add_f32_e32 v246, v245, v246
	global_store_dwordx4 v247, v[142:145], s[38:39] sc1
	v_cvt_pk_bf16_f32 v242, v142, v143
	v_cvt_pk_bf16_f32 v243, v144, v145
	v_add_f32_dpp v246, v246, v246 quad_perm:[1,0,3,2] row_mask:0xf bank_mask:0xf
	global_store_dwordx2 v248, v[242:243], s[50:51] sc1
	s_add_u32 s38, s38, 0x4000
	s_addc_u32 s39, s39, 0
	v_add_f32_dpp v246, v246, v246 quad_perm:[2,3,0,1] row_mask:0xf bank_mask:0xf
	s_add_u32 s50, s50, 0x2000
	s_addc_u32 s51, s51, 0
	v_add_f32_dpp v246, v246, v246 row_half_mirror row_mask:0xf bank_mask:0xf
	s_nop 1
	v_add_f32_dpp v246, v246, v246 row_mirror row_mask:0xf bank_mask:0xf
	s_mov_b64 exec, s[48:49]
	global_store_dword v249, v246, s[34:35] offset:768
	s_mov_b64 exec, -1
	s_waitcnt vmcnt(39) lgkmcnt(1)
	v_pk_add_f32 v[146:147], v[228:229], v[146:147]
	v_pk_add_f32 v[148:149], v[230:231], v[148:149]
	v_pk_mul_f32 v[232:233], v[146:147], v[146:147]
	v_pk_mul_f32 v[234:235], v[148:149], v[148:149]
	ds_read_b128 v[228:231], v215 offset:6144
	v_add_f32_e32 v236, v232, v233
	v_add_f32_e32 v236, v234, v236
	v_add_f32_e32 v236, v235, v236
	global_store_dwordx4 v247, v[146:149], s[38:39] sc1
	v_cvt_pk_bf16_f32 v232, v146, v147
	v_cvt_pk_bf16_f32 v233, v148, v149
	v_add_f32_dpp v236, v236, v236 quad_perm:[1,0,3,2] row_mask:0xf bank_mask:0xf
	global_store_dwordx2 v248, v[232:233], s[50:51] sc1
	s_add_u32 s38, s38, 0x4000
	s_addc_u32 s39, s39, 0
	v_add_f32_dpp v236, v236, v236 quad_perm:[2,3,0,1] row_mask:0xf bank_mask:0xf
	s_add_u32 s50, s50, 0x2000
	s_addc_u32 s51, s51, 0
	v_add_f32_dpp v236, v236, v236 row_half_mirror row_mask:0xf bank_mask:0xf
	s_nop 1
	v_add_f32_dpp v236, v236, v236 row_mirror row_mask:0xf bank_mask:0xf
	s_mov_b64 exec, s[48:49]
	global_store_dword v249, v236, s[34:35] offset:1024
	s_mov_b64 exec, -1
	s_waitcnt vmcnt(41) lgkmcnt(1)
	v_pk_add_f32 v[150:151], v[238:239], v[150:151]
	v_pk_add_f32 v[152:153], v[240:241], v[152:153]
	v_pk_mul_f32 v[242:243], v[150:151], v[150:151]
	v_pk_mul_f32 v[244:245], v[152:153], v[152:153]
	ds_read_b128 v[238:241], v237 offset:7168
	v_add_f32_e32 v246, v242, v243
	v_add_f32_e32 v246, v244, v246
	v_add_f32_e32 v246, v245, v246
	global_store_dwordx4 v247, v[150:153], s[38:39] sc1
	v_cvt_pk_bf16_f32 v242, v150, v151
	v_cvt_pk_bf16_f32 v243, v152, v153
	v_add_f32_dpp v246, v246, v246 quad_perm:[1,0,3,2] row_mask:0xf bank_mask:0xf
	global_store_dwordx2 v248, v[242:243], s[50:51] sc1
	s_add_u32 s38, s38, 0x4000
	s_addc_u32 s39, s39, 0
	v_add_f32_dpp v246, v246, v246 quad_perm:[2,3,0,1] row_mask:0xf bank_mask:0xf
	s_add_u32 s50, s50, 0x2000
	s_addc_u32 s51, s51, 0
	v_add_f32_dpp v246, v246, v246 row_half_mirror row_mask:0xf bank_mask:0xf
	s_nop 1
	v_add_f32_dpp v246, v246, v246 row_mirror row_mask:0xf bank_mask:0xf
	s_mov_b64 exec, s[48:49]
	global_store_dword v249, v246, s[34:35] offset:1280
	s_mov_b64 exec, -1
	s_waitcnt vmcnt(43) lgkmcnt(1)
	v_pk_add_f32 v[154:155], v[228:229], v[154:155]
	v_pk_add_f32 v[156:157], v[230:231], v[156:157]
	v_pk_mul_f32 v[232:233], v[154:155], v[154:155]
	v_pk_mul_f32 v[234:235], v[156:157], v[156:157]
	ds_read_b128 v[228:231], v210 offset:8192
	v_add_f32_e32 v236, v232, v233
	v_add_f32_e32 v236, v234, v236
	v_add_f32_e32 v236, v235, v236
	global_store_dwordx4 v247, v[154:157], s[38:39] sc1
	v_cvt_pk_bf16_f32 v232, v154, v155
	v_cvt_pk_bf16_f32 v233, v156, v157
	v_add_f32_dpp v236, v236, v236 quad_perm:[1,0,3,2] row_mask:0xf bank_mask:0xf
	global_store_dwordx2 v248, v[232:233], s[50:51] sc1
	s_add_u32 s38, s38, 0x4000
	s_addc_u32 s39, s39, 0
	v_add_f32_dpp v236, v236, v236 quad_perm:[2,3,0,1] row_mask:0xf bank_mask:0xf
	s_add_u32 s50, s50, 0x2000
	s_addc_u32 s51, s51, 0
	v_add_f32_dpp v236, v236, v236 row_half_mirror row_mask:0xf bank_mask:0xf
	s_nop 1
	v_add_f32_dpp v236, v236, v236 row_mirror row_mask:0xf bank_mask:0xf
	s_mov_b64 exec, s[48:49]
	global_store_dword v249, v236, s[34:35] offset:1536
	s_mov_b64 exec, -1
	s_waitcnt vmcnt(45) lgkmcnt(1)
	v_pk_add_f32 v[158:159], v[238:239], v[158:159]
	v_pk_add_f32 v[160:161], v[240:241], v[160:161]
	v_pk_mul_f32 v[242:243], v[158:159], v[158:159]
	v_pk_mul_f32 v[244:245], v[160:161], v[160:161]
	ds_read_b128 v[238:241], v211 offset:9216
	v_add_f32_e32 v246, v242, v243
	v_add_f32_e32 v246, v244, v246
	v_add_f32_e32 v246, v245, v246
	global_store_dwordx4 v247, v[158:161], s[38:39] sc1
	v_cvt_pk_bf16_f32 v242, v158, v159
	v_cvt_pk_bf16_f32 v243, v160, v161
	v_add_f32_dpp v246, v246, v246 quad_perm:[1,0,3,2] row_mask:0xf bank_mask:0xf
	global_store_dwordx2 v248, v[242:243], s[50:51] sc1
	s_add_u32 s38, s38, 0x4000
	s_addc_u32 s39, s39, 0
	v_add_f32_dpp v246, v246, v246 quad_perm:[2,3,0,1] row_mask:0xf bank_mask:0xf
	s_add_u32 s50, s50, 0x2000
	s_addc_u32 s51, s51, 0
	v_add_f32_dpp v246, v246, v246 row_half_mirror row_mask:0xf bank_mask:0xf
	s_nop 1
	v_add_f32_dpp v246, v246, v246 row_mirror row_mask:0xf bank_mask:0xf
	s_mov_b64 exec, s[48:49]
	global_store_dword v249, v246, s[34:35] offset:1792
	s_mov_b64 exec, -1
	s_waitcnt vmcnt(47) lgkmcnt(1)
	v_pk_add_f32 v[162:163], v[228:229], v[162:163]
	v_pk_add_f32 v[164:165], v[230:231], v[164:165]
	v_pk_mul_f32 v[232:233], v[162:163], v[162:163]
	v_pk_mul_f32 v[234:235], v[164:165], v[164:165]
	ds_read_b128 v[228:231], v215 offset:10240
	v_add_f32_e32 v236, v232, v233
	v_add_f32_e32 v236, v234, v236
	v_add_f32_e32 v236, v235, v236
	global_store_dwordx4 v247, v[162:165], s[38:39] sc1
	v_cvt_pk_bf16_f32 v232, v162, v163
	v_cvt_pk_bf16_f32 v233, v164, v165
	v_add_f32_dpp v236, v236, v236 quad_perm:[1,0,3,2] row_mask:0xf bank_mask:0xf
	global_store_dwordx2 v248, v[232:233], s[50:51] sc1
	s_add_u32 s38, s38, 0x4000
	s_addc_u32 s39, s39, 0
	v_add_f32_dpp v236, v236, v236 quad_perm:[2,3,0,1] row_mask:0xf bank_mask:0xf
	s_add_u32 s50, s50, 0x2000
	s_addc_u32 s51, s51, 0
	v_add_f32_dpp v236, v236, v236 row_half_mirror row_mask:0xf bank_mask:0xf
	s_nop 1
	v_add_f32_dpp v236, v236, v236 row_mirror row_mask:0xf bank_mask:0xf
	s_mov_b64 exec, s[48:49]
	global_store_dword v249, v236, s[34:35] offset:2048
	s_mov_b64 exec, -1
	s_waitcnt vmcnt(49) lgkmcnt(1)
	v_pk_add_f32 v[166:167], v[238:239], v[166:167]
	v_pk_add_f32 v[168:169], v[240:241], v[168:169]
	v_pk_mul_f32 v[242:243], v[166:167], v[166:167]
	v_pk_mul_f32 v[244:245], v[168:169], v[168:169]
	ds_read_b128 v[238:241], v237 offset:11264
	v_add_f32_e32 v246, v242, v243
	v_add_f32_e32 v246, v244, v246
	v_add_f32_e32 v246, v245, v246
	global_store_dwordx4 v247, v[166:169], s[38:39] sc1
	v_cvt_pk_bf16_f32 v242, v166, v167
	v_cvt_pk_bf16_f32 v243, v168, v169
	v_add_f32_dpp v246, v246, v246 quad_perm:[1,0,3,2] row_mask:0xf bank_mask:0xf
	global_store_dwordx2 v248, v[242:243], s[50:51] sc1
	s_add_u32 s38, s38, 0x4000
	s_addc_u32 s39, s39, 0
	v_add_f32_dpp v246, v246, v246 quad_perm:[2,3,0,1] row_mask:0xf bank_mask:0xf
	s_add_u32 s50, s50, 0x2000
	s_addc_u32 s51, s51, 0
	v_add_f32_dpp v246, v246, v246 row_half_mirror row_mask:0xf bank_mask:0xf
	s_nop 1
	v_add_f32_dpp v246, v246, v246 row_mirror row_mask:0xf bank_mask:0xf
	s_mov_b64 exec, s[48:49]
	global_store_dword v249, v246, s[34:35] offset:2304
	s_mov_b64 exec, -1
	s_waitcnt vmcnt(51) lgkmcnt(1)
	v_pk_add_f32 v[170:171], v[228:229], v[170:171]
	v_pk_add_f32 v[172:173], v[230:231], v[172:173]
	v_pk_mul_f32 v[232:233], v[170:171], v[170:171]
	v_pk_mul_f32 v[234:235], v[172:173], v[172:173]
	ds_read_b128 v[228:231], v210 offset:12288
	v_add_f32_e32 v236, v232, v233
	v_add_f32_e32 v236, v234, v236
	v_add_f32_e32 v236, v235, v236
	global_store_dwordx4 v247, v[170:173], s[38:39] sc1
	v_cvt_pk_bf16_f32 v232, v170, v171
	v_cvt_pk_bf16_f32 v233, v172, v173
	v_add_f32_dpp v236, v236, v236 quad_perm:[1,0,3,2] row_mask:0xf bank_mask:0xf
	global_store_dwordx2 v248, v[232:233], s[50:51] sc1
	s_add_u32 s38, s38, 0x4000
	s_addc_u32 s39, s39, 0
	v_add_f32_dpp v236, v236, v236 quad_perm:[2,3,0,1] row_mask:0xf bank_mask:0xf
	s_add_u32 s50, s50, 0x2000
	s_addc_u32 s51, s51, 0
	v_add_f32_dpp v236, v236, v236 row_half_mirror row_mask:0xf bank_mask:0xf
	s_nop 1
	v_add_f32_dpp v236, v236, v236 row_mirror row_mask:0xf bank_mask:0xf
	s_mov_b64 exec, s[48:49]
	global_store_dword v249, v236, s[34:35] offset:2560
	s_mov_b64 exec, -1
	s_waitcnt vmcnt(53) lgkmcnt(1)
	v_pk_add_f32 v[174:175], v[238:239], v[174:175]
	v_pk_add_f32 v[176:177], v[240:241], v[176:177]
	v_pk_mul_f32 v[242:243], v[174:175], v[174:175]
	v_pk_mul_f32 v[244:245], v[176:177], v[176:177]
	ds_read_b128 v[238:241], v211 offset:13312
	v_add_f32_e32 v246, v242, v243
	v_add_f32_e32 v246, v244, v246
	v_add_f32_e32 v246, v245, v246
	global_store_dwordx4 v247, v[174:177], s[38:39] sc1
	v_cvt_pk_bf16_f32 v242, v174, v175
	v_cvt_pk_bf16_f32 v243, v176, v177
	v_add_f32_dpp v246, v246, v246 quad_perm:[1,0,3,2] row_mask:0xf bank_mask:0xf
	global_store_dwordx2 v248, v[242:243], s[50:51] sc1
	s_add_u32 s38, s38, 0x4000
	s_addc_u32 s39, s39, 0
	v_add_f32_dpp v246, v246, v246 quad_perm:[2,3,0,1] row_mask:0xf bank_mask:0xf
	s_add_u32 s50, s50, 0x2000
	s_addc_u32 s51, s51, 0
	v_add_f32_dpp v246, v246, v246 row_half_mirror row_mask:0xf bank_mask:0xf
	s_nop 1
	v_add_f32_dpp v246, v246, v246 row_mirror row_mask:0xf bank_mask:0xf
	s_mov_b64 exec, s[48:49]
	global_store_dword v249, v246, s[34:35] offset:2816
	s_mov_b64 exec, -1
	s_waitcnt vmcnt(55) lgkmcnt(1)
	v_pk_add_f32 v[200:201], v[228:229], v[200:201]
	v_pk_add_f32 v[202:203], v[230:231], v[202:203]
	v_pk_mul_f32 v[232:233], v[200:201], v[200:201]
	v_pk_mul_f32 v[234:235], v[202:203], v[202:203]
	ds_read_b128 v[228:231], v215 offset:14336
	v_add_f32_e32 v236, v232, v233
	v_add_f32_e32 v236, v234, v236
	v_add_f32_e32 v236, v235, v236
	global_store_dwordx4 v247, v[200:203], s[38:39] sc1
	v_cvt_pk_bf16_f32 v232, v200, v201
	v_cvt_pk_bf16_f32 v233, v202, v203
	v_add_f32_dpp v236, v236, v236 quad_perm:[1,0,3,2] row_mask:0xf bank_mask:0xf
	global_store_dwordx2 v248, v[232:233], s[50:51] sc1
	s_add_u32 s38, s38, 0x4000
	s_addc_u32 s39, s39, 0
	v_add_f32_dpp v236, v236, v236 quad_perm:[2,3,0,1] row_mask:0xf bank_mask:0xf
	s_add_u32 s50, s50, 0x2000
	s_addc_u32 s51, s51, 0
	v_add_f32_dpp v236, v236, v236 row_half_mirror row_mask:0xf bank_mask:0xf
	s_nop 1
	v_add_f32_dpp v236, v236, v236 row_mirror row_mask:0xf bank_mask:0xf
	s_mov_b64 exec, s[48:49]
	global_store_dword v249, v236, s[34:35] offset:3072
	s_mov_b64 exec, -1
	s_waitcnt vmcnt(57) lgkmcnt(1)
	v_pk_add_f32 v[216:217], v[238:239], v[216:217]
	v_pk_add_f32 v[218:219], v[240:241], v[218:219]
	v_pk_mul_f32 v[242:243], v[216:217], v[216:217]
	v_pk_mul_f32 v[244:245], v[218:219], v[218:219]
	ds_read_b128 v[238:241], v237 offset:15360
	v_add_f32_e32 v246, v242, v243
	v_add_f32_e32 v246, v244, v246
	v_add_f32_e32 v246, v245, v246
	global_store_dwordx4 v247, v[216:219], s[38:39] sc1
	v_cvt_pk_bf16_f32 v242, v216, v217
	v_cvt_pk_bf16_f32 v243, v218, v219
	v_add_f32_dpp v246, v246, v246 quad_perm:[1,0,3,2] row_mask:0xf bank_mask:0xf
	global_store_dwordx2 v248, v[242:243], s[50:51] sc1
	s_add_u32 s38, s38, 0x4000
	s_addc_u32 s39, s39, 0
	v_add_f32_dpp v246, v246, v246 quad_perm:[2,3,0,1] row_mask:0xf bank_mask:0xf
	s_add_u32 s50, s50, 0x2000
	s_addc_u32 s51, s51, 0
	v_add_f32_dpp v246, v246, v246 row_half_mirror row_mask:0xf bank_mask:0xf
	s_nop 1
	v_add_f32_dpp v246, v246, v246 row_mirror row_mask:0xf bank_mask:0xf
	s_mov_b64 exec, s[48:49]
	global_store_dword v249, v246, s[34:35] offset:3328
	s_mov_b64 exec, -1
	s_waitcnt vmcnt(59) lgkmcnt(1)
	v_pk_add_f32 v[220:221], v[228:229], v[220:221]
	v_pk_add_f32 v[222:223], v[230:231], v[222:223]
	v_pk_mul_f32 v[232:233], v[220:221], v[220:221]
	v_pk_mul_f32 v[234:235], v[222:223], v[222:223]
	v_add_f32_e32 v236, v232, v233
	v_add_f32_e32 v236, v234, v236
	v_add_f32_e32 v236, v235, v236
	global_store_dwordx4 v247, v[220:223], s[38:39] sc1
	v_cvt_pk_bf16_f32 v232, v220, v221
	v_cvt_pk_bf16_f32 v233, v222, v223
	v_add_f32_dpp v236, v236, v236 quad_perm:[1,0,3,2] row_mask:0xf bank_mask:0xf
	global_store_dwordx2 v248, v[232:233], s[50:51] sc1
	s_add_u32 s38, s38, 0x4000
	s_addc_u32 s39, s39, 0
	v_add_f32_dpp v236, v236, v236 quad_perm:[2,3,0,1] row_mask:0xf bank_mask:0xf
	s_add_u32 s50, s50, 0x2000
	s_addc_u32 s51, s51, 0
	v_add_f32_dpp v236, v236, v236 row_half_mirror row_mask:0xf bank_mask:0xf
	s_nop 1
	v_add_f32_dpp v236, v236, v236 row_mirror row_mask:0xf bank_mask:0xf
	s_mov_b64 exec, s[48:49]
	global_store_dword v249, v236, s[34:35] offset:3584
	s_mov_b64 exec, -1
	s_waitcnt vmcnt(61) lgkmcnt(0)
	v_pk_add_f32 v[224:225], v[238:239], v[224:225]
	v_pk_add_f32 v[226:227], v[240:241], v[226:227]
	v_pk_mul_f32 v[242:243], v[224:225], v[224:225]
	v_pk_mul_f32 v[244:245], v[226:227], v[226:227]
	v_add_f32_e32 v246, v242, v243
	v_add_f32_e32 v246, v244, v246
	v_add_f32_e32 v246, v245, v246
	global_store_dwordx4 v247, v[224:227], s[38:39] sc1
	v_cvt_pk_bf16_f32 v242, v224, v225
	v_cvt_pk_bf16_f32 v243, v226, v227
	v_add_f32_dpp v246, v246, v246 quad_perm:[1,0,3,2] row_mask:0xf bank_mask:0xf
	global_store_dwordx2 v248, v[242:243], s[50:51] sc1
	s_add_u32 s38, s38, 0x4000
	s_addc_u32 s39, s39, 0
	v_add_f32_dpp v246, v246, v246 quad_perm:[2,3,0,1] row_mask:0xf bank_mask:0xf
	s_add_u32 s50, s50, 0x2000
	s_addc_u32 s51, s51, 0
	v_add_f32_dpp v246, v246, v246 row_half_mirror row_mask:0xf bank_mask:0xf
	s_nop 1
	v_add_f32_dpp v246, v246, v246 row_mirror row_mask:0xf bank_mask:0xf
	s_mov_b64 exec, s[48:49]
	global_store_dword v249, v246, s[34:35] offset:3840
	s_mov_b64 exec, -1
	s_add_u32 s34, s34, 0x1000
	s_addc_u32 s35, s35, 0
	v_and_b32_e32 v238, 15, v198
	v_xor_b32_e32 v238, v238, v199
	v_lshl_add_u32 v239, v198, 8, s40
	v_xor_b32_e32 v228, 0, v238
	v_lshl_add_u32 v228, v228, 4, v239
	v_xor_b32_e32 v229, 2, v238
	v_lshl_add_u32 v229, v229, 4, v239
	v_xor_b32_e32 v230, 4, v238
	v_lshl_add_u32 v230, v230, 4, v239
	v_xor_b32_e32 v231, 6, v238
	v_lshl_add_u32 v231, v231, 4, v239
	v_xor_b32_e32 v232, 8, v238
	v_lshl_add_u32 v232, v232, 4, v239
	v_xor_b32_e32 v233, 10, v238
	v_lshl_add_u32 v233, v233, 4, v239
	v_xor_b32_e32 v234, 12, v238
	v_lshl_add_u32 v234, v234, 4, v239
	v_xor_b32_e32 v235, 14, v238
	v_lshl_add_u32 v235, v235, 4, v239
	ds_write_b128 v228, v[18:21]
	ds_write_b128 v229, v[22:25]
	ds_write_b128 v230, v[26:29]
	ds_write_b128 v231, v[30:33]
	ds_write_b128 v232, v[50:53]
	ds_write_b128 v233, v[54:57]
	ds_write_b128 v234, v[58:61]
	ds_write_b128 v235, v[62:65]
	ds_write_b128 v228, v[2:5] offset:8192
	ds_write_b128 v229, v[6:9] offset:8192
	ds_write_b128 v230, v[10:13] offset:8192
	ds_write_b128 v231, v[14:17] offset:8192
	ds_write_b128 v232, v[34:37] offset:8192
	ds_write_b128 v233, v[38:41] offset:8192
	ds_write_b128 v234, v[42:45] offset:8192
	ds_write_b128 v235, v[46:49] offset:8192
	s_waitcnt lgkmcnt(0)
	ds_read_b128 v[228:231], v210 offset:0
	ds_read_b128 v[238:241], v211 offset:1024
	s_waitcnt vmcnt(63) lgkmcnt(1)
	v_pk_add_f32 v[82:83], v[228:229], v[82:83]
	v_pk_add_f32 v[84:85], v[230:231], v[84:85]
	v_pk_mul_f32 v[232:233], v[82:83], v[82:83]
	v_pk_mul_f32 v[234:235], v[84:85], v[84:85]
	ds_read_b128 v[228:231], v215 offset:2048
	v_add_f32_e32 v236, v232, v233
	v_add_f32_e32 v236, v234, v236
	v_add_f32_e32 v236, v235, v236
	global_store_dwordx4 v247, v[82:85], s[38:39] sc1
	v_cvt_pk_bf16_f32 v232, v82, v83
	v_cvt_pk_bf16_f32 v233, v84, v85
	v_add_f32_dpp v236, v236, v236 quad_perm:[1,0,3,2] row_mask:0xf bank_mask:0xf
	global_store_dwordx2 v248, v[232:233], s[50:51] sc1
	s_add_u32 s38, s38, 0x4000
	s_addc_u32 s39, s39, 0
	v_add_f32_dpp v236, v236, v236 quad_perm:[2,3,0,1] row_mask:0xf bank_mask:0xf
	s_add_u32 s50, s50, 0x2000
	s_addc_u32 s51, s51, 0
	v_add_f32_dpp v236, v236, v236 row_half_mirror row_mask:0xf bank_mask:0xf
	s_nop 1
	v_add_f32_dpp v236, v236, v236 row_mirror row_mask:0xf bank_mask:0xf
	s_mov_b64 exec, s[48:49]
	global_store_dword v249, v236, s[34:35] offset:0
	s_mov_b64 exec, -1
	s_waitcnt vmcnt(63) lgkmcnt(1)
	v_pk_add_f32 v[86:87], v[238:239], v[86:87]
	v_pk_add_f32 v[88:89], v[240:241], v[88:89]
	v_pk_mul_f32 v[242:243], v[86:87], v[86:87]
	v_pk_mul_f32 v[244:245], v[88:89], v[88:89]
	ds_read_b128 v[238:241], v237 offset:3072
	v_add_f32_e32 v246, v242, v243
	v_add_f32_e32 v246, v244, v246
	v_add_f32_e32 v246, v245, v246
	global_store_dwordx4 v247, v[86:89], s[38:39] sc1
	v_cvt_pk_bf16_f32 v242, v86, v87
	v_cvt_pk_bf16_f32 v243, v88, v89
	v_add_f32_dpp v246, v246, v246 quad_perm:[1,0,3,2] row_mask:0xf bank_mask:0xf
	global_store_dwordx2 v248, v[242:243], s[50:51] sc1
	s_add_u32 s38, s38, 0x4000
	s_addc_u32 s39, s39, 0
	v_add_f32_dpp v246, v246, v246 quad_perm:[2,3,0,1] row_mask:0xf bank_mask:0xf
	s_add_u32 s50, s50, 0x2000
	s_addc_u32 s51, s51, 0
	v_add_f32_dpp v246, v246, v246 row_half_mirror row_mask:0xf bank_mask:0xf
	s_nop 1
	v_add_f32_dpp v246, v246, v246 row_mirror row_mask:0xf bank_mask:0xf
	s_mov_b64 exec, s[48:49]
	global_store_dword v249, v246, s[34:35] offset:256
	s_mov_b64 exec, -1
	s_waitcnt vmcnt(63) lgkmcnt(1)
	v_pk_add_f32 v[90:91], v[228:229], v[90:91]
	v_pk_add_f32 v[92:93], v[230:231], v[92:93]
	v_pk_mul_f32 v[232:233], v[90:91], v[90:91]
	v_pk_mul_f32 v[234:235], v[92:93], v[92:93]
	ds_read_b128 v[228:231], v210 offset:4096
	v_add_f32_e32 v236, v232, v233
	v_add_f32_e32 v236, v234, v236
	v_add_f32_e32 v236, v235, v236
	global_store_dwordx4 v247, v[90:93], s[38:39] sc1
	v_cvt_pk_bf16_f32 v232, v90, v91
	v_cvt_pk_bf16_f32 v233, v92, v93
	v_add_f32_dpp v236, v236, v236 quad_perm:[1,0,3,2] row_mask:0xf bank_mask:0xf
	global_store_dwordx2 v248, v[232:233], s[50:51] sc1
	s_add_u32 s38, s38, 0x4000
	s_addc_u32 s39, s39, 0
	v_add_f32_dpp v236, v236, v236 quad_perm:[2,3,0,1] row_mask:0xf bank_mask:0xf
	s_add_u32 s50, s50, 0x2000
	s_addc_u32 s51, s51, 0
	v_add_f32_dpp v236, v236, v236 row_half_mirror row_mask:0xf bank_mask:0xf
	s_nop 1
	v_add_f32_dpp v236, v236, v236 row_mirror row_mask:0xf bank_mask:0xf
	s_mov_b64 exec, s[48:49]
	global_store_dword v249, v236, s[34:35] offset:512
	s_mov_b64 exec, -1
	s_waitcnt vmcnt(63) lgkmcnt(1)
	v_pk_add_f32 v[94:95], v[238:239], v[94:95]
	v_pk_add_f32 v[96:97], v[240:241], v[96:97]
	v_pk_mul_f32 v[242:243], v[94:95], v[94:95]
	v_pk_mul_f32 v[244:245], v[96:97], v[96:97]
	ds_read_b128 v[238:241], v211 offset:5120
	v_add_f32_e32 v246, v242, v243
	v_add_f32_e32 v246, v244, v246
	v_add_f32_e32 v246, v245, v246
	global_store_dwordx4 v247, v[94:97], s[38:39] sc1
	v_cvt_pk_bf16_f32 v242, v94, v95
	v_cvt_pk_bf16_f32 v243, v96, v97
	v_add_f32_dpp v246, v246, v246 quad_perm:[1,0,3,2] row_mask:0xf bank_mask:0xf
	global_store_dwordx2 v248, v[242:243], s[50:51] sc1
	s_add_u32 s38, s38, 0x4000
	s_addc_u32 s39, s39, 0
	v_add_f32_dpp v246, v246, v246 quad_perm:[2,3,0,1] row_mask:0xf bank_mask:0xf
	s_add_u32 s50, s50, 0x2000
	s_addc_u32 s51, s51, 0
	v_add_f32_dpp v246, v246, v246 row_half_mirror row_mask:0xf bank_mask:0xf
	s_nop 1
	v_add_f32_dpp v246, v246, v246 row_mirror row_mask:0xf bank_mask:0xf
	s_mov_b64 exec, s[48:49]
	global_store_dword v249, v246, s[34:35] offset:768
	s_mov_b64 exec, -1
	s_waitcnt vmcnt(63) lgkmcnt(1)
	v_pk_add_f32 v[114:115], v[228:229], v[114:115]
	v_pk_add_f32 v[116:117], v[230:231], v[116:117]
	v_pk_mul_f32 v[232:233], v[114:115], v[114:115]
	v_pk_mul_f32 v[234:235], v[116:117], v[116:117]
	ds_read_b128 v[228:231], v215 offset:6144
	v_add_f32_e32 v236, v232, v233
	v_add_f32_e32 v236, v234, v236
	v_add_f32_e32 v236, v235, v236
	global_store_dwordx4 v247, v[114:117], s[38:39] sc1
	v_cvt_pk_bf16_f32 v232, v114, v115
	v_cvt_pk_bf16_f32 v233, v116, v117
	v_add_f32_dpp v236, v236, v236 quad_perm:[1,0,3,2] row_mask:0xf bank_mask:0xf
	global_store_dwordx2 v248, v[232:233], s[50:51] sc1
	s_add_u32 s38, s38, 0x4000
	s_addc_u32 s39, s39, 0
	v_add_f32_dpp v236, v236, v236 quad_perm:[2,3,0,1] row_mask:0xf bank_mask:0xf
	s_add_u32 s50, s50, 0x2000
	s_addc_u32 s51, s51, 0
	v_add_f32_dpp v236, v236, v236 row_half_mirror row_mask:0xf bank_mask:0xf
	s_nop 1
	v_add_f32_dpp v236, v236, v236 row_mirror row_mask:0xf bank_mask:0xf
	s_mov_b64 exec, s[48:49]
	global_store_dword v249, v236, s[34:35] offset:1024
	s_mov_b64 exec, -1
	s_waitcnt vmcnt(63) lgkmcnt(1)
	v_pk_add_f32 v[118:119], v[238:239], v[118:119]
	v_pk_add_f32 v[120:121], v[240:241], v[120:121]
	v_pk_mul_f32 v[242:243], v[118:119], v[118:119]
	v_pk_mul_f32 v[244:245], v[120:121], v[120:121]
	ds_read_b128 v[238:241], v237 offset:7168
	v_add_f32_e32 v246, v242, v243
	v_add_f32_e32 v246, v244, v246
	v_add_f32_e32 v246, v245, v246
	global_store_dwordx4 v247, v[118:121], s[38:39] sc1
	v_cvt_pk_bf16_f32 v242, v118, v119
	v_cvt_pk_bf16_f32 v243, v120, v121
	v_add_f32_dpp v246, v246, v246 quad_perm:[1,0,3,2] row_mask:0xf bank_mask:0xf
	global_store_dwordx2 v248, v[242:243], s[50:51] sc1
	s_add_u32 s38, s38, 0x4000
	s_addc_u32 s39, s39, 0
	v_add_f32_dpp v246, v246, v246 quad_perm:[2,3,0,1] row_mask:0xf bank_mask:0xf
	s_add_u32 s50, s50, 0x2000
	s_addc_u32 s51, s51, 0
	v_add_f32_dpp v246, v246, v246 row_half_mirror row_mask:0xf bank_mask:0xf
	s_nop 1
	v_add_f32_dpp v246, v246, v246 row_mirror row_mask:0xf bank_mask:0xf
	s_mov_b64 exec, s[48:49]
	global_store_dword v249, v246, s[34:35] offset:1280
	s_mov_b64 exec, -1
	s_waitcnt vmcnt(63) lgkmcnt(1)
	v_pk_add_f32 v[122:123], v[228:229], v[122:123]
	v_pk_add_f32 v[124:125], v[230:231], v[124:125]
	v_pk_mul_f32 v[232:233], v[122:123], v[122:123]
	v_pk_mul_f32 v[234:235], v[124:125], v[124:125]
	ds_read_b128 v[228:231], v210 offset:8192
	v_add_f32_e32 v236, v232, v233
	v_add_f32_e32 v236, v234, v236
	v_add_f32_e32 v236, v235, v236
	global_store_dwordx4 v247, v[122:125], s[38:39] sc1
	v_cvt_pk_bf16_f32 v232, v122, v123
	v_cvt_pk_bf16_f32 v233, v124, v125
	v_add_f32_dpp v236, v236, v236 quad_perm:[1,0,3,2] row_mask:0xf bank_mask:0xf
	global_store_dwordx2 v248, v[232:233], s[50:51] sc1
	s_add_u32 s38, s38, 0x4000
	s_addc_u32 s39, s39, 0
	v_add_f32_dpp v236, v236, v236 quad_perm:[2,3,0,1] row_mask:0xf bank_mask:0xf
	s_add_u32 s50, s50, 0x2000
	s_addc_u32 s51, s51, 0
	v_add_f32_dpp v236, v236, v236 row_half_mirror row_mask:0xf bank_mask:0xf
	s_nop 1
	v_add_f32_dpp v236, v236, v236 row_mirror row_mask:0xf bank_mask:0xf
	s_mov_b64 exec, s[48:49]
	global_store_dword v249, v236, s[34:35] offset:1536
	s_mov_b64 exec, -1
	s_waitcnt vmcnt(63) lgkmcnt(1)
	v_pk_add_f32 v[126:127], v[238:239], v[126:127]
	v_pk_add_f32 v[128:129], v[240:241], v[128:129]
	v_pk_mul_f32 v[242:243], v[126:127], v[126:127]
	v_pk_mul_f32 v[244:245], v[128:129], v[128:129]
	ds_read_b128 v[238:241], v211 offset:9216
	v_add_f32_e32 v246, v242, v243
	v_add_f32_e32 v246, v244, v246
	v_add_f32_e32 v246, v245, v246
	global_store_dwordx4 v247, v[126:129], s[38:39] sc1
	v_cvt_pk_bf16_f32 v242, v126, v127
	v_cvt_pk_bf16_f32 v243, v128, v129
	v_add_f32_dpp v246, v246, v246 quad_perm:[1,0,3,2] row_mask:0xf bank_mask:0xf
	global_store_dwordx2 v248, v[242:243], s[50:51] sc1
	s_add_u32 s38, s38, 0x4000
	s_addc_u32 s39, s39, 0
	v_add_f32_dpp v246, v246, v246 quad_perm:[2,3,0,1] row_mask:0xf bank_mask:0xf
	s_add_u32 s50, s50, 0x2000
	s_addc_u32 s51, s51, 0
	v_add_f32_dpp v246, v246, v246 row_half_mirror row_mask:0xf bank_mask:0xf
	s_nop 1
	v_add_f32_dpp v246, v246, v246 row_mirror row_mask:0xf bank_mask:0xf
	s_mov_b64 exec, s[48:49]
	global_store_dword v249, v246, s[34:35] offset:1792
	s_mov_b64 exec, -1
	s_waitcnt vmcnt(63) lgkmcnt(1)
	v_pk_add_f32 v[66:67], v[228:229], v[66:67]
	v_pk_add_f32 v[68:69], v[230:231], v[68:69]
	v_pk_mul_f32 v[232:233], v[66:67], v[66:67]
	v_pk_mul_f32 v[234:235], v[68:69], v[68:69]
	ds_read_b128 v[228:231], v215 offset:10240
	v_add_f32_e32 v236, v232, v233
	v_add_f32_e32 v236, v234, v236
	v_add_f32_e32 v236, v235, v236
	global_store_dwordx4 v247, v[66:69], s[38:39] sc1
	v_cvt_pk_bf16_f32 v232, v66, v67
	v_cvt_pk_bf16_f32 v233, v68, v69
	v_add_f32_dpp v236, v236, v236 quad_perm:[1,0,3,2] row_mask:0xf bank_mask:0xf
	global_store_dwordx2 v248, v[232:233], s[50:51] sc1
	s_add_u32 s38, s38, 0x4000
	s_addc_u32 s39, s39, 0
	v_add_f32_dpp v236, v236, v236 quad_perm:[2,3,0,1] row_mask:0xf bank_mask:0xf
	s_add_u32 s50, s50, 0x2000
	s_addc_u32 s51, s51, 0
	v_add_f32_dpp v236, v236, v236 row_half_mirror row_mask:0xf bank_mask:0xf
	s_nop 1
	v_add_f32_dpp v236, v236, v236 row_mirror row_mask:0xf bank_mask:0xf
	s_mov_b64 exec, s[48:49]
	global_store_dword v249, v236, s[34:35] offset:2048
	s_mov_b64 exec, -1
	s_waitcnt vmcnt(63) lgkmcnt(1)
	v_pk_add_f32 v[70:71], v[238:239], v[70:71]
	v_pk_add_f32 v[72:73], v[240:241], v[72:73]
	v_pk_mul_f32 v[242:243], v[70:71], v[70:71]
	v_pk_mul_f32 v[244:245], v[72:73], v[72:73]
	ds_read_b128 v[238:241], v237 offset:11264
	v_add_f32_e32 v246, v242, v243
	v_add_f32_e32 v246, v244, v246
	v_add_f32_e32 v246, v245, v246
	global_store_dwordx4 v247, v[70:73], s[38:39] sc1
	v_cvt_pk_bf16_f32 v242, v70, v71
	v_cvt_pk_bf16_f32 v243, v72, v73
	v_add_f32_dpp v246, v246, v246 quad_perm:[1,0,3,2] row_mask:0xf bank_mask:0xf
	global_store_dwordx2 v248, v[242:243], s[50:51] sc1
	s_add_u32 s38, s38, 0x4000
	s_addc_u32 s39, s39, 0
	v_add_f32_dpp v246, v246, v246 quad_perm:[2,3,0,1] row_mask:0xf bank_mask:0xf
	s_add_u32 s50, s50, 0x2000
	s_addc_u32 s51, s51, 0
	v_add_f32_dpp v246, v246, v246 row_half_mirror row_mask:0xf bank_mask:0xf
	s_nop 1
	v_add_f32_dpp v246, v246, v246 row_mirror row_mask:0xf bank_mask:0xf
	s_mov_b64 exec, s[48:49]
	global_store_dword v249, v246, s[34:35] offset:2304
	s_mov_b64 exec, -1
	s_waitcnt vmcnt(63) lgkmcnt(1)
	v_pk_add_f32 v[74:75], v[228:229], v[74:75]
	v_pk_add_f32 v[76:77], v[230:231], v[76:77]
	v_pk_mul_f32 v[232:233], v[74:75], v[74:75]
	v_pk_mul_f32 v[234:235], v[76:77], v[76:77]
	ds_read_b128 v[228:231], v210 offset:12288
	v_add_f32_e32 v236, v232, v233
	v_add_f32_e32 v236, v234, v236
	v_add_f32_e32 v236, v235, v236
	global_store_dwordx4 v247, v[74:77], s[38:39] sc1
	v_cvt_pk_bf16_f32 v232, v74, v75
	v_cvt_pk_bf16_f32 v233, v76, v77
	v_add_f32_dpp v236, v236, v236 quad_perm:[1,0,3,2] row_mask:0xf bank_mask:0xf
	global_store_dwordx2 v248, v[232:233], s[50:51] sc1
	s_add_u32 s38, s38, 0x4000
	s_addc_u32 s39, s39, 0
	v_add_f32_dpp v236, v236, v236 quad_perm:[2,3,0,1] row_mask:0xf bank_mask:0xf
	s_add_u32 s50, s50, 0x2000
	s_addc_u32 s51, s51, 0
	v_add_f32_dpp v236, v236, v236 row_half_mirror row_mask:0xf bank_mask:0xf
	s_nop 1
	v_add_f32_dpp v236, v236, v236 row_mirror row_mask:0xf bank_mask:0xf
	s_mov_b64 exec, s[48:49]
	global_store_dword v249, v236, s[34:35] offset:2560
	s_mov_b64 exec, -1
	s_waitcnt vmcnt(63) lgkmcnt(1)
	v_pk_add_f32 v[78:79], v[238:239], v[78:79]
	v_pk_add_f32 v[80:81], v[240:241], v[80:81]
	v_pk_mul_f32 v[242:243], v[78:79], v[78:79]
	v_pk_mul_f32 v[244:245], v[80:81], v[80:81]
	ds_read_b128 v[238:241], v211 offset:13312
	v_add_f32_e32 v246, v242, v243
	v_add_f32_e32 v246, v244, v246
	v_add_f32_e32 v246, v245, v246
	global_store_dwordx4 v247, v[78:81], s[38:39] sc1
	v_cvt_pk_bf16_f32 v242, v78, v79
	v_cvt_pk_bf16_f32 v243, v80, v81
	v_add_f32_dpp v246, v246, v246 quad_perm:[1,0,3,2] row_mask:0xf bank_mask:0xf
	global_store_dwordx2 v248, v[242:243], s[50:51] sc1
	s_add_u32 s38, s38, 0x4000
	s_addc_u32 s39, s39, 0
	v_add_f32_dpp v246, v246, v246 quad_perm:[2,3,0,1] row_mask:0xf bank_mask:0xf
	s_add_u32 s50, s50, 0x2000
	s_addc_u32 s51, s51, 0
	v_add_f32_dpp v246, v246, v246 row_half_mirror row_mask:0xf bank_mask:0xf
	s_nop 1
	v_add_f32_dpp v246, v246, v246 row_mirror row_mask:0xf bank_mask:0xf
	s_mov_b64 exec, s[48:49]
	global_store_dword v249, v246, s[34:35] offset:2816
	s_mov_b64 exec, -1
	s_waitcnt vmcnt(63) lgkmcnt(1)
	v_pk_add_f32 v[98:99], v[228:229], v[98:99]
	v_pk_add_f32 v[100:101], v[230:231], v[100:101]
	v_pk_mul_f32 v[232:233], v[98:99], v[98:99]
	v_pk_mul_f32 v[234:235], v[100:101], v[100:101]
	ds_read_b128 v[228:231], v215 offset:14336
	v_add_f32_e32 v236, v232, v233
	v_add_f32_e32 v236, v234, v236
	v_add_f32_e32 v236, v235, v236
	global_store_dwordx4 v247, v[98:101], s[38:39] sc1
	v_cvt_pk_bf16_f32 v232, v98, v99
	v_cvt_pk_bf16_f32 v233, v100, v101
	v_add_f32_dpp v236, v236, v236 quad_perm:[1,0,3,2] row_mask:0xf bank_mask:0xf
	global_store_dwordx2 v248, v[232:233], s[50:51] sc1
	s_add_u32 s38, s38, 0x4000
	s_addc_u32 s39, s39, 0
	v_add_f32_dpp v236, v236, v236 quad_perm:[2,3,0,1] row_mask:0xf bank_mask:0xf
	s_add_u32 s50, s50, 0x2000
	s_addc_u32 s51, s51, 0
	v_add_f32_dpp v236, v236, v236 row_half_mirror row_mask:0xf bank_mask:0xf
	s_nop 1
	v_add_f32_dpp v236, v236, v236 row_mirror row_mask:0xf bank_mask:0xf
	s_mov_b64 exec, s[48:49]
	global_store_dword v249, v236, s[34:35] offset:3072
	s_mov_b64 exec, -1
	s_waitcnt vmcnt(63) lgkmcnt(1)
	v_pk_add_f32 v[102:103], v[238:239], v[102:103]
	v_pk_add_f32 v[104:105], v[240:241], v[104:105]
	v_pk_mul_f32 v[242:243], v[102:103], v[102:103]
	v_pk_mul_f32 v[244:245], v[104:105], v[104:105]
	ds_read_b128 v[238:241], v237 offset:15360
	v_add_f32_e32 v246, v242, v243
	v_add_f32_e32 v246, v244, v246
	v_add_f32_e32 v246, v245, v246
	global_store_dwordx4 v247, v[102:105], s[38:39] sc1
	v_cvt_pk_bf16_f32 v242, v102, v103
	v_cvt_pk_bf16_f32 v243, v104, v105
	v_add_f32_dpp v246, v246, v246 quad_perm:[1,0,3,2] row_mask:0xf bank_mask:0xf
	global_store_dwordx2 v248, v[242:243], s[50:51] sc1
	s_add_u32 s38, s38, 0x4000
	s_addc_u32 s39, s39, 0
	v_add_f32_dpp v246, v246, v246 quad_perm:[2,3,0,1] row_mask:0xf bank_mask:0xf
	s_add_u32 s50, s50, 0x2000
	s_addc_u32 s51, s51, 0
	v_add_f32_dpp v246, v246, v246 row_half_mirror row_mask:0xf bank_mask:0xf
	s_nop 1
	v_add_f32_dpp v246, v246, v246 row_mirror row_mask:0xf bank_mask:0xf
	s_mov_b64 exec, s[48:49]
	global_store_dword v249, v246, s[34:35] offset:3328
	s_mov_b64 exec, -1
	s_waitcnt vmcnt(63) lgkmcnt(1)
	v_pk_add_f32 v[106:107], v[228:229], v[106:107]
	v_pk_add_f32 v[108:109], v[230:231], v[108:109]
	v_pk_mul_f32 v[232:233], v[106:107], v[106:107]
	v_pk_mul_f32 v[234:235], v[108:109], v[108:109]
	v_add_f32_e32 v236, v232, v233
	v_add_f32_e32 v236, v234, v236
	v_add_f32_e32 v236, v235, v236
	global_store_dwordx4 v247, v[106:109], s[38:39] sc1
	v_cvt_pk_bf16_f32 v232, v106, v107
	v_cvt_pk_bf16_f32 v233, v108, v109
	v_add_f32_dpp v236, v236, v236 quad_perm:[1,0,3,2] row_mask:0xf bank_mask:0xf
	global_store_dwordx2 v248, v[232:233], s[50:51] sc1
	s_add_u32 s38, s38, 0x4000
	s_addc_u32 s39, s39, 0
	v_add_f32_dpp v236, v236, v236 quad_perm:[2,3,0,1] row_mask:0xf bank_mask:0xf
	s_add_u32 s50, s50, 0x2000
	s_addc_u32 s51, s51, 0
	v_add_f32_dpp v236, v236, v236 row_half_mirror row_mask:0xf bank_mask:0xf
	s_nop 1
	v_add_f32_dpp v236, v236, v236 row_mirror row_mask:0xf bank_mask:0xf
	s_mov_b64 exec, s[48:49]
	global_store_dword v249, v236, s[34:35] offset:3584
	s_mov_b64 exec, -1
	s_waitcnt vmcnt(63) lgkmcnt(0)
	v_pk_add_f32 v[110:111], v[238:239], v[110:111]
	v_pk_add_f32 v[112:113], v[240:241], v[112:113]
	v_pk_mul_f32 v[242:243], v[110:111], v[110:111]
	v_pk_mul_f32 v[244:245], v[112:113], v[112:113]
	v_add_f32_e32 v246, v242, v243
	v_add_f32_e32 v246, v244, v246
	v_add_f32_e32 v246, v245, v246
	global_store_dwordx4 v247, v[110:113], s[38:39] sc1
	v_cvt_pk_bf16_f32 v242, v110, v111
	v_cvt_pk_bf16_f32 v243, v112, v113
	v_add_f32_dpp v246, v246, v246 quad_perm:[1,0,3,2] row_mask:0xf bank_mask:0xf
	global_store_dwordx2 v248, v[242:243], s[50:51] sc1
	s_add_u32 s38, s38, 0x4000
	s_addc_u32 s39, s39, 0
	v_add_f32_dpp v246, v246, v246 quad_perm:[2,3,0,1] row_mask:0xf bank_mask:0xf
	s_add_u32 s50, s50, 0x2000
	s_addc_u32 s51, s51, 0
	v_add_f32_dpp v246, v246, v246 row_half_mirror row_mask:0xf bank_mask:0xf
	s_nop 1
	v_add_f32_dpp v246, v246, v246 row_mirror row_mask:0xf bank_mask:0xf
	s_mov_b64 exec, s[48:49]
	global_store_dword v249, v246, s[34:35] offset:3840
	s_mov_b64 exec, -1
	s_waitcnt lgkmcnt(0)
	s_branch .LBB0_1122

.LBB0_1526:
	v_readfirstlane_b32 s40, v204
	s_lshr_b32 s40, s40, 6
	s_and_b32 s41, s40, 1
	s_bfe_u32 s42, s40, 0x10001
	s_lshr_b32 s43, s40, 2
	s_lshl_b32 s44, s4, 1
	s_add_i32 s44, s44, s42
	s_lshl_b32 s45, s44, 7
	s_lshl_b32 s46, s41, 6
	s_add_i32 s45, s45, s46
	s_lshl_b32 s46, s43, 7
	s_add_i32 s46, s46, s2
	s_lshl_b32 s47, s44, 1
	s_add_i32 s47, s47, s41
	v_readlane_b32 s36, v251, 50
	v_readlane_b32 s37, v251, 51
	v_readlane_b32 s38, v250, 9
	v_readlane_b32 s39, v250, 10
	v_readlane_b32 s50, v250, 11
	v_readlane_b32 s51, v250, 12
	s_add_u32 s34, s50, 0xf900000
	s_addc_u32 s35, s51, 0
	s_add_u32 s50, s50, 0x5800000
	s_addc_u32 s51, s51, 0
	s_lshl_b32 s48, s46, 12
	s_lshl_b32 s49, s45, 2
	s_add_u32 s48, s48, s49
	s_add_u32 s36, s36, s48
	s_addc_u32 s37, s37, 0
	s_add_u32 s38, s38, s48
	s_addc_u32 s39, s39, 0
	s_lshr_b32 s48, s48, 1
	s_add_u32 s50, s50, s48
	s_addc_u32 s51, s51, 0
	s_lshl_b32 s48, s46, 6
	s_lshl_b32 s49, s47, 2
	s_add_u32 s48, s48, s49
	s_add_u32 s34, s34, s48
	s_addc_u32 s35, s35, 0
	v_and_b32_e32 v249, 63, v204
	v_and_b32_e32 v198, 31, v249
	v_lshrrev_b32_e32 v199, 5, v249
	v_and_b32_e32 v208, 15, v249
	v_lshrrev_b32_e32 v209, 4, v249
	s_lshl_b32 s40, s40, 14
	v_and_b32_e32 v238, 15, v198
	v_xor_b32_e32 v238, v238, v199
	v_lshl_add_u32 v239, v198, 8, s40
	v_xor_b32_e32 v228, 0, v238
	v_lshl_add_u32 v228, v228, 4, v239
	v_xor_b32_e32 v229, 2, v238
	v_lshl_add_u32 v229, v229, 4, v239
	v_xor_b32_e32 v230, 4, v238
	v_lshl_add_u32 v230, v230, 4, v239
	v_xor_b32_e32 v231, 6, v238
	v_lshl_add_u32 v231, v231, 4, v239
	v_xor_b32_e32 v232, 8, v238
	v_lshl_add_u32 v232, v232, 4, v239
	v_xor_b32_e32 v233, 10, v238
	v_lshl_add_u32 v233, v233, 4, v239
	v_xor_b32_e32 v234, 12, v238
	v_lshl_add_u32 v234, v234, 4, v239
	v_xor_b32_e32 v235, 14, v238
	v_lshl_add_u32 v235, v235, 4, v239
	v_lshl_add_u32 v239, v209, 8, s40
	v_add_u32_e32 v210, 0, v209
	v_xor_b32_e32 v210, v210, v208
	v_lshl_add_u32 v210, v210, 4, v239
	v_add_u32_e32 v211, 4, v209
	v_xor_b32_e32 v211, v211, v208
	v_lshl_add_u32 v211, v211, 4, v239
	v_add_u32_e32 v215, 8, v209
	v_xor_b32_e32 v215, v215, v208
	v_lshl_add_u32 v215, v215, 4, v239
	v_add_u32_e32 v237, 12, v209
	v_xor_b32_e32 v237, v237, v208
	v_lshl_add_u32 v237, v237, 4, v239
	v_lshlrev_b32_e32 v247, 12, v209
	v_lshl_add_u32 v247, v208, 4, v247
	v_lshrrev_b32_e32 v248, 1, v247
	v_lshlrev_b32_e32 v249, 6, v209
	s_mov_b32 s48, 0x00010001
	s_mov_b32 s49, 0x00010001
	global_load_dwordx4 v[130:133], v247, s[36:37]
	s_add_u32 s36, s36, 0x4000
	s_addc_u32 s37, s37, 0
	global_load_dwordx4 v[134:137], v247, s[36:37]
	s_add_u32 s36, s36, 0x4000
	s_addc_u32 s37, s37, 0
	global_load_dwordx4 v[138:141], v247, s[36:37]
	s_add_u32 s36, s36, 0x4000
	s_addc_u32 s37, s37, 0
	global_load_dwordx4 v[142:145], v247, s[36:37]
	s_add_u32 s36, s36, 0x4000
	s_addc_u32 s37, s37, 0
	global_load_dwordx4 v[146:149], v247, s[36:37]
	s_add_u32 s36, s36, 0x4000
	s_addc_u32 s37, s37, 0
	global_load_dwordx4 v[150:153], v247, s[36:37]
	s_add_u32 s36, s36, 0x4000
	s_addc_u32 s37, s37, 0
	global_load_dwordx4 v[154:157], v247, s[36:37]
	s_add_u32 s36, s36, 0x4000
	s_addc_u32 s37, s37, 0
	global_load_dwordx4 v[158:161], v247, s[36:37]
	s_add_u32 s36, s36, 0x4000
	s_addc_u32 s37, s37, 0
	global_load_dwordx4 v[162:165], v247, s[36:37]
	s_add_u32 s36, s36, 0x4000
	s_addc_u32 s37, s37, 0
	global_load_dwordx4 v[166:169], v247, s[36:37]
	s_add_u32 s36, s36, 0x4000
	s_addc_u32 s37, s37, 0
	global_load_dwordx4 v[170:173], v247, s[36:37]
	s_add_u32 s36, s36, 0x4000
	s_addc_u32 s37, s37, 0
	global_load_dwordx4 v[188:191], v247, s[36:37]
	s_add_u32 s36, s36, 0x4000
	s_addc_u32 s37, s37, 0
	global_load_dwordx4 v[200:203], v247, s[36:37]
	s_add_u32 s36, s36, 0x4000
	s_addc_u32 s37, s37, 0
	global_load_dwordx4 v[216:219], v247, s[36:37]
	s_add_u32 s36, s36, 0x4000
	s_addc_u32 s37, s37, 0
	global_load_dwordx4 v[220:223], v247, s[36:37]
	s_add_u32 s36, s36, 0x4000
	s_addc_u32 s37, s37, 0
	global_load_dwordx4 v[224:227], v247, s[36:37]
	s_add_u32 s36, s36, 0x4000
	s_addc_u32 s37, s37, 0
	ds_write_b128 v228, v[82:85]
	ds_write_b128 v229, v[86:89]
	ds_write_b128 v230, v[90:93]
	ds_write_b128 v231, v[94:97]
	ds_write_b128 v232, v[114:117]
	ds_write_b128 v233, v[118:121]
	ds_write_b128 v234, v[122:125]
	ds_write_b128 v235, v[126:129]
	ds_write_b128 v228, v[66:69] offset:8192
	ds_write_b128 v229, v[70:73] offset:8192
	ds_write_b128 v230, v[74:77] offset:8192
	ds_write_b128 v231, v[78:81] offset:8192
	ds_write_b128 v232, v[98:101] offset:8192
	ds_write_b128 v233, v[102:105] offset:8192
	ds_write_b128 v234, v[106:109] offset:8192
	ds_write_b128 v235, v[110:113] offset:8192
	global_load_dwordx4 v[82:85], v247, s[36:37]
	s_add_u32 s36, s36, 0x4000
	s_addc_u32 s37, s37, 0
	global_load_dwordx4 v[86:89], v247, s[36:37]
	s_add_u32 s36, s36, 0x4000
	s_addc_u32 s37, s37, 0
	global_load_dwordx4 v[90:93], v247, s[36:37]
	s_add_u32 s36, s36, 0x4000
	s_addc_u32 s37, s37, 0
	global_load_dwordx4 v[94:97], v247, s[36:37]
	s_add_u32 s36, s36, 0x4000
	s_addc_u32 s37, s37, 0
	global_load_dwordx4 v[114:117], v247, s[36:37]
	s_add_u32 s36, s36, 0x4000
	s_addc_u32 s37, s37, 0
	global_load_dwordx4 v[118:121], v247, s[36:37]
	s_add_u32 s36, s36, 0x4000
	s_addc_u32 s37, s37, 0
	global_load_dwordx4 v[122:125], v247, s[36:37]
	s_add_u32 s36, s36, 0x4000
	s_addc_u32 s37, s37, 0
	global_load_dwordx4 v[126:129], v247, s[36:37]
	s_add_u32 s36, s36, 0x4000
	s_addc_u32 s37, s37, 0
	global_load_dwordx4 v[66:69], v247, s[36:37]
	s_add_u32 s36, s36, 0x4000
	s_addc_u32 s37, s37, 0
	global_load_dwordx4 v[70:73], v247, s[36:37]
	s_add_u32 s36, s36, 0x4000
	s_addc_u32 s37, s37, 0
	global_load_dwordx4 v[74:77], v247, s[36:37]
	s_add_u32 s36, s36, 0x4000
	s_addc_u32 s37, s37, 0
	global_load_dwordx4 v[78:81], v247, s[36:37]
	s_add_u32 s36, s36, 0x4000
	s_addc_u32 s37, s37, 0
	global_load_dwordx4 v[98:101], v247, s[36:37]
	s_add_u32 s36, s36, 0x4000
	s_addc_u32 s37, s37, 0
	global_load_dwordx4 v[102:105], v247, s[36:37]
	s_add_u32 s36, s36, 0x4000
	s_addc_u32 s37, s37, 0
	global_load_dwordx4 v[106:109], v247, s[36:37]
	s_add_u32 s36, s36, 0x4000
	s_addc_u32 s37, s37, 0
	global_load_dwordx4 v[110:113], v247, s[36:37]
	s_add_u32 s36, s36, 0x4000
	s_addc_u32 s37, s37, 0
	s_waitcnt lgkmcnt(0)
	ds_read_b128 v[228:231], v210 offset:0
	ds_read_b128 v[238:241], v211 offset:1024
	s_waitcnt vmcnt(31) lgkmcnt(1)
	v_pk_add_f32 v[130:131], v[228:229], v[130:131]
	v_pk_add_f32 v[132:133], v[230:231], v[132:133]
	v_pk_mul_f32 v[232:233], v[130:131], v[130:131]
	v_pk_mul_f32 v[234:235], v[132:133], v[132:133]
	ds_read_b128 v[228:231], v215 offset:2048
	v_add_f32_e32 v236, v232, v233
	v_add_f32_e32 v236, v234, v236
	v_add_f32_e32 v236, v235, v236
	global_store_dwordx4 v247, v[130:133], s[38:39] sc1
	v_cvt_pk_bf16_f32 v232, v130, v131
	v_cvt_pk_bf16_f32 v233, v132, v133
	v_add_f32_dpp v236, v236, v236 quad_perm:[1,0,3,2] row_mask:0xf bank_mask:0xf
	global_store_dwordx2 v248, v[232:233], s[50:51] sc1
	s_add_u32 s38, s38, 0x4000
	s_addc_u32 s39, s39, 0
	v_add_f32_dpp v236, v236, v236 quad_perm:[2,3,0,1] row_mask:0xf bank_mask:0xf
	s_add_u32 s50, s50, 0x2000
	s_addc_u32 s51, s51, 0
	v_add_f32_dpp v236, v236, v236 row_half_mirror row_mask:0xf bank_mask:0xf
	s_nop 1
	v_add_f32_dpp v236, v236, v236 row_mirror row_mask:0xf bank_mask:0xf
	s_mov_b64 exec, s[48:49]
	global_store_dword v249, v236, s[34:35] offset:0
	s_mov_b64 exec, -1
	s_waitcnt vmcnt(33) lgkmcnt(1)
	v_pk_add_f32 v[134:135], v[238:239], v[134:135]
	v_pk_add_f32 v[136:137], v[240:241], v[136:137]
	v_pk_mul_f32 v[242:243], v[134:135], v[134:135]
	v_pk_mul_f32 v[244:245], v[136:137], v[136:137]
	ds_read_b128 v[238:241], v237 offset:3072
	v_add_f32_e32 v246, v242, v243
	v_add_f32_e32 v246, v244, v246
	v_add_f32_e32 v246, v245, v246
	global_store_dwordx4 v247, v[134:137], s[38:39] sc1
	v_cvt_pk_bf16_f32 v242, v134, v135
	v_cvt_pk_bf16_f32 v243, v136, v137
	v_add_f32_dpp v246, v246, v246 quad_perm:[1,0,3,2] row_mask:0xf bank_mask:0xf
	global_store_dwordx2 v248, v[242:243], s[50:51] sc1
	s_add_u32 s38, s38, 0x4000
	s_addc_u32 s39, s39, 0
	v_add_f32_dpp v246, v246, v246 quad_perm:[2,3,0,1] row_mask:0xf bank_mask:0xf
	s_add_u32 s50, s50, 0x2000
	s_addc_u32 s51, s51, 0
	v_add_f32_dpp v246, v246, v246 row_half_mirror row_mask:0xf bank_mask:0xf
	s_nop 1
	v_add_f32_dpp v246, v246, v246 row_mirror row_mask:0xf bank_mask:0xf
	s_mov_b64 exec, s[48:49]
	global_store_dword v249, v246, s[34:35] offset:256
	s_mov_b64 exec, -1
	s_waitcnt vmcnt(35) lgkmcnt(1)
	v_pk_add_f32 v[138:139], v[228:229], v[138:139]
	v_pk_add_f32 v[140:141], v[230:231], v[140:141]
	v_pk_mul_f32 v[232:233], v[138:139], v[138:139]
	v_pk_mul_f32 v[234:235], v[140:141], v[140:141]
	ds_read_b128 v[228:231], v210 offset:4096
	v_add_f32_e32 v236, v232, v233
	v_add_f32_e32 v236, v234, v236
	v_add_f32_e32 v236, v235, v236
	global_store_dwordx4 v247, v[138:141], s[38:39] sc1
	v_cvt_pk_bf16_f32 v232, v138, v139
	v_cvt_pk_bf16_f32 v233, v140, v141
	v_add_f32_dpp v236, v236, v236 quad_perm:[1,0,3,2] row_mask:0xf bank_mask:0xf
	global_store_dwordx2 v248, v[232:233], s[50:51] sc1
	s_add_u32 s38, s38, 0x4000
	s_addc_u32 s39, s39, 0
	v_add_f32_dpp v236, v236, v236 quad_perm:[2,3,0,1] row_mask:0xf bank_mask:0xf
	s_add_u32 s50, s50, 0x2000
	s_addc_u32 s51, s51, 0
	v_add_f32_dpp v236, v236, v236 row_half_mirror row_mask:0xf bank_mask:0xf
	s_nop 1
	v_add_f32_dpp v236, v236, v236 row_mirror row_mask:0xf bank_mask:0xf
	s_mov_b64 exec, s[48:49]
	global_store_dword v249, v236, s[34:35] offset:512
	s_mov_b64 exec, -1
	s_waitcnt vmcnt(37) lgkmcnt(1)
	v_pk_add_f32 v[142:143], v[238:239], v[142:143]
	v_pk_add_f32 v[144:145], v[240:241], v[144:145]
	v_pk_mul_f32 v[242:243], v[142:143], v[142:143]
	v_pk_mul_f32 v[244:245], v[144:145], v[144:145]
	ds_read_b128 v[238:241], v211 offset:5120
	v_add_f32_e32 v246, v242, v243
	v_add_f32_e32 v246, v244, v246
	v_add_f32_e32 v246, v245, v246
	global_store_dwordx4 v247, v[142:145], s[38:39] sc1
	v_cvt_pk_bf16_f32 v242, v142, v143
	v_cvt_pk_bf16_f32 v243, v144, v145
	v_add_f32_dpp v246, v246, v246 quad_perm:[1,0,3,2] row_mask:0xf bank_mask:0xf
	global_store_dwordx2 v248, v[242:243], s[50:51] sc1
	s_add_u32 s38, s38, 0x4000
	s_addc_u32 s39, s39, 0
	v_add_f32_dpp v246, v246, v246 quad_perm:[2,3,0,1] row_mask:0xf bank_mask:0xf
	s_add_u32 s50, s50, 0x2000
	s_addc_u32 s51, s51, 0
	v_add_f32_dpp v246, v246, v246 row_half_mirror row_mask:0xf bank_mask:0xf
	s_nop 1
	v_add_f32_dpp v246, v246, v246 row_mirror row_mask:0xf bank_mask:0xf
	s_mov_b64 exec, s[48:49]
	global_store_dword v249, v246, s[34:35] offset:768
	s_mov_b64 exec, -1
	s_waitcnt vmcnt(39) lgkmcnt(1)
	v_pk_add_f32 v[146:147], v[228:229], v[146:147]
	v_pk_add_f32 v[148:149], v[230:231], v[148:149]
	v_pk_mul_f32 v[232:233], v[146:147], v[146:147]
	v_pk_mul_f32 v[234:235], v[148:149], v[148:149]
	ds_read_b128 v[228:231], v215 offset:6144
	v_add_f32_e32 v236, v232, v233
	v_add_f32_e32 v236, v234, v236
	v_add_f32_e32 v236, v235, v236
	global_store_dwordx4 v247, v[146:149], s[38:39] sc1
	v_cvt_pk_bf16_f32 v232, v146, v147
	v_cvt_pk_bf16_f32 v233, v148, v149
	v_add_f32_dpp v236, v236, v236 quad_perm:[1,0,3,2] row_mask:0xf bank_mask:0xf
	global_store_dwordx2 v248, v[232:233], s[50:51] sc1
	s_add_u32 s38, s38, 0x4000
	s_addc_u32 s39, s39, 0
	v_add_f32_dpp v236, v236, v236 quad_perm:[2,3,0,1] row_mask:0xf bank_mask:0xf
	s_add_u32 s50, s50, 0x2000
	s_addc_u32 s51, s51, 0
	v_add_f32_dpp v236, v236, v236 row_half_mirror row_mask:0xf bank_mask:0xf
	s_nop 1
	v_add_f32_dpp v236, v236, v236 row_mirror row_mask:0xf bank_mask:0xf
	s_mov_b64 exec, s[48:49]
	global_store_dword v249, v236, s[34:35] offset:1024
	s_mov_b64 exec, -1
	s_waitcnt vmcnt(41) lgkmcnt(1)
	v_pk_add_f32 v[150:151], v[238:239], v[150:151]
	v_pk_add_f32 v[152:153], v[240:241], v[152:153]
	v_pk_mul_f32 v[242:243], v[150:151], v[150:151]
	v_pk_mul_f32 v[244:245], v[152:153], v[152:153]
	ds_read_b128 v[238:241], v237 offset:7168
	v_add_f32_e32 v246, v242, v243
	v_add_f32_e32 v246, v244, v246
	v_add_f32_e32 v246, v245, v246
	global_store_dwordx4 v247, v[150:153], s[38:39] sc1
	v_cvt_pk_bf16_f32 v242, v150, v151
	v_cvt_pk_bf16_f32 v243, v152, v153
	v_add_f32_dpp v246, v246, v246 quad_perm:[1,0,3,2] row_mask:0xf bank_mask:0xf
	global_store_dwordx2 v248, v[242:243], s[50:51] sc1
	s_add_u32 s38, s38, 0x4000
	s_addc_u32 s39, s39, 0
	v_add_f32_dpp v246, v246, v246 quad_perm:[2,3,0,1] row_mask:0xf bank_mask:0xf
	s_add_u32 s50, s50, 0x2000
	s_addc_u32 s51, s51, 0
	v_add_f32_dpp v246, v246, v246 row_half_mirror row_mask:0xf bank_mask:0xf
	s_nop 1
	v_add_f32_dpp v246, v246, v246 row_mirror row_mask:0xf bank_mask:0xf
	s_mov_b64 exec, s[48:49]
	global_store_dword v249, v246, s[34:35] offset:1280
	s_mov_b64 exec, -1
	s_waitcnt vmcnt(43) lgkmcnt(1)
	v_pk_add_f32 v[154:155], v[228:229], v[154:155]
	v_pk_add_f32 v[156:157], v[230:231], v[156:157]
	v_pk_mul_f32 v[232:233], v[154:155], v[154:155]
	v_pk_mul_f32 v[234:235], v[156:157], v[156:157]
	ds_read_b128 v[228:231], v210 offset:8192
	v_add_f32_e32 v236, v232, v233
	v_add_f32_e32 v236, v234, v236
	v_add_f32_e32 v236, v235, v236
	global_store_dwordx4 v247, v[154:157], s[38:39] sc1
	v_cvt_pk_bf16_f32 v232, v154, v155
	v_cvt_pk_bf16_f32 v233, v156, v157
	v_add_f32_dpp v236, v236, v236 quad_perm:[1,0,3,2] row_mask:0xf bank_mask:0xf
	global_store_dwordx2 v248, v[232:233], s[50:51] sc1
	s_add_u32 s38, s38, 0x4000
	s_addc_u32 s39, s39, 0
	v_add_f32_dpp v236, v236, v236 quad_perm:[2,3,0,1] row_mask:0xf bank_mask:0xf
	s_add_u32 s50, s50, 0x2000
	s_addc_u32 s51, s51, 0
	v_add_f32_dpp v236, v236, v236 row_half_mirror row_mask:0xf bank_mask:0xf
	s_nop 1
	v_add_f32_dpp v236, v236, v236 row_mirror row_mask:0xf bank_mask:0xf
	s_mov_b64 exec, s[48:49]
	global_store_dword v249, v236, s[34:35] offset:1536
	s_mov_b64 exec, -1
	s_waitcnt vmcnt(45) lgkmcnt(1)
	v_pk_add_f32 v[158:159], v[238:239], v[158:159]
	v_pk_add_f32 v[160:161], v[240:241], v[160:161]
	v_pk_mul_f32 v[242:243], v[158:159], v[158:159]
	v_pk_mul_f32 v[244:245], v[160:161], v[160:161]
	ds_read_b128 v[238:241], v211 offset:9216
	v_add_f32_e32 v246, v242, v243
	v_add_f32_e32 v246, v244, v246
	v_add_f32_e32 v246, v245, v246
	global_store_dwordx4 v247, v[158:161], s[38:39] sc1
	v_cvt_pk_bf16_f32 v242, v158, v159
	v_cvt_pk_bf16_f32 v243, v160, v161
	v_add_f32_dpp v246, v246, v246 quad_perm:[1,0,3,2] row_mask:0xf bank_mask:0xf
	global_store_dwordx2 v248, v[242:243], s[50:51] sc1
	s_add_u32 s38, s38, 0x4000
	s_addc_u32 s39, s39, 0
	v_add_f32_dpp v246, v246, v246 quad_perm:[2,3,0,1] row_mask:0xf bank_mask:0xf
	s_add_u32 s50, s50, 0x2000
	s_addc_u32 s51, s51, 0
	v_add_f32_dpp v246, v246, v246 row_half_mirror row_mask:0xf bank_mask:0xf
	s_nop 1
	v_add_f32_dpp v246, v246, v246 row_mirror row_mask:0xf bank_mask:0xf
	s_mov_b64 exec, s[48:49]
	global_store_dword v249, v246, s[34:35] offset:1792
	s_mov_b64 exec, -1
	s_waitcnt vmcnt(47) lgkmcnt(1)
	v_pk_add_f32 v[162:163], v[228:229], v[162:163]
	v_pk_add_f32 v[164:165], v[230:231], v[164:165]
	v_pk_mul_f32 v[232:233], v[162:163], v[162:163]
	v_pk_mul_f32 v[234:235], v[164:165], v[164:165]
	ds_read_b128 v[228:231], v215 offset:10240
	v_add_f32_e32 v236, v232, v233
	v_add_f32_e32 v236, v234, v236
	v_add_f32_e32 v236, v235, v236
	global_store_dwordx4 v247, v[162:165], s[38:39] sc1
	v_cvt_pk_bf16_f32 v232, v162, v163
	v_cvt_pk_bf16_f32 v233, v164, v165
	v_add_f32_dpp v236, v236, v236 quad_perm:[1,0,3,2] row_mask:0xf bank_mask:0xf
	global_store_dwordx2 v248, v[232:233], s[50:51] sc1
	s_add_u32 s38, s38, 0x4000
	s_addc_u32 s39, s39, 0
	v_add_f32_dpp v236, v236, v236 quad_perm:[2,3,0,1] row_mask:0xf bank_mask:0xf
	s_add_u32 s50, s50, 0x2000
	s_addc_u32 s51, s51, 0
	v_add_f32_dpp v236, v236, v236 row_half_mirror row_mask:0xf bank_mask:0xf
	s_nop 1
	v_add_f32_dpp v236, v236, v236 row_mirror row_mask:0xf bank_mask:0xf
	s_mov_b64 exec, s[48:49]
	global_store_dword v249, v236, s[34:35] offset:2048
	s_mov_b64 exec, -1
	s_waitcnt vmcnt(49) lgkmcnt(1)
	v_pk_add_f32 v[166:167], v[238:239], v[166:167]
	v_pk_add_f32 v[168:169], v[240:241], v[168:169]
	v_pk_mul_f32 v[242:243], v[166:167], v[166:167]
	v_pk_mul_f32 v[244:245], v[168:169], v[168:169]
	ds_read_b128 v[238:241], v237 offset:11264
	v_add_f32_e32 v246, v242, v243
	v_add_f32_e32 v246, v244, v246
	v_add_f32_e32 v246, v245, v246
	global_store_dwordx4 v247, v[166:169], s[38:39] sc1
	v_cvt_pk_bf16_f32 v242, v166, v167
	v_cvt_pk_bf16_f32 v243, v168, v169
	v_add_f32_dpp v246, v246, v246 quad_perm:[1,0,3,2] row_mask:0xf bank_mask:0xf
	global_store_dwordx2 v248, v[242:243], s[50:51] sc1
	s_add_u32 s38, s38, 0x4000
	s_addc_u32 s39, s39, 0
	v_add_f32_dpp v246, v246, v246 quad_perm:[2,3,0,1] row_mask:0xf bank_mask:0xf
	s_add_u32 s50, s50, 0x2000
	s_addc_u32 s51, s51, 0
	v_add_f32_dpp v246, v246, v246 row_half_mirror row_mask:0xf bank_mask:0xf
	s_nop 1
	v_add_f32_dpp v246, v246, v246 row_mirror row_mask:0xf bank_mask:0xf
	s_mov_b64 exec, s[48:49]
	global_store_dword v249, v246, s[34:35] offset:2304
	s_mov_b64 exec, -1
	s_waitcnt vmcnt(51) lgkmcnt(1)
	v_pk_add_f32 v[170:171], v[228:229], v[170:171]
	v_pk_add_f32 v[172:173], v[230:231], v[172:173]
	v_pk_mul_f32 v[232:233], v[170:171], v[170:171]
	v_pk_mul_f32 v[234:235], v[172:173], v[172:173]
	ds_read_b128 v[228:231], v210 offset:12288
	v_add_f32_e32 v236, v232, v233
	v_add_f32_e32 v236, v234, v236
	v_add_f32_e32 v236, v235, v236
	global_store_dwordx4 v247, v[170:173], s[38:39] sc1
	v_cvt_pk_bf16_f32 v232, v170, v171
	v_cvt_pk_bf16_f32 v233, v172, v173
	v_add_f32_dpp v236, v236, v236 quad_perm:[1,0,3,2] row_mask:0xf bank_mask:0xf
	global_store_dwordx2 v248, v[232:233], s[50:51] sc1
	s_add_u32 s38, s38, 0x4000
	s_addc_u32 s39, s39, 0
	v_add_f32_dpp v236, v236, v236 quad_perm:[2,3,0,1] row_mask:0xf bank_mask:0xf
	s_add_u32 s50, s50, 0x2000
	s_addc_u32 s51, s51, 0
	v_add_f32_dpp v236, v236, v236 row_half_mirror row_mask:0xf bank_mask:0xf
	s_nop 1
	v_add_f32_dpp v236, v236, v236 row_mirror row_mask:0xf bank_mask:0xf
	s_mov_b64 exec, s[48:49]
	global_store_dword v249, v236, s[34:35] offset:2560
	s_mov_b64 exec, -1
	s_waitcnt vmcnt(53) lgkmcnt(1)
	v_pk_add_f32 v[188:189], v[238:239], v[188:189]
	v_pk_add_f32 v[190:191], v[240:241], v[190:191]
	v_pk_mul_f32 v[242:243], v[188:189], v[188:189]
	v_pk_mul_f32 v[244:245], v[190:191], v[190:191]
	ds_read_b128 v[238:241], v211 offset:13312
	v_add_f32_e32 v246, v242, v243
	v_add_f32_e32 v246, v244, v246
	v_add_f32_e32 v246, v245, v246
	global_store_dwordx4 v247, v[188:191], s[38:39] sc1
	v_cvt_pk_bf16_f32 v242, v188, v189
	v_cvt_pk_bf16_f32 v243, v190, v191
	v_add_f32_dpp v246, v246, v246 quad_perm:[1,0,3,2] row_mask:0xf bank_mask:0xf
	global_store_dwordx2 v248, v[242:243], s[50:51] sc1
	s_add_u32 s38, s38, 0x4000
	s_addc_u32 s39, s39, 0
	v_add_f32_dpp v246, v246, v246 quad_perm:[2,3,0,1] row_mask:0xf bank_mask:0xf
	s_add_u32 s50, s50, 0x2000
	s_addc_u32 s51, s51, 0
	v_add_f32_dpp v246, v246, v246 row_half_mirror row_mask:0xf bank_mask:0xf
	s_nop 1
	v_add_f32_dpp v246, v246, v246 row_mirror row_mask:0xf bank_mask:0xf
	s_mov_b64 exec, s[48:49]
	global_store_dword v249, v246, s[34:35] offset:2816
	s_mov_b64 exec, -1
	s_waitcnt vmcnt(55) lgkmcnt(1)
	v_pk_add_f32 v[200:201], v[228:229], v[200:201]
	v_pk_add_f32 v[202:203], v[230:231], v[202:203]
	v_pk_mul_f32 v[232:233], v[200:201], v[200:201]
	v_pk_mul_f32 v[234:235], v[202:203], v[202:203]
	ds_read_b128 v[228:231], v215 offset:14336
	v_add_f32_e32 v236, v232, v233
	v_add_f32_e32 v236, v234, v236
	v_add_f32_e32 v236, v235, v236
	global_store_dwordx4 v247, v[200:203], s[38:39] sc1
	v_cvt_pk_bf16_f32 v232, v200, v201
	v_cvt_pk_bf16_f32 v233, v202, v203
	v_add_f32_dpp v236, v236, v236 quad_perm:[1,0,3,2] row_mask:0xf bank_mask:0xf
	global_store_dwordx2 v248, v[232:233], s[50:51] sc1
	s_add_u32 s38, s38, 0x4000
	s_addc_u32 s39, s39, 0
	v_add_f32_dpp v236, v236, v236 quad_perm:[2,3,0,1] row_mask:0xf bank_mask:0xf
	s_add_u32 s50, s50, 0x2000
	s_addc_u32 s51, s51, 0
	v_add_f32_dpp v236, v236, v236 row_half_mirror row_mask:0xf bank_mask:0xf
	s_nop 1
	v_add_f32_dpp v236, v236, v236 row_mirror row_mask:0xf bank_mask:0xf
	s_mov_b64 exec, s[48:49]
	global_store_dword v249, v236, s[34:35] offset:3072
	s_mov_b64 exec, -1
	s_waitcnt vmcnt(57) lgkmcnt(1)
	v_pk_add_f32 v[216:217], v[238:239], v[216:217]
	v_pk_add_f32 v[218:219], v[240:241], v[218:219]
	v_pk_mul_f32 v[242:243], v[216:217], v[216:217]
	v_pk_mul_f32 v[244:245], v[218:219], v[218:219]
	ds_read_b128 v[238:241], v237 offset:15360
	v_add_f32_e32 v246, v242, v243
	v_add_f32_e32 v246, v244, v246
	v_add_f32_e32 v246, v245, v246
	global_store_dwordx4 v247, v[216:219], s[38:39] sc1
	v_cvt_pk_bf16_f32 v242, v216, v217
	v_cvt_pk_bf16_f32 v243, v218, v219
	v_add_f32_dpp v246, v246, v246 quad_perm:[1,0,3,2] row_mask:0xf bank_mask:0xf
	global_store_dwordx2 v248, v[242:243], s[50:51] sc1
	s_add_u32 s38, s38, 0x4000
	s_addc_u32 s39, s39, 0
	v_add_f32_dpp v246, v246, v246 quad_perm:[2,3,0,1] row_mask:0xf bank_mask:0xf
	s_add_u32 s50, s50, 0x2000
	s_addc_u32 s51, s51, 0
	v_add_f32_dpp v246, v246, v246 row_half_mirror row_mask:0xf bank_mask:0xf
	s_nop 1
	v_add_f32_dpp v246, v246, v246 row_mirror row_mask:0xf bank_mask:0xf
	s_mov_b64 exec, s[48:49]
	global_store_dword v249, v246, s[34:35] offset:3328
	s_mov_b64 exec, -1
	s_waitcnt vmcnt(59) lgkmcnt(1)
	v_pk_add_f32 v[220:221], v[228:229], v[220:221]
	v_pk_add_f32 v[222:223], v[230:231], v[222:223]
	v_pk_mul_f32 v[232:233], v[220:221], v[220:221]
	v_pk_mul_f32 v[234:235], v[222:223], v[222:223]
	v_add_f32_e32 v236, v232, v233
	v_add_f32_e32 v236, v234, v236
	v_add_f32_e32 v236, v235, v236
	global_store_dwordx4 v247, v[220:223], s[38:39] sc1
	v_cvt_pk_bf16_f32 v232, v220, v221
	v_cvt_pk_bf16_f32 v233, v222, v223
	v_add_f32_dpp v236, v236, v236 quad_perm:[1,0,3,2] row_mask:0xf bank_mask:0xf
	global_store_dwordx2 v248, v[232:233], s[50:51] sc1
	s_add_u32 s38, s38, 0x4000
	s_addc_u32 s39, s39, 0
	v_add_f32_dpp v236, v236, v236 quad_perm:[2,3,0,1] row_mask:0xf bank_mask:0xf
	s_add_u32 s50, s50, 0x2000
	s_addc_u32 s51, s51, 0
	v_add_f32_dpp v236, v236, v236 row_half_mirror row_mask:0xf bank_mask:0xf
	s_nop 1
	v_add_f32_dpp v236, v236, v236 row_mirror row_mask:0xf bank_mask:0xf
	s_mov_b64 exec, s[48:49]
	global_store_dword v249, v236, s[34:35] offset:3584
	s_mov_b64 exec, -1
	s_waitcnt vmcnt(61) lgkmcnt(0)
	v_pk_add_f32 v[224:225], v[238:239], v[224:225]
	v_pk_add_f32 v[226:227], v[240:241], v[226:227]
	v_pk_mul_f32 v[242:243], v[224:225], v[224:225]
	v_pk_mul_f32 v[244:245], v[226:227], v[226:227]
	v_add_f32_e32 v246, v242, v243
	v_add_f32_e32 v246, v244, v246
	v_add_f32_e32 v246, v245, v246
	global_store_dwordx4 v247, v[224:227], s[38:39] sc1
	v_cvt_pk_bf16_f32 v242, v224, v225
	v_cvt_pk_bf16_f32 v243, v226, v227
	v_add_f32_dpp v246, v246, v246 quad_perm:[1,0,3,2] row_mask:0xf bank_mask:0xf
	global_store_dwordx2 v248, v[242:243], s[50:51] sc1
	s_add_u32 s38, s38, 0x4000
	s_addc_u32 s39, s39, 0
	v_add_f32_dpp v246, v246, v246 quad_perm:[2,3,0,1] row_mask:0xf bank_mask:0xf
	s_add_u32 s50, s50, 0x2000
	s_addc_u32 s51, s51, 0
	v_add_f32_dpp v246, v246, v246 row_half_mirror row_mask:0xf bank_mask:0xf
	s_nop 1
	v_add_f32_dpp v246, v246, v246 row_mirror row_mask:0xf bank_mask:0xf
	s_mov_b64 exec, s[48:49]
	global_store_dword v249, v246, s[34:35] offset:3840
	s_mov_b64 exec, -1
	s_add_u32 s34, s34, 0x1000
	s_addc_u32 s35, s35, 0
	v_and_b32_e32 v238, 15, v198
	v_xor_b32_e32 v238, v238, v199
	v_lshl_add_u32 v239, v198, 8, s40
	v_xor_b32_e32 v228, 0, v238
	v_lshl_add_u32 v228, v228, 4, v239
	v_xor_b32_e32 v229, 2, v238
	v_lshl_add_u32 v229, v229, 4, v239
	v_xor_b32_e32 v230, 4, v238
	v_lshl_add_u32 v230, v230, 4, v239
	v_xor_b32_e32 v231, 6, v238
	v_lshl_add_u32 v231, v231, 4, v239
	v_xor_b32_e32 v232, 8, v238
	v_lshl_add_u32 v232, v232, 4, v239
	v_xor_b32_e32 v233, 10, v238
	v_lshl_add_u32 v233, v233, 4, v239
	v_xor_b32_e32 v234, 12, v238
	v_lshl_add_u32 v234, v234, 4, v239
	v_xor_b32_e32 v235, 14, v238
	v_lshl_add_u32 v235, v235, 4, v239
	ds_write_b128 v228, v[18:21]
	ds_write_b128 v229, v[22:25]
	ds_write_b128 v230, v[26:29]
	ds_write_b128 v231, v[30:33]
	ds_write_b128 v232, v[50:53]
	ds_write_b128 v233, v[54:57]
	ds_write_b128 v234, v[58:61]
	ds_write_b128 v235, v[62:65]
	ds_write_b128 v228, v[2:5] offset:8192
	ds_write_b128 v229, v[6:9] offset:8192
	ds_write_b128 v230, v[10:13] offset:8192
	ds_write_b128 v231, v[14:17] offset:8192
	ds_write_b128 v232, v[34:37] offset:8192
	ds_write_b128 v233, v[38:41] offset:8192
	ds_write_b128 v234, v[42:45] offset:8192
	ds_write_b128 v235, v[46:49] offset:8192
	s_waitcnt lgkmcnt(0)
	ds_read_b128 v[228:231], v210 offset:0
	ds_read_b128 v[238:241], v211 offset:1024
	s_waitcnt vmcnt(63) lgkmcnt(1)
	v_pk_add_f32 v[82:83], v[228:229], v[82:83]
	v_pk_add_f32 v[84:85], v[230:231], v[84:85]
	v_pk_mul_f32 v[232:233], v[82:83], v[82:83]
	v_pk_mul_f32 v[234:235], v[84:85], v[84:85]
	ds_read_b128 v[228:231], v215 offset:2048
	v_add_f32_e32 v236, v232, v233
	v_add_f32_e32 v236, v234, v236
	v_add_f32_e32 v236, v235, v236
	global_store_dwordx4 v247, v[82:85], s[38:39] sc1
	v_cvt_pk_bf16_f32 v232, v82, v83
	v_cvt_pk_bf16_f32 v233, v84, v85
	v_add_f32_dpp v236, v236, v236 quad_perm:[1,0,3,2] row_mask:0xf bank_mask:0xf
	global_store_dwordx2 v248, v[232:233], s[50:51] sc1
	s_add_u32 s38, s38, 0x4000
	s_addc_u32 s39, s39, 0
	v_add_f32_dpp v236, v236, v236 quad_perm:[2,3,0,1] row_mask:0xf bank_mask:0xf
	s_add_u32 s50, s50, 0x2000
	s_addc_u32 s51, s51, 0
	v_add_f32_dpp v236, v236, v236 row_half_mirror row_mask:0xf bank_mask:0xf
	s_nop 1
	v_add_f32_dpp v236, v236, v236 row_mirror row_mask:0xf bank_mask:0xf
	s_mov_b64 exec, s[48:49]
	global_store_dword v249, v236, s[34:35] offset:0
	s_mov_b64 exec, -1
	s_waitcnt vmcnt(63) lgkmcnt(1)
	v_pk_add_f32 v[86:87], v[238:239], v[86:87]
	v_pk_add_f32 v[88:89], v[240:241], v[88:89]
	v_pk_mul_f32 v[242:243], v[86:87], v[86:87]
	v_pk_mul_f32 v[244:245], v[88:89], v[88:89]
	ds_read_b128 v[238:241], v237 offset:3072
	v_add_f32_e32 v246, v242, v243
	v_add_f32_e32 v246, v244, v246
	v_add_f32_e32 v246, v245, v246
	global_store_dwordx4 v247, v[86:89], s[38:39] sc1
	v_cvt_pk_bf16_f32 v242, v86, v87
	v_cvt_pk_bf16_f32 v243, v88, v89
	v_add_f32_dpp v246, v246, v246 quad_perm:[1,0,3,2] row_mask:0xf bank_mask:0xf
	global_store_dwordx2 v248, v[242:243], s[50:51] sc1
	s_add_u32 s38, s38, 0x4000
	s_addc_u32 s39, s39, 0
	v_add_f32_dpp v246, v246, v246 quad_perm:[2,3,0,1] row_mask:0xf bank_mask:0xf
	s_add_u32 s50, s50, 0x2000
	s_addc_u32 s51, s51, 0
	v_add_f32_dpp v246, v246, v246 row_half_mirror row_mask:0xf bank_mask:0xf
	s_nop 1
	v_add_f32_dpp v246, v246, v246 row_mirror row_mask:0xf bank_mask:0xf
	s_mov_b64 exec, s[48:49]
	global_store_dword v249, v246, s[34:35] offset:256
	s_mov_b64 exec, -1
	s_waitcnt vmcnt(63) lgkmcnt(1)
	v_pk_add_f32 v[90:91], v[228:229], v[90:91]
	v_pk_add_f32 v[92:93], v[230:231], v[92:93]
	v_pk_mul_f32 v[232:233], v[90:91], v[90:91]
	v_pk_mul_f32 v[234:235], v[92:93], v[92:93]
	ds_read_b128 v[228:231], v210 offset:4096
	v_add_f32_e32 v236, v232, v233
	v_add_f32_e32 v236, v234, v236
	v_add_f32_e32 v236, v235, v236
	global_store_dwordx4 v247, v[90:93], s[38:39] sc1
	v_cvt_pk_bf16_f32 v232, v90, v91
	v_cvt_pk_bf16_f32 v233, v92, v93
	v_add_f32_dpp v236, v236, v236 quad_perm:[1,0,3,2] row_mask:0xf bank_mask:0xf
	global_store_dwordx2 v248, v[232:233], s[50:51] sc1
	s_add_u32 s38, s38, 0x4000
	s_addc_u32 s39, s39, 0
	v_add_f32_dpp v236, v236, v236 quad_perm:[2,3,0,1] row_mask:0xf bank_mask:0xf
	s_add_u32 s50, s50, 0x2000
	s_addc_u32 s51, s51, 0
	v_add_f32_dpp v236, v236, v236 row_half_mirror row_mask:0xf bank_mask:0xf
	s_nop 1
	v_add_f32_dpp v236, v236, v236 row_mirror row_mask:0xf bank_mask:0xf
	s_mov_b64 exec, s[48:49]
	global_store_dword v249, v236, s[34:35] offset:512
	s_mov_b64 exec, -1
	s_waitcnt vmcnt(63) lgkmcnt(1)
	v_pk_add_f32 v[94:95], v[238:239], v[94:95]
	v_pk_add_f32 v[96:97], v[240:241], v[96:97]
	v_pk_mul_f32 v[242:243], v[94:95], v[94:95]
	v_pk_mul_f32 v[244:245], v[96:97], v[96:97]
	ds_read_b128 v[238:241], v211 offset:5120
	v_add_f32_e32 v246, v242, v243
	v_add_f32_e32 v246, v244, v246
	v_add_f32_e32 v246, v245, v246
	global_store_dwordx4 v247, v[94:97], s[38:39] sc1
	v_cvt_pk_bf16_f32 v242, v94, v95
	v_cvt_pk_bf16_f32 v243, v96, v97
	v_add_f32_dpp v246, v246, v246 quad_perm:[1,0,3,2] row_mask:0xf bank_mask:0xf
	global_store_dwordx2 v248, v[242:243], s[50:51] sc1
	s_add_u32 s38, s38, 0x4000
	s_addc_u32 s39, s39, 0
	v_add_f32_dpp v246, v246, v246 quad_perm:[2,3,0,1] row_mask:0xf bank_mask:0xf
	s_add_u32 s50, s50, 0x2000
	s_addc_u32 s51, s51, 0
	v_add_f32_dpp v246, v246, v246 row_half_mirror row_mask:0xf bank_mask:0xf
	s_nop 1
	v_add_f32_dpp v246, v246, v246 row_mirror row_mask:0xf bank_mask:0xf
	s_mov_b64 exec, s[48:49]
	global_store_dword v249, v246, s[34:35] offset:768
	s_mov_b64 exec, -1
	s_waitcnt vmcnt(63) lgkmcnt(1)
	v_pk_add_f32 v[114:115], v[228:229], v[114:115]
	v_pk_add_f32 v[116:117], v[230:231], v[116:117]
	v_pk_mul_f32 v[232:233], v[114:115], v[114:115]
	v_pk_mul_f32 v[234:235], v[116:117], v[116:117]
	ds_read_b128 v[228:231], v215 offset:6144
	v_add_f32_e32 v236, v232, v233
	v_add_f32_e32 v236, v234, v236
	v_add_f32_e32 v236, v235, v236
	global_store_dwordx4 v247, v[114:117], s[38:39] sc1
	v_cvt_pk_bf16_f32 v232, v114, v115
	v_cvt_pk_bf16_f32 v233, v116, v117
	v_add_f32_dpp v236, v236, v236 quad_perm:[1,0,3,2] row_mask:0xf bank_mask:0xf
	global_store_dwordx2 v248, v[232:233], s[50:51] sc1
	s_add_u32 s38, s38, 0x4000
	s_addc_u32 s39, s39, 0
	v_add_f32_dpp v236, v236, v236 quad_perm:[2,3,0,1] row_mask:0xf bank_mask:0xf
	s_add_u32 s50, s50, 0x2000
	s_addc_u32 s51, s51, 0
	v_add_f32_dpp v236, v236, v236 row_half_mirror row_mask:0xf bank_mask:0xf
	s_nop 1
	v_add_f32_dpp v236, v236, v236 row_mirror row_mask:0xf bank_mask:0xf
	s_mov_b64 exec, s[48:49]
	global_store_dword v249, v236, s[34:35] offset:1024
	s_mov_b64 exec, -1
	s_waitcnt vmcnt(63) lgkmcnt(1)
	v_pk_add_f32 v[118:119], v[238:239], v[118:119]
	v_pk_add_f32 v[120:121], v[240:241], v[120:121]
	v_pk_mul_f32 v[242:243], v[118:119], v[118:119]
	v_pk_mul_f32 v[244:245], v[120:121], v[120:121]
	ds_read_b128 v[238:241], v237 offset:7168
	v_add_f32_e32 v246, v242, v243
	v_add_f32_e32 v246, v244, v246
	v_add_f32_e32 v246, v245, v246
	global_store_dwordx4 v247, v[118:121], s[38:39] sc1
	v_cvt_pk_bf16_f32 v242, v118, v119
	v_cvt_pk_bf16_f32 v243, v120, v121
	v_add_f32_dpp v246, v246, v246 quad_perm:[1,0,3,2] row_mask:0xf bank_mask:0xf
	global_store_dwordx2 v248, v[242:243], s[50:51] sc1
	s_add_u32 s38, s38, 0x4000
	s_addc_u32 s39, s39, 0
	v_add_f32_dpp v246, v246, v246 quad_perm:[2,3,0,1] row_mask:0xf bank_mask:0xf
	s_add_u32 s50, s50, 0x2000
	s_addc_u32 s51, s51, 0
	v_add_f32_dpp v246, v246, v246 row_half_mirror row_mask:0xf bank_mask:0xf
	s_nop 1
	v_add_f32_dpp v246, v246, v246 row_mirror row_mask:0xf bank_mask:0xf
	s_mov_b64 exec, s[48:49]
	global_store_dword v249, v246, s[34:35] offset:1280
	s_mov_b64 exec, -1
	s_waitcnt vmcnt(63) lgkmcnt(1)
	v_pk_add_f32 v[122:123], v[228:229], v[122:123]
	v_pk_add_f32 v[124:125], v[230:231], v[124:125]
	v_pk_mul_f32 v[232:233], v[122:123], v[122:123]
	v_pk_mul_f32 v[234:235], v[124:125], v[124:125]
	ds_read_b128 v[228:231], v210 offset:8192
	v_add_f32_e32 v236, v232, v233
	v_add_f32_e32 v236, v234, v236
	v_add_f32_e32 v236, v235, v236
	global_store_dwordx4 v247, v[122:125], s[38:39] sc1
	v_cvt_pk_bf16_f32 v232, v122, v123
	v_cvt_pk_bf16_f32 v233, v124, v125
	v_add_f32_dpp v236, v236, v236 quad_perm:[1,0,3,2] row_mask:0xf bank_mask:0xf
	global_store_dwordx2 v248, v[232:233], s[50:51] sc1
	s_add_u32 s38, s38, 0x4000
	s_addc_u32 s39, s39, 0
	v_add_f32_dpp v236, v236, v236 quad_perm:[2,3,0,1] row_mask:0xf bank_mask:0xf
	s_add_u32 s50, s50, 0x2000
	s_addc_u32 s51, s51, 0
	v_add_f32_dpp v236, v236, v236 row_half_mirror row_mask:0xf bank_mask:0xf
	s_nop 1
	v_add_f32_dpp v236, v236, v236 row_mirror row_mask:0xf bank_mask:0xf
	s_mov_b64 exec, s[48:49]
	global_store_dword v249, v236, s[34:35] offset:1536
	s_mov_b64 exec, -1
	s_waitcnt vmcnt(63) lgkmcnt(1)
	v_pk_add_f32 v[126:127], v[238:239], v[126:127]
	v_pk_add_f32 v[128:129], v[240:241], v[128:129]
	v_pk_mul_f32 v[242:243], v[126:127], v[126:127]
	v_pk_mul_f32 v[244:245], v[128:129], v[128:129]
	ds_read_b128 v[238:241], v211 offset:9216
	v_add_f32_e32 v246, v242, v243
	v_add_f32_e32 v246, v244, v246
	v_add_f32_e32 v246, v245, v246
	global_store_dwordx4 v247, v[126:129], s[38:39] sc1
	v_cvt_pk_bf16_f32 v242, v126, v127
	v_cvt_pk_bf16_f32 v243, v128, v129
	v_add_f32_dpp v246, v246, v246 quad_perm:[1,0,3,2] row_mask:0xf bank_mask:0xf
	global_store_dwordx2 v248, v[242:243], s[50:51] sc1
	s_add_u32 s38, s38, 0x4000
	s_addc_u32 s39, s39, 0
	v_add_f32_dpp v246, v246, v246 quad_perm:[2,3,0,1] row_mask:0xf bank_mask:0xf
	s_add_u32 s50, s50, 0x2000
	s_addc_u32 s51, s51, 0
	v_add_f32_dpp v246, v246, v246 row_half_mirror row_mask:0xf bank_mask:0xf
	s_nop 1
	v_add_f32_dpp v246, v246, v246 row_mirror row_mask:0xf bank_mask:0xf
	s_mov_b64 exec, s[48:49]
	global_store_dword v249, v246, s[34:35] offset:1792
	s_mov_b64 exec, -1
	s_waitcnt vmcnt(63) lgkmcnt(1)
	v_pk_add_f32 v[66:67], v[228:229], v[66:67]
	v_pk_add_f32 v[68:69], v[230:231], v[68:69]
	v_pk_mul_f32 v[232:233], v[66:67], v[66:67]
	v_pk_mul_f32 v[234:235], v[68:69], v[68:69]
	ds_read_b128 v[228:231], v215 offset:10240
	v_add_f32_e32 v236, v232, v233
	v_add_f32_e32 v236, v234, v236
	v_add_f32_e32 v236, v235, v236
	global_store_dwordx4 v247, v[66:69], s[38:39] sc1
	v_cvt_pk_bf16_f32 v232, v66, v67
	v_cvt_pk_bf16_f32 v233, v68, v69
	v_add_f32_dpp v236, v236, v236 quad_perm:[1,0,3,2] row_mask:0xf bank_mask:0xf
	global_store_dwordx2 v248, v[232:233], s[50:51] sc1
	s_add_u32 s38, s38, 0x4000
	s_addc_u32 s39, s39, 0
	v_add_f32_dpp v236, v236, v236 quad_perm:[2,3,0,1] row_mask:0xf bank_mask:0xf
	s_add_u32 s50, s50, 0x2000
	s_addc_u32 s51, s51, 0
	v_add_f32_dpp v236, v236, v236 row_half_mirror row_mask:0xf bank_mask:0xf
	s_nop 1
	v_add_f32_dpp v236, v236, v236 row_mirror row_mask:0xf bank_mask:0xf
	s_mov_b64 exec, s[48:49]
	global_store_dword v249, v236, s[34:35] offset:2048
	s_mov_b64 exec, -1
	s_waitcnt vmcnt(63) lgkmcnt(1)
	v_pk_add_f32 v[70:71], v[238:239], v[70:71]
	v_pk_add_f32 v[72:73], v[240:241], v[72:73]
	v_pk_mul_f32 v[242:243], v[70:71], v[70:71]
	v_pk_mul_f32 v[244:245], v[72:73], v[72:73]
	ds_read_b128 v[238:241], v237 offset:11264
	v_add_f32_e32 v246, v242, v243
	v_add_f32_e32 v246, v244, v246
	v_add_f32_e32 v246, v245, v246
	global_store_dwordx4 v247, v[70:73], s[38:39] sc1
	v_cvt_pk_bf16_f32 v242, v70, v71
	v_cvt_pk_bf16_f32 v243, v72, v73
	v_add_f32_dpp v246, v246, v246 quad_perm:[1,0,3,2] row_mask:0xf bank_mask:0xf
	global_store_dwordx2 v248, v[242:243], s[50:51] sc1
	s_add_u32 s38, s38, 0x4000
	s_addc_u32 s39, s39, 0
	v_add_f32_dpp v246, v246, v246 quad_perm:[2,3,0,1] row_mask:0xf bank_mask:0xf
	s_add_u32 s50, s50, 0x2000
	s_addc_u32 s51, s51, 0
	v_add_f32_dpp v246, v246, v246 row_half_mirror row_mask:0xf bank_mask:0xf
	s_nop 1
	v_add_f32_dpp v246, v246, v246 row_mirror row_mask:0xf bank_mask:0xf
	s_mov_b64 exec, s[48:49]
	global_store_dword v249, v246, s[34:35] offset:2304
	s_mov_b64 exec, -1
	s_waitcnt vmcnt(63) lgkmcnt(1)
	v_pk_add_f32 v[74:75], v[228:229], v[74:75]
	v_pk_add_f32 v[76:77], v[230:231], v[76:77]
	v_pk_mul_f32 v[232:233], v[74:75], v[74:75]
	v_pk_mul_f32 v[234:235], v[76:77], v[76:77]
	ds_read_b128 v[228:231], v210 offset:12288
	v_add_f32_e32 v236, v232, v233
	v_add_f32_e32 v236, v234, v236
	v_add_f32_e32 v236, v235, v236
	global_store_dwordx4 v247, v[74:77], s[38:39] sc1
	v_cvt_pk_bf16_f32 v232, v74, v75
	v_cvt_pk_bf16_f32 v233, v76, v77
	v_add_f32_dpp v236, v236, v236 quad_perm:[1,0,3,2] row_mask:0xf bank_mask:0xf
	global_store_dwordx2 v248, v[232:233], s[50:51] sc1
	s_add_u32 s38, s38, 0x4000
	s_addc_u32 s39, s39, 0
	v_add_f32_dpp v236, v236, v236 quad_perm:[2,3,0,1] row_mask:0xf bank_mask:0xf
	s_add_u32 s50, s50, 0x2000
	s_addc_u32 s51, s51, 0
	v_add_f32_dpp v236, v236, v236 row_half_mirror row_mask:0xf bank_mask:0xf
	s_nop 1
	v_add_f32_dpp v236, v236, v236 row_mirror row_mask:0xf bank_mask:0xf
	s_mov_b64 exec, s[48:49]
	global_store_dword v249, v236, s[34:35] offset:2560
	s_mov_b64 exec, -1
	s_waitcnt vmcnt(63) lgkmcnt(1)
	v_pk_add_f32 v[78:79], v[238:239], v[78:79]
	v_pk_add_f32 v[80:81], v[240:241], v[80:81]
	v_pk_mul_f32 v[242:243], v[78:79], v[78:79]
	v_pk_mul_f32 v[244:245], v[80:81], v[80:81]
	ds_read_b128 v[238:241], v211 offset:13312
	v_add_f32_e32 v246, v242, v243
	v_add_f32_e32 v246, v244, v246
	v_add_f32_e32 v246, v245, v246
	global_store_dwordx4 v247, v[78:81], s[38:39] sc1
	v_cvt_pk_bf16_f32 v242, v78, v79
	v_cvt_pk_bf16_f32 v243, v80, v81
	v_add_f32_dpp v246, v246, v246 quad_perm:[1,0,3,2] row_mask:0xf bank_mask:0xf
	global_store_dwordx2 v248, v[242:243], s[50:51] sc1
	s_add_u32 s38, s38, 0x4000
	s_addc_u32 s39, s39, 0
	v_add_f32_dpp v246, v246, v246 quad_perm:[2,3,0,1] row_mask:0xf bank_mask:0xf
	s_add_u32 s50, s50, 0x2000
	s_addc_u32 s51, s51, 0
	v_add_f32_dpp v246, v246, v246 row_half_mirror row_mask:0xf bank_mask:0xf
	s_nop 1
	v_add_f32_dpp v246, v246, v246 row_mirror row_mask:0xf bank_mask:0xf
	s_mov_b64 exec, s[48:49]
	global_store_dword v249, v246, s[34:35] offset:2816
	s_mov_b64 exec, -1
	s_waitcnt vmcnt(63) lgkmcnt(1)
	v_pk_add_f32 v[98:99], v[228:229], v[98:99]
	v_pk_add_f32 v[100:101], v[230:231], v[100:101]
	v_pk_mul_f32 v[232:233], v[98:99], v[98:99]
	v_pk_mul_f32 v[234:235], v[100:101], v[100:101]
	ds_read_b128 v[228:231], v215 offset:14336
	v_add_f32_e32 v236, v232, v233
	v_add_f32_e32 v236, v234, v236
	v_add_f32_e32 v236, v235, v236
	global_store_dwordx4 v247, v[98:101], s[38:39] sc1
	v_cvt_pk_bf16_f32 v232, v98, v99
	v_cvt_pk_bf16_f32 v233, v100, v101
	v_add_f32_dpp v236, v236, v236 quad_perm:[1,0,3,2] row_mask:0xf bank_mask:0xf
	global_store_dwordx2 v248, v[232:233], s[50:51] sc1
	s_add_u32 s38, s38, 0x4000
	s_addc_u32 s39, s39, 0
	v_add_f32_dpp v236, v236, v236 quad_perm:[2,3,0,1] row_mask:0xf bank_mask:0xf
	s_add_u32 s50, s50, 0x2000
	s_addc_u32 s51, s51, 0
	v_add_f32_dpp v236, v236, v236 row_half_mirror row_mask:0xf bank_mask:0xf
	s_nop 1
	v_add_f32_dpp v236, v236, v236 row_mirror row_mask:0xf bank_mask:0xf
	s_mov_b64 exec, s[48:49]
	global_store_dword v249, v236, s[34:35] offset:3072
	s_mov_b64 exec, -1
	s_waitcnt vmcnt(63) lgkmcnt(1)
	v_pk_add_f32 v[102:103], v[238:239], v[102:103]
	v_pk_add_f32 v[104:105], v[240:241], v[104:105]
	v_pk_mul_f32 v[242:243], v[102:103], v[102:103]
	v_pk_mul_f32 v[244:245], v[104:105], v[104:105]
	ds_read_b128 v[238:241], v237 offset:15360
	v_add_f32_e32 v246, v242, v243
	v_add_f32_e32 v246, v244, v246
	v_add_f32_e32 v246, v245, v246
	global_store_dwordx4 v247, v[102:105], s[38:39] sc1
	v_cvt_pk_bf16_f32 v242, v102, v103
	v_cvt_pk_bf16_f32 v243, v104, v105
	v_add_f32_dpp v246, v246, v246 quad_perm:[1,0,3,2] row_mask:0xf bank_mask:0xf
	global_store_dwordx2 v248, v[242:243], s[50:51] sc1
	s_add_u32 s38, s38, 0x4000
	s_addc_u32 s39, s39, 0
	v_add_f32_dpp v246, v246, v246 quad_perm:[2,3,0,1] row_mask:0xf bank_mask:0xf
	s_add_u32 s50, s50, 0x2000
	s_addc_u32 s51, s51, 0
	v_add_f32_dpp v246, v246, v246 row_half_mirror row_mask:0xf bank_mask:0xf
	s_nop 1
	v_add_f32_dpp v246, v246, v246 row_mirror row_mask:0xf bank_mask:0xf
	s_mov_b64 exec, s[48:49]
	global_store_dword v249, v246, s[34:35] offset:3328
	s_mov_b64 exec, -1
	s_waitcnt vmcnt(63) lgkmcnt(1)
	v_pk_add_f32 v[106:107], v[228:229], v[106:107]
	v_pk_add_f32 v[108:109], v[230:231], v[108:109]
	v_pk_mul_f32 v[232:233], v[106:107], v[106:107]
	v_pk_mul_f32 v[234:235], v[108:109], v[108:109]
	v_add_f32_e32 v236, v232, v233
	v_add_f32_e32 v236, v234, v236
	v_add_f32_e32 v236, v235, v236
	global_store_dwordx4 v247, v[106:109], s[38:39] sc1
	v_cvt_pk_bf16_f32 v232, v106, v107
	v_cvt_pk_bf16_f32 v233, v108, v109
	v_add_f32_dpp v236, v236, v236 quad_perm:[1,0,3,2] row_mask:0xf bank_mask:0xf
	global_store_dwordx2 v248, v[232:233], s[50:51] sc1
	s_add_u32 s38, s38, 0x4000
	s_addc_u32 s39, s39, 0
	v_add_f32_dpp v236, v236, v236 quad_perm:[2,3,0,1] row_mask:0xf bank_mask:0xf
	s_add_u32 s50, s50, 0x2000
	s_addc_u32 s51, s51, 0
	v_add_f32_dpp v236, v236, v236 row_half_mirror row_mask:0xf bank_mask:0xf
	s_nop 1
	v_add_f32_dpp v236, v236, v236 row_mirror row_mask:0xf bank_mask:0xf
	s_mov_b64 exec, s[48:49]
	global_store_dword v249, v236, s[34:35] offset:3584
	s_mov_b64 exec, -1
	s_waitcnt vmcnt(63) lgkmcnt(0)
	v_pk_add_f32 v[110:111], v[238:239], v[110:111]
	v_pk_add_f32 v[112:113], v[240:241], v[112:113]
	v_pk_mul_f32 v[242:243], v[110:111], v[110:111]
	v_pk_mul_f32 v[244:245], v[112:113], v[112:113]
	v_add_f32_e32 v246, v242, v243
	v_add_f32_e32 v246, v244, v246
	v_add_f32_e32 v246, v245, v246
	global_store_dwordx4 v247, v[110:113], s[38:39] sc1
	v_cvt_pk_bf16_f32 v242, v110, v111
	v_cvt_pk_bf16_f32 v243, v112, v113
	v_add_f32_dpp v246, v246, v246 quad_perm:[1,0,3,2] row_mask:0xf bank_mask:0xf
	global_store_dwordx2 v248, v[242:243], s[50:51] sc1
	s_add_u32 s38, s38, 0x4000
	s_addc_u32 s39, s39, 0
	v_add_f32_dpp v246, v246, v246 quad_perm:[2,3,0,1] row_mask:0xf bank_mask:0xf
	s_add_u32 s50, s50, 0x2000
	s_addc_u32 s51, s51, 0
	v_add_f32_dpp v246, v246, v246 row_half_mirror row_mask:0xf bank_mask:0xf
	s_nop 1
	v_add_f32_dpp v246, v246, v246 row_mirror row_mask:0xf bank_mask:0xf
	s_mov_b64 exec, s[48:49]
	global_store_dword v249, v246, s[34:35] offset:3840
	s_mov_b64 exec, -1
	s_waitcnt lgkmcnt(0)
	s_branch .LBB0_1507

.LBB0_1601:
	v_mov_b32_e32 v0, v174
	v_mov_b32_e32 v133, v177
	v_mov_b32_e32 v132, v175
	v_mov_b32_e32 v134, v180
	v_mov_b32_e32 v162, v176
	v_mov_b32_e32 v135, v179
	v_mov_b32_e32 v163, v173
	ds_read2_b32 v[150:151], v185 offset1:32
	ds_read2_b32 v[130:131], v185 offset0:64 offset1:96
	s_lshl_b32 s1, s6, 8
	v_readfirstlane_b32 s0, v134
	v_lshlrev_b32_e32 v0, 14, v0
	v_lshlrev_b32_e32 v134, 7, v162
	v_lshlrev_b32_e32 v133, 3, v133
	v_ashrrev_i32_e32 v148, 3, v163
	v_add3_u32 v133, v0, v134, v133
	v_xor_b32_e32 v134, v148, v163
	v_lshlrev_b32_e32 v134, 4, v134
	v_add_u32_e32 v142, 32, v148
	v_and_or_b32 v0, v134, s55, v0
	v_ashrrev_i32_e32 v149, 31, v148
	v_ashrrev_i32_e32 v143, 31, v142
	v_lshlrev_b32_e32 v152, 6, v135
	v_lshl_add_u32 v154, v148, 7, v0
	v_lshlrev_b64 v[134:135], 13, v[148:149]
	v_add_u32_e32 v136, 8, v148
	v_add_u32_e32 v138, 16, v148
	v_add_u32_e32 v140, 24, v148
	v_lshl_add_u32 v158, v142, 7, v0
	v_lshlrev_b64 v[144:145], 13, v[142:143]
	v_add_u32_e32 v142, 40, v148
	v_add_u32_e32 v146, 48, v148
	v_add_u32_e32 v148, 56, v148
	v_lshl_add_u32 v155, v136, 7, v0
	v_lshl_add_u32 v156, v138, 7, v0
	v_lshl_add_u32 v157, v140, 7, v0
	v_lshl_add_u32 v159, v142, 7, v0
	v_lshl_add_u32 v160, v146, 7, v0
	v_lshl_add_u32 v161, v148, 7, v0
	s_waitcnt lgkmcnt(1)
	v_mul_f32_e32 v0, v98, v150
	v_mul_f32_e32 v98, v99, v150
	v_max_f32_e32 v0, 0, v0
	v_max_f32_e32 v98, 0, v98
	v_mul_f32_e32 v99, v100, v150
	v_mul_f32_e32 v100, v101, v150
	v_max_f32_e32 v99, 0, v99
	v_max_f32_e32 v100, 0, v100
	v_mul_f32_e32 v0, v0, v0
	v_mul_f32_e32 v98, v98, v98
	v_cvt_pk_bf16_f32 v98, v0, v98
	v_mul_f32_e32 v0, v99, v99
	v_mul_f32_e32 v99, v100, v100
	v_cvt_pk_bf16_f32 v99, v0, v99
	v_lshlrev_b32_e32 v0, 4, v162
	v_and_b32_e32 v0, 0x70, v0
	v_add_u32_e32 v100, v133, v0
	ds_write_b64 v100, v[98:99]
	v_mul_f32_e32 v98, v102, v150
	v_mul_f32_e32 v99, v103, v150
	v_max_f32_e32 v98, 0, v98
	v_max_f32_e32 v99, 0, v99
	v_mul_f32_e32 v101, v104, v150
	v_mul_f32_e32 v102, v105, v150
	v_max_f32_e32 v101, 0, v101
	v_max_f32_e32 v102, 0, v102
	v_mul_f32_e32 v98, v98, v98
	v_mul_f32_e32 v99, v99, v99
	v_cvt_pk_bf16_f32 v98, v98, v99
	v_mul_f32_e32 v99, v101, v101
	v_mul_f32_e32 v101, v102, v102
	v_cvt_pk_bf16_f32 v99, v99, v101
	v_xad_u32 v101, v0, 16, v133
	ds_write_b64 v101, v[98:99]
	v_mul_f32_e32 v98, v106, v150
	v_mul_f32_e32 v99, v107, v150
	v_max_f32_e32 v98, 0, v98
	v_max_f32_e32 v99, 0, v99
	v_mul_f32_e32 v102, v108, v150
	v_mul_f32_e32 v103, v109, v150
	v_max_f32_e32 v102, 0, v102
	v_max_f32_e32 v103, 0, v103
	v_mul_f32_e32 v98, v98, v98
	v_mul_f32_e32 v99, v99, v99
	v_cvt_pk_bf16_f32 v98, v98, v99
	v_mul_f32_e32 v99, v102, v102
	v_mul_f32_e32 v102, v103, v103
	v_cvt_pk_bf16_f32 v99, v99, v102
	v_xad_u32 v102, v0, 32, v133
	ds_write_b64 v102, v[98:99]
	v_mul_f32_e32 v98, v110, v150
	v_mul_f32_e32 v99, v111, v150
	v_max_f32_e32 v98, 0, v98
	v_max_f32_e32 v99, 0, v99
	v_mul_f32_e32 v103, v112, v150
	v_mul_f32_e32 v104, v113, v150
	v_max_f32_e32 v103, 0, v103
	v_max_f32_e32 v104, 0, v104
	v_mul_f32_e32 v98, v98, v98
	v_mul_f32_e32 v99, v99, v99
	v_cvt_pk_bf16_f32 v98, v98, v99
	v_mul_f32_e32 v99, v103, v103
	v_mul_f32_e32 v103, v104, v104
	v_cvt_pk_bf16_f32 v99, v99, v103
	v_xad_u32 v103, v0, 48, v133
	ds_write_b64 v103, v[98:99]
	v_mul_f32_e32 v98, v114, v150
	v_mul_f32_e32 v99, v115, v150
	v_max_f32_e32 v98, 0, v98
	v_max_f32_e32 v99, 0, v99
	v_mul_f32_e32 v104, v116, v150
	v_mul_f32_e32 v105, v117, v150
	v_max_f32_e32 v104, 0, v104
	v_max_f32_e32 v105, 0, v105
	v_mul_f32_e32 v98, v98, v98
	v_mul_f32_e32 v99, v99, v99
	v_cvt_pk_bf16_f32 v98, v98, v99
	v_mul_f32_e32 v99, v104, v104
	v_mul_f32_e32 v104, v105, v105
	v_cvt_pk_bf16_f32 v99, v99, v104
	v_xad_u32 v104, v0, 64, v133
	ds_write_b64 v104, v[98:99]
	v_mul_f32_e32 v98, v118, v150
	v_mul_f32_e32 v99, v119, v150
	v_max_f32_e32 v98, 0, v98
	v_max_f32_e32 v99, 0, v99
	v_mul_f32_e32 v105, v120, v150
	v_mul_f32_e32 v106, v121, v150
	v_max_f32_e32 v105, 0, v105
	v_max_f32_e32 v106, 0, v106
	v_mul_f32_e32 v98, v98, v98
	v_mul_f32_e32 v99, v99, v99
	v_cvt_pk_bf16_f32 v98, v98, v99
	v_mul_f32_e32 v99, v105, v105
	v_mul_f32_e32 v105, v106, v106
	v_cvt_pk_bf16_f32 v99, v99, v105
	v_xad_u32 v105, v0, s70, v133
	ds_write_b64 v105, v[98:99]
	v_mul_f32_e32 v98, v122, v150
	v_mul_f32_e32 v99, v123, v150
	v_max_f32_e32 v98, 0, v98
	v_max_f32_e32 v99, 0, v99
	v_mul_f32_e32 v106, v124, v150
	v_mul_f32_e32 v107, v125, v150
	v_max_f32_e32 v106, 0, v106
	v_max_f32_e32 v107, 0, v107
	v_mul_f32_e32 v98, v98, v98
	v_mul_f32_e32 v99, v99, v99
	v_cvt_pk_bf16_f32 v98, v98, v99
	v_mul_f32_e32 v99, v106, v106
	v_mul_f32_e32 v106, v107, v107
	v_cvt_pk_bf16_f32 v99, v99, v106
	v_xad_u32 v106, v0, s63, v133
	ds_write_b64 v106, v[98:99]
	v_mul_f32_e32 v98, v126, v150
	v_mul_f32_e32 v99, v127, v150
	v_max_f32_e32 v98, 0, v98
	v_max_f32_e32 v99, 0, v99
	v_mul_f32_e32 v107, v128, v150
	v_mul_f32_e32 v108, v129, v150
	v_max_f32_e32 v107, 0, v107
	v_max_f32_e32 v108, 0, v108
	v_mul_f32_e32 v98, v98, v98
	v_mul_f32_e32 v99, v99, v99
	v_cvt_pk_bf16_f32 v98, v98, v99
	v_mul_f32_e32 v99, v107, v107
	v_mul_f32_e32 v107, v108, v108
	v_cvt_pk_bf16_f32 v99, v99, v107
	v_xad_u32 v107, v0, s55, v133
	v_mul_f32_e32 v0, v82, v151
	v_mul_f32_e32 v82, v83, v151
	v_max_f32_e32 v0, 0, v0
	v_max_f32_e32 v82, 0, v82
	v_mul_f32_e32 v83, v84, v151
	v_mul_f32_e32 v84, v85, v151
	v_max_f32_e32 v83, 0, v83
	v_max_f32_e32 v84, 0, v84
	v_mul_f32_e32 v0, v0, v0
	v_mul_f32_e32 v82, v82, v82
	v_cvt_pk_bf16_f32 v82, v0, v82
	v_mul_f32_e32 v0, v83, v83
	v_mul_f32_e32 v83, v84, v84
	v_cvt_pk_bf16_f32 v83, v0, v83
	ds_write_b64 v100, v[82:83] offset:4096
	v_mul_f32_e32 v0, v86, v151
	v_mul_f32_e32 v82, v87, v151
	v_max_f32_e32 v0, 0, v0
	v_max_f32_e32 v82, 0, v82
	v_mul_f32_e32 v83, v88, v151
	v_mul_f32_e32 v84, v89, v151
	v_max_f32_e32 v83, 0, v83
	v_max_f32_e32 v84, 0, v84
	v_mul_f32_e32 v0, v0, v0
	v_mul_f32_e32 v82, v82, v82
	v_cvt_pk_bf16_f32 v82, v0, v82
	v_mul_f32_e32 v0, v83, v83
	v_mul_f32_e32 v83, v84, v84
	v_cvt_pk_bf16_f32 v83, v0, v83
	ds_write_b64 v101, v[82:83] offset:4096
	v_mul_f32_e32 v0, v90, v151
	v_mul_f32_e32 v82, v91, v151
	v_max_f32_e32 v0, 0, v0
	v_max_f32_e32 v82, 0, v82
	v_mul_f32_e32 v83, v92, v151
	v_mul_f32_e32 v84, v93, v151
	v_max_f32_e32 v83, 0, v83
	v_max_f32_e32 v84, 0, v84
	v_mul_f32_e32 v0, v0, v0
	v_mul_f32_e32 v82, v82, v82
	v_cvt_pk_bf16_f32 v82, v0, v82
	v_mul_f32_e32 v0, v83, v83
	v_mul_f32_e32 v83, v84, v84
	v_cvt_pk_bf16_f32 v83, v0, v83
	ds_write_b64 v102, v[82:83] offset:4096
	v_mul_f32_e32 v0, v94, v151
	v_mul_f32_e32 v82, v95, v151
	v_max_f32_e32 v0, 0, v0
	v_max_f32_e32 v82, 0, v82
	v_mul_f32_e32 v83, v96, v151
	v_mul_f32_e32 v84, v97, v151
	v_max_f32_e32 v83, 0, v83
	v_max_f32_e32 v84, 0, v84
	v_mul_f32_e32 v0, v0, v0
	v_mul_f32_e32 v82, v82, v82
	v_cvt_pk_bf16_f32 v82, v0, v82
	v_mul_f32_e32 v0, v83, v83
	v_mul_f32_e32 v83, v84, v84
	v_cvt_pk_bf16_f32 v83, v0, v83
	v_mul_f32_e32 v0, v66, v151
	v_mul_f32_e32 v66, v67, v151
	v_max_f32_e32 v0, 0, v0
	v_max_f32_e32 v66, 0, v66
	v_mul_f32_e32 v67, v68, v151
	v_mul_f32_e32 v68, v69, v151
	v_max_f32_e32 v67, 0, v67
	v_max_f32_e32 v68, 0, v68
	v_mul_f32_e32 v0, v0, v0
	v_mul_f32_e32 v66, v66, v66
	v_cvt_pk_bf16_f32 v66, v0, v66
	v_mul_f32_e32 v0, v67, v67
	v_mul_f32_e32 v67, v68, v68
	v_cvt_pk_bf16_f32 v67, v0, v67
	ds_write_b64 v103, v[82:83] offset:4096
	ds_write_b64 v104, v[66:67] offset:4096
	v_mul_f32_e32 v0, v70, v151
	v_mul_f32_e32 v66, v71, v151
	v_max_f32_e32 v0, 0, v0
	v_max_f32_e32 v66, 0, v66
	v_mul_f32_e32 v67, v72, v151
	v_mul_f32_e32 v68, v73, v151
	v_max_f32_e32 v67, 0, v67
	v_max_f32_e32 v68, 0, v68
	v_mul_f32_e32 v0, v0, v0
	v_mul_f32_e32 v66, v66, v66
	v_cvt_pk_bf16_f32 v66, v0, v66
	v_mul_f32_e32 v0, v67, v67
	v_mul_f32_e32 v67, v68, v68
	v_cvt_pk_bf16_f32 v67, v0, v67
	ds_write_b64 v105, v[66:67] offset:4096
	v_mul_f32_e32 v0, v74, v151
	v_mul_f32_e32 v66, v75, v151
	v_max_f32_e32 v0, 0, v0
	v_max_f32_e32 v66, 0, v66
	v_mul_f32_e32 v67, v76, v151
	v_mul_f32_e32 v68, v77, v151
	v_max_f32_e32 v67, 0, v67
	v_max_f32_e32 v68, 0, v68
	v_mul_f32_e32 v0, v0, v0
	v_mul_f32_e32 v66, v66, v66
	v_cvt_pk_bf16_f32 v66, v0, v66
	v_mul_f32_e32 v0, v67, v67
	v_mul_f32_e32 v67, v68, v68
	v_cvt_pk_bf16_f32 v67, v0, v67
	ds_write_b64 v106, v[66:67] offset:4096
	v_mul_f32_e32 v0, v78, v151
	v_mul_f32_e32 v66, v79, v151
	v_max_f32_e32 v0, 0, v0
	v_max_f32_e32 v66, 0, v66
	v_mul_f32_e32 v67, v80, v151
	v_mul_f32_e32 v68, v81, v151
	v_max_f32_e32 v67, 0, v67
	v_max_f32_e32 v68, 0, v68
	v_mul_f32_e32 v0, v0, v0
	v_mul_f32_e32 v66, v66, v66
	s_lshl_b32 s0, s0, 7
	v_lshl_add_u32 v132, v132, 7, s4
	v_cvt_pk_bf16_f32 v66, v0, v66
	v_mul_f32_e32 v0, v67, v67
	v_mul_f32_e32 v67, v68, v68
	s_add_i32 s0, s0, s1
	v_cvt_pk_bf16_f32 v67, v0, v67
	v_ashrrev_i32_e32 v133, 31, v132
	v_readlane_b32 s4, v250, 48
	s_ashr_i32 s1, s0, 31
	ds_write_b64 v107, v[66:67] offset:4096
	v_lshlrev_b64 v[66:67], 13, v[132:133]
	v_readlane_b32 s5, v250, 49
	v_ashrrev_i32_e32 v153, 31, v152
	s_lshl_b64 s[0:1], s[0:1], 1
	v_lshl_add_u64 v[66:67], s[4:5], 0, v[66:67]
	ds_write_b64 v107, v[98:99]
	v_lshl_add_u64 v[68:69], v[66:67], 0, s[0:1]
	v_lshlrev_b64 v[66:67], 1, v[152:153]
	v_lshl_add_u64 v[72:73], v[68:69], 0, v[66:67]
	ds_read_b128 v[68:71], v154
	v_lshlrev_b32_e32 v0, 4, v163
	v_and_b32_e32 v0, 0x70, v0
	v_lshl_add_u64 v[80:81], v[72:73], 0, v[0:1]
	ds_read_b128 v[72:75], v155
	v_lshl_add_u64 v[76:77], v[80:81], 0, v[134:135]
	s_waitcnt lgkmcnt(1)
	global_store_dwordx4 v[76:77], v[68:71], off sc1
	ds_read_b128 v[68:71], v156
	v_ashrrev_i32_e32 v137, 31, v136
	v_lshlrev_b64 v[136:137], 13, v[136:137]
	v_ashrrev_i32_e32 v139, 31, v138
	v_lshlrev_b64 v[138:139], 13, v[138:139]
	v_lshl_add_u64 v[76:77], v[80:81], 0, v[136:137]
	s_waitcnt lgkmcnt(1)
	global_store_dwordx4 v[76:77], v[72:75], off sc1
	ds_read_b128 v[72:75], v157
	v_lshl_add_u64 v[76:77], v[80:81], 0, v[138:139]
	s_waitcnt lgkmcnt(1)
	global_store_dwordx4 v[76:77], v[68:71], off sc1
	ds_read_b128 v[68:71], v158
	v_mul_f32_e32 v18, v18, v131
	v_mul_f32_e32 v19, v19, v131
	v_ashrrev_i32_e32 v141, 31, v140
	v_max_f32_e32 v18, 0, v18
	v_max_f32_e32 v19, 0, v19
	v_mul_f32_e32 v20, v20, v131
	v_mul_f32_e32 v21, v21, v131
	v_lshlrev_b64 v[140:141], 13, v[140:141]
	v_max_f32_e32 v20, 0, v20
	v_max_f32_e32 v21, 0, v21
	v_mul_f32_e32 v18, v18, v18
	v_mul_f32_e32 v19, v19, v19
	v_lshl_add_u64 v[76:77], v[80:81], 0, v[140:141]
	v_mul_f32_e32 v50, v50, v130
	v_mul_f32_e32 v51, v51, v130
	v_cvt_pk_bf16_f32 v18, v18, v19
	v_mul_f32_e32 v19, v20, v20
	v_mul_f32_e32 v20, v21, v21
	s_waitcnt lgkmcnt(1)
	global_store_dwordx4 v[76:77], v[72:75], off sc1
	v_lshl_add_u64 v[76:77], v[80:81], 0, v[144:145]
	v_max_f32_e32 v50, 0, v50
	v_max_f32_e32 v51, 0, v51
	v_mul_f32_e32 v52, v52, v130
	v_mul_f32_e32 v53, v53, v130
	v_cvt_pk_bf16_f32 v19, v19, v20
	ds_read_b128 v[72:75], v159
	s_waitcnt lgkmcnt(1)
	global_store_dwordx4 v[76:77], v[68:71], off sc1
	ds_read_b128 v[68:71], v160
	ds_read_b128 v[76:79], v161
	v_max_f32_e32 v52, 0, v52
	v_max_f32_e32 v53, 0, v53
	v_mul_f32_e32 v50, v50, v50
	v_mul_f32_e32 v51, v51, v51
	ds_write_b64 v100, v[18:19] offset:4096
	v_mul_f32_e32 v18, v22, v131
	v_mul_f32_e32 v19, v23, v131
	v_cvt_pk_bf16_f32 v50, v50, v51
	v_mul_f32_e32 v51, v52, v52
	v_mul_f32_e32 v52, v53, v53
	v_max_f32_e32 v18, 0, v18
	v_max_f32_e32 v19, 0, v19
	v_mul_f32_e32 v20, v24, v131
	v_mul_f32_e32 v21, v25, v131
	v_cvt_pk_bf16_f32 v51, v51, v52
	v_max_f32_e32 v20, 0, v20
	v_max_f32_e32 v21, 0, v21
	v_mul_f32_e32 v18, v18, v18
	v_mul_f32_e32 v19, v19, v19
	ds_write_b64 v100, v[50:51]
	v_mul_f32_e32 v50, v54, v130
	v_mul_f32_e32 v51, v55, v130
	v_cvt_pk_bf16_f32 v18, v18, v19
	v_mul_f32_e32 v19, v20, v20
	v_mul_f32_e32 v20, v21, v21
	v_max_f32_e32 v50, 0, v50
	v_max_f32_e32 v51, 0, v51
	v_mul_f32_e32 v52, v56, v130
	v_mul_f32_e32 v53, v57, v130
	v_cvt_pk_bf16_f32 v19, v19, v20
	v_max_f32_e32 v52, 0, v52
	v_max_f32_e32 v53, 0, v53
	v_mul_f32_e32 v50, v50, v50
	v_mul_f32_e32 v51, v51, v51
	ds_write_b64 v101, v[18:19] offset:4096
	v_mul_f32_e32 v18, v26, v131
	v_mul_f32_e32 v19, v27, v131
	v_cvt_pk_bf16_f32 v50, v50, v51
	v_mul_f32_e32 v51, v52, v52
	v_mul_f32_e32 v52, v53, v53
	v_max_f32_e32 v18, 0, v18
	v_max_f32_e32 v19, 0, v19
	v_mul_f32_e32 v20, v28, v131
	v_mul_f32_e32 v21, v29, v131
	v_cvt_pk_bf16_f32 v51, v51, v52
	v_max_f32_e32 v20, 0, v20
	v_max_f32_e32 v21, 0, v21
	v_mul_f32_e32 v18, v18, v18
	v_mul_f32_e32 v19, v19, v19
	ds_write_b64 v101, v[50:51]
	v_mul_f32_e32 v50, v58, v130
	v_mul_f32_e32 v51, v59, v130
	v_cvt_pk_bf16_f32 v18, v18, v19
	v_mul_f32_e32 v19, v20, v20
	v_mul_f32_e32 v20, v21, v21
	v_max_f32_e32 v50, 0, v50
	v_max_f32_e32 v51, 0, v51
	v_mul_f32_e32 v52, v60, v130
	v_mul_f32_e32 v53, v61, v130
	v_cvt_pk_bf16_f32 v19, v19, v20
	v_max_f32_e32 v52, 0, v52
	v_max_f32_e32 v53, 0, v53
	v_mul_f32_e32 v50, v50, v50
	v_mul_f32_e32 v51, v51, v51
	ds_write_b64 v102, v[18:19] offset:4096
	v_mul_f32_e32 v18, v30, v131
	v_mul_f32_e32 v19, v31, v131
	v_mul_f32_e32 v2, v2, v131
	v_mul_f32_e32 v3, v3, v131
	v_cvt_pk_bf16_f32 v50, v50, v51
	v_mul_f32_e32 v51, v52, v52
	v_mul_f32_e32 v52, v53, v53
	v_max_f32_e32 v18, 0, v18
	v_max_f32_e32 v19, 0, v19
	v_mul_f32_e32 v20, v32, v131
	v_mul_f32_e32 v21, v33, v131
	v_max_f32_e32 v2, 0, v2
	v_max_f32_e32 v3, 0, v3
	v_mul_f32_e32 v4, v4, v131
	v_mul_f32_e32 v5, v5, v131
	v_cvt_pk_bf16_f32 v51, v51, v52
	v_max_f32_e32 v20, 0, v20
	v_max_f32_e32 v21, 0, v21
	v_mul_f32_e32 v18, v18, v18
	v_mul_f32_e32 v19, v19, v19
	v_max_f32_e32 v4, 0, v4
	v_max_f32_e32 v5, 0, v5
	v_mul_f32_e32 v2, v2, v2
	v_mul_f32_e32 v3, v3, v3
	ds_write_b64 v102, v[50:51]
	v_mul_f32_e32 v50, v62, v130
	v_mul_f32_e32 v51, v63, v130
	v_mul_f32_e32 v34, v34, v130
	v_mul_f32_e32 v35, v35, v130
	v_cvt_pk_bf16_f32 v18, v18, v19
	v_mul_f32_e32 v19, v20, v20
	v_mul_f32_e32 v20, v21, v21
	v_cvt_pk_bf16_f32 v2, v2, v3
	v_mul_f32_e32 v3, v4, v4
	v_mul_f32_e32 v4, v5, v5
	v_max_f32_e32 v50, 0, v50
	v_max_f32_e32 v51, 0, v51
	v_mul_f32_e32 v52, v64, v130
	v_mul_f32_e32 v53, v65, v130
	v_max_f32_e32 v34, 0, v34
	v_max_f32_e32 v35, 0, v35
	v_mul_f32_e32 v36, v36, v130
	v_mul_f32_e32 v37, v37, v130
	v_cvt_pk_bf16_f32 v19, v19, v20
	v_cvt_pk_bf16_f32 v3, v3, v4
	v_max_f32_e32 v52, 0, v52
	v_max_f32_e32 v53, 0, v53
	v_mul_f32_e32 v50, v50, v50
	v_mul_f32_e32 v51, v51, v51
	v_max_f32_e32 v36, 0, v36
	v_max_f32_e32 v37, 0, v37
	v_mul_f32_e32 v34, v34, v34
	v_mul_f32_e32 v35, v35, v35
	ds_write_b64 v103, v[18:19] offset:4096
	ds_write_b64 v104, v[2:3] offset:4096
	v_mul_f32_e32 v2, v6, v131
	v_mul_f32_e32 v3, v7, v131
	v_cvt_pk_bf16_f32 v50, v50, v51
	v_mul_f32_e32 v51, v52, v52
	v_mul_f32_e32 v52, v53, v53
	v_cvt_pk_bf16_f32 v34, v34, v35
	v_mul_f32_e32 v35, v36, v36
	v_mul_f32_e32 v36, v37, v37
	v_max_f32_e32 v2, 0, v2
	v_max_f32_e32 v3, 0, v3
	v_mul_f32_e32 v4, v8, v131
	v_mul_f32_e32 v5, v9, v131
	v_cvt_pk_bf16_f32 v51, v51, v52
	v_cvt_pk_bf16_f32 v35, v35, v36
	v_max_f32_e32 v4, 0, v4
	v_max_f32_e32 v5, 0, v5
	v_mul_f32_e32 v2, v2, v2
	v_mul_f32_e32 v3, v3, v3
	ds_write_b64 v103, v[50:51]
	ds_write_b64 v104, v[34:35]
	v_mul_f32_e32 v34, v38, v130
	v_mul_f32_e32 v35, v39, v130
	v_cvt_pk_bf16_f32 v2, v2, v3
	v_mul_f32_e32 v3, v4, v4
	v_mul_f32_e32 v4, v5, v5
	v_max_f32_e32 v34, 0, v34
	v_max_f32_e32 v35, 0, v35
	v_mul_f32_e32 v36, v40, v130
	v_mul_f32_e32 v37, v41, v130
	v_cvt_pk_bf16_f32 v3, v3, v4
	v_max_f32_e32 v36, 0, v36
	v_max_f32_e32 v37, 0, v37
	v_mul_f32_e32 v34, v34, v34
	v_mul_f32_e32 v35, v35, v35
	ds_write_b64 v105, v[2:3] offset:4096
	v_mul_f32_e32 v2, v10, v131
	v_mul_f32_e32 v3, v11, v131
	v_cvt_pk_bf16_f32 v34, v34, v35
	v_mul_f32_e32 v35, v36, v36
	v_mul_f32_e32 v36, v37, v37
	v_max_f32_e32 v2, 0, v2
	v_max_f32_e32 v3, 0, v3
	v_mul_f32_e32 v4, v12, v131
	v_mul_f32_e32 v5, v13, v131
	v_cvt_pk_bf16_f32 v35, v35, v36
	v_max_f32_e32 v4, 0, v4
	v_max_f32_e32 v5, 0, v5
	v_mul_f32_e32 v2, v2, v2
	v_mul_f32_e32 v3, v3, v3
	ds_write_b64 v105, v[34:35]
	v_mul_f32_e32 v34, v42, v130
	v_mul_f32_e32 v35, v43, v130
	v_cvt_pk_bf16_f32 v2, v2, v3
	v_mul_f32_e32 v3, v4, v4
	v_mul_f32_e32 v4, v5, v5
	v_max_f32_e32 v34, 0, v34
	v_max_f32_e32 v35, 0, v35
	v_mul_f32_e32 v36, v44, v130
	v_mul_f32_e32 v37, v45, v130
	v_cvt_pk_bf16_f32 v3, v3, v4
	v_max_f32_e32 v36, 0, v36
	v_max_f32_e32 v37, 0, v37
	v_mul_f32_e32 v34, v34, v34
	v_mul_f32_e32 v35, v35, v35
	ds_write_b64 v106, v[2:3] offset:4096
	v_mul_f32_e32 v2, v14, v131
	v_mul_f32_e32 v3, v15, v131
	v_cvt_pk_bf16_f32 v34, v34, v35
	v_mul_f32_e32 v35, v36, v36
	v_mul_f32_e32 v36, v37, v37
	v_max_f32_e32 v2, 0, v2
	v_max_f32_e32 v3, 0, v3
	v_mul_f32_e32 v4, v16, v131
	v_mul_f32_e32 v5, v17, v131
	v_cvt_pk_bf16_f32 v35, v35, v36
	v_max_f32_e32 v4, 0, v4
	v_max_f32_e32 v5, 0, v5
	v_mul_f32_e32 v2, v2, v2
	v_mul_f32_e32 v3, v3, v3
	ds_write_b64 v106, v[34:35]
	v_mul_f32_e32 v34, v46, v130
	v_mul_f32_e32 v35, v47, v130
	v_cvt_pk_bf16_f32 v2, v2, v3
	v_mul_f32_e32 v3, v4, v4
	v_mul_f32_e32 v4, v5, v5
	v_max_f32_e32 v34, 0, v34
	v_max_f32_e32 v35, 0, v35
	v_mul_f32_e32 v36, v48, v130
	v_mul_f32_e32 v37, v49, v130
	v_cvt_pk_bf16_f32 v3, v3, v4
	v_max_f32_e32 v36, 0, v36
	v_max_f32_e32 v37, 0, v37
	v_mul_f32_e32 v34, v34, v34
	v_mul_f32_e32 v35, v35, v35
	ds_write_b64 v107, v[2:3] offset:4096
	v_or_b32_e32 v2, 64, v132
	v_cvt_pk_bf16_f32 v34, v34, v35
	v_mul_f32_e32 v35, v36, v36
	v_mul_f32_e32 v36, v37, v37
	v_ashrrev_i32_e32 v3, 31, v2
	v_cvt_pk_bf16_f32 v35, v35, v36
	v_lshlrev_b64 v[2:3], 13, v[2:3]
	ds_write_b64 v107, v[34:35]
	v_lshl_add_u64 v[2:3], s[4:5], 0, v[2:3]
	v_lshl_add_u64 v[6:7], v[2:3], 0, s[0:1]
	ds_read_b128 v[2:5], v154
	v_lshl_add_u64 v[6:7], v[6:7], 0, v[66:67]
	v_lshl_add_u64 v[14:15], v[6:7], 0, v[0:1]
	ds_read_b128 v[6:9], v155
	v_lshl_add_u64 v[10:11], v[14:15], 0, v[134:135]
	s_waitcnt lgkmcnt(1)
	global_store_dwordx4 v[10:11], v[2:5], off sc1
	ds_read_b128 v[2:5], v156
	v_lshl_add_u64 v[10:11], v[14:15], 0, v[136:137]
	s_waitcnt lgkmcnt(1)
	global_store_dwordx4 v[10:11], v[6:9], off sc1
	ds_read_b128 v[6:9], v157
	v_lshl_add_u64 v[10:11], v[14:15], 0, v[138:139]
	s_waitcnt lgkmcnt(1)
	global_store_dwordx4 v[10:11], v[2:5], off sc1
	ds_read_b128 v[2:5], v158
	v_lshl_add_u64 v[10:11], v[14:15], 0, v[140:141]
	s_waitcnt lgkmcnt(1)
	global_store_dwordx4 v[10:11], v[6:9], off sc1
	v_lshl_add_u64 v[10:11], v[14:15], 0, v[144:145]
	ds_read_b128 v[6:9], v159
	s_waitcnt lgkmcnt(1)
	global_store_dwordx4 v[10:11], v[2:5], off sc1
	ds_read_b128 v[2:5], v160
	ds_read_b128 v[10:13], v161
	v_ashrrev_i32_e32 v143, 31, v142
	v_lshlrev_b64 v[142:143], 13, v[142:143]
	v_ashrrev_i32_e32 v147, 31, v146
	v_lshlrev_b64 v[146:147], 13, v[146:147]
	v_ashrrev_i32_e32 v149, 31, v148
	v_lshl_add_u64 v[82:83], v[80:81], 0, v[142:143]
	v_lshl_add_u64 v[16:17], v[14:15], 0, v[142:143]
	v_readlane_b32 s0, v250, 13
	v_lshlrev_b64 v[148:149], 13, v[148:149]
	global_store_dwordx4 v[82:83], v[72:75], off sc1
	s_waitcnt lgkmcnt(2)
	global_store_dwordx4 v[16:17], v[6:9], off sc1
	s_add_i32 s35, s35, s0
	v_lshl_add_u64 v[72:73], v[80:81], 0, v[146:147]
	v_lshl_add_u64 v[6:7], v[14:15], 0, v[146:147]
	global_store_dwordx4 v[72:73], v[68:71], off sc1
	s_waitcnt lgkmcnt(1)
	global_store_dwordx4 v[6:7], v[2:5], off sc1
	s_cmpk_gt_i32 s35, 0x3ff
	v_lshl_add_u64 v[68:69], v[80:81], 0, v[148:149]
	v_lshl_add_u64 v[2:3], v[14:15], 0, v[148:149]
	global_store_dwordx4 v[68:69], v[76:79], off sc1
	s_waitcnt lgkmcnt(0)
	global_store_dwordx4 v[2:3], v[10:13], off sc1
	s_barrier
	v_readlane_b32 s1, v250, 14
	s_cbranch_scc1 .LBB0_1622

.LBB0_1696:
	v_readfirstlane_b32 s40, v204
	s_lshr_b32 s40, s40, 6
	s_and_b32 s41, s40, 1
	s_bfe_u32 s42, s40, 0x10001
	s_lshr_b32 s43, s40, 2
	s_lshl_b32 s44, s4, 1
	s_add_i32 s44, s44, s42
	s_lshl_b32 s45, s44, 7
	s_lshl_b32 s46, s41, 6
	s_add_i32 s45, s45, s46
	s_lshl_b32 s46, s43, 7
	s_add_i32 s46, s46, s2
	s_lshl_b32 s47, s44, 1
	s_add_i32 s47, s47, s41
	v_readlane_b32 s36, v250, 9
	v_readlane_b32 s37, v250, 10
	s_mov_b64 s[38:39], s[36:37]
	v_readlane_b32 s50, v250, 11
	v_readlane_b32 s51, v250, 12
	s_add_u32 s34, s50, 0xf900000
	s_addc_u32 s35, s51, 0
	s_add_u32 s50, s50, 0x5800000
	s_addc_u32 s51, s51, 0
	s_lshl_b32 s48, s46, 12
	s_lshl_b32 s49, s45, 2
	s_add_u32 s48, s48, s49
	s_add_u32 s36, s36, s48
	s_addc_u32 s37, s37, 0
	s_add_u32 s38, s38, s48
	s_addc_u32 s39, s39, 0
	s_lshr_b32 s48, s48, 1
	s_add_u32 s50, s50, s48
	s_addc_u32 s51, s51, 0
	s_lshl_b32 s48, s46, 6
	s_lshl_b32 s49, s47, 2
	s_add_u32 s48, s48, s49
	s_add_u32 s34, s34, s48
	s_addc_u32 s35, s35, 0
	v_and_b32_e32 v249, 63, v204
	v_and_b32_e32 v170, 31, v249
	v_lshrrev_b32_e32 v171, 5, v249
	v_and_b32_e32 v208, 15, v249
	v_lshrrev_b32_e32 v209, 4, v249
	s_lshl_b32 s40, s40, 14
	v_and_b32_e32 v238, 15, v170
	v_xor_b32_e32 v238, v238, v171
	v_lshl_add_u32 v239, v170, 8, s40
	v_xor_b32_e32 v228, 0, v238
	v_lshl_add_u32 v228, v228, 4, v239
	v_xor_b32_e32 v229, 2, v238
	v_lshl_add_u32 v229, v229, 4, v239
	v_xor_b32_e32 v230, 4, v238
	v_lshl_add_u32 v230, v230, 4, v239
	v_xor_b32_e32 v231, 6, v238
	v_lshl_add_u32 v231, v231, 4, v239
	v_xor_b32_e32 v232, 8, v238
	v_lshl_add_u32 v232, v232, 4, v239
	v_xor_b32_e32 v233, 10, v238
	v_lshl_add_u32 v233, v233, 4, v239
	v_xor_b32_e32 v234, 12, v238
	v_lshl_add_u32 v234, v234, 4, v239
	v_xor_b32_e32 v235, 14, v238
	v_lshl_add_u32 v235, v235, 4, v239
	v_lshl_add_u32 v239, v209, 8, s40
	v_add_u32_e32 v210, 0, v209
	v_xor_b32_e32 v210, v210, v208
	v_lshl_add_u32 v210, v210, 4, v239
	v_add_u32_e32 v211, 4, v209
	v_xor_b32_e32 v211, v211, v208
	v_lshl_add_u32 v211, v211, 4, v239
	v_add_u32_e32 v215, 8, v209
	v_xor_b32_e32 v215, v215, v208
	v_lshl_add_u32 v215, v215, 4, v239
	v_add_u32_e32 v237, 12, v209
	v_xor_b32_e32 v237, v237, v208
	v_lshl_add_u32 v237, v237, 4, v239
	v_lshlrev_b32_e32 v247, 12, v209
	v_lshl_add_u32 v247, v208, 4, v247
	v_lshrrev_b32_e32 v248, 1, v247
	v_lshlrev_b32_e32 v249, 6, v209
	s_mov_b32 s48, 0x00010001
	s_mov_b32 s49, 0x00010001
	global_load_dwordx4 v[130:133], v247, s[36:37]
	s_add_u32 s36, s36, 0x4000
	s_addc_u32 s37, s37, 0
	global_load_dwordx4 v[134:137], v247, s[36:37]
	s_add_u32 s36, s36, 0x4000
	s_addc_u32 s37, s37, 0
	global_load_dwordx4 v[138:141], v247, s[36:37]
	s_add_u32 s36, s36, 0x4000
	s_addc_u32 s37, s37, 0
	global_load_dwordx4 v[142:145], v247, s[36:37]
	s_add_u32 s36, s36, 0x4000
	s_addc_u32 s37, s37, 0
	global_load_dwordx4 v[146:149], v247, s[36:37]
	s_add_u32 s36, s36, 0x4000
	s_addc_u32 s37, s37, 0
	global_load_dwordx4 v[150:153], v247, s[36:37]
	s_add_u32 s36, s36, 0x4000
	s_addc_u32 s37, s37, 0
	global_load_dwordx4 v[154:157], v247, s[36:37]
	s_add_u32 s36, s36, 0x4000
	s_addc_u32 s37, s37, 0
	global_load_dwordx4 v[158:161], v247, s[36:37]
	s_add_u32 s36, s36, 0x4000
	s_addc_u32 s37, s37, 0
	global_load_dwordx4 v[162:165], v247, s[36:37]
	s_add_u32 s36, s36, 0x4000
	s_addc_u32 s37, s37, 0
	global_load_dwordx4 v[166:169], v247, s[36:37]
	s_add_u32 s36, s36, 0x4000
	s_addc_u32 s37, s37, 0
	global_load_dwordx4 v[192:195], v247, s[36:37]
	s_add_u32 s36, s36, 0x4000
	s_addc_u32 s37, s37, 0
	global_load_dwordx4 v[196:199], v247, s[36:37]
	s_add_u32 s36, s36, 0x4000
	s_addc_u32 s37, s37, 0
	global_load_dwordx4 v[200:203], v247, s[36:37]
	s_add_u32 s36, s36, 0x4000
	s_addc_u32 s37, s37, 0
	global_load_dwordx4 v[216:219], v247, s[36:37]
	s_add_u32 s36, s36, 0x4000
	s_addc_u32 s37, s37, 0
	global_load_dwordx4 v[220:223], v247, s[36:37]
	s_add_u32 s36, s36, 0x4000
	s_addc_u32 s37, s37, 0
	global_load_dwordx4 v[224:227], v247, s[36:37]
	s_add_u32 s36, s36, 0x4000
	s_addc_u32 s37, s37, 0
	ds_write_b128 v228, v[66:69]
	ds_write_b128 v229, v[70:73]
	ds_write_b128 v230, v[74:77]
	ds_write_b128 v231, v[78:81]
	ds_write_b128 v232, v[114:117]
	ds_write_b128 v233, v[118:121]
	ds_write_b128 v234, v[122:125]
	ds_write_b128 v235, v[126:129]
	ds_write_b128 v228, v[82:85] offset:8192
	ds_write_b128 v229, v[86:89] offset:8192
	ds_write_b128 v230, v[90:93] offset:8192
	ds_write_b128 v231, v[94:97] offset:8192
	ds_write_b128 v232, v[98:101] offset:8192
	ds_write_b128 v233, v[102:105] offset:8192
	ds_write_b128 v234, v[106:109] offset:8192
	ds_write_b128 v235, v[110:113] offset:8192
	global_load_dwordx4 v[66:69], v247, s[36:37]
	s_add_u32 s36, s36, 0x4000
	s_addc_u32 s37, s37, 0
	global_load_dwordx4 v[70:73], v247, s[36:37]
	s_add_u32 s36, s36, 0x4000
	s_addc_u32 s37, s37, 0
	global_load_dwordx4 v[74:77], v247, s[36:37]
	s_add_u32 s36, s36, 0x4000
	s_addc_u32 s37, s37, 0
	global_load_dwordx4 v[78:81], v247, s[36:37]
	s_add_u32 s36, s36, 0x4000
	s_addc_u32 s37, s37, 0
	global_load_dwordx4 v[114:117], v247, s[36:37]
	s_add_u32 s36, s36, 0x4000
	s_addc_u32 s37, s37, 0
	global_load_dwordx4 v[118:121], v247, s[36:37]
	s_add_u32 s36, s36, 0x4000
	s_addc_u32 s37, s37, 0
	global_load_dwordx4 v[122:125], v247, s[36:37]
	s_add_u32 s36, s36, 0x4000
	s_addc_u32 s37, s37, 0
	global_load_dwordx4 v[126:129], v247, s[36:37]
	s_add_u32 s36, s36, 0x4000
	s_addc_u32 s37, s37, 0
	global_load_dwordx4 v[82:85], v247, s[36:37]
	s_add_u32 s36, s36, 0x4000
	s_addc_u32 s37, s37, 0
	global_load_dwordx4 v[86:89], v247, s[36:37]
	s_add_u32 s36, s36, 0x4000
	s_addc_u32 s37, s37, 0
	global_load_dwordx4 v[90:93], v247, s[36:37]
	s_add_u32 s36, s36, 0x4000
	s_addc_u32 s37, s37, 0
	global_load_dwordx4 v[94:97], v247, s[36:37]
	s_add_u32 s36, s36, 0x4000
	s_addc_u32 s37, s37, 0
	global_load_dwordx4 v[98:101], v247, s[36:37]
	s_add_u32 s36, s36, 0x4000
	s_addc_u32 s37, s37, 0
	global_load_dwordx4 v[102:105], v247, s[36:37]
	s_add_u32 s36, s36, 0x4000
	s_addc_u32 s37, s37, 0
	global_load_dwordx4 v[106:109], v247, s[36:37]
	s_add_u32 s36, s36, 0x4000
	s_addc_u32 s37, s37, 0
	global_load_dwordx4 v[110:113], v247, s[36:37]
	s_add_u32 s36, s36, 0x4000
	s_addc_u32 s37, s37, 0
	s_waitcnt lgkmcnt(0)
	ds_read_b128 v[228:231], v210 offset:0
	ds_read_b128 v[238:241], v211 offset:1024
	s_waitcnt vmcnt(31) lgkmcnt(1)
	v_pk_add_f32 v[130:131], v[228:229], v[130:131]
	v_pk_add_f32 v[132:133], v[230:231], v[132:133]
	v_pk_mul_f32 v[232:233], v[130:131], v[130:131]
	v_pk_mul_f32 v[234:235], v[132:133], v[132:133]
	ds_read_b128 v[228:231], v215 offset:2048
	v_add_f32_e32 v236, v232, v233
	v_add_f32_e32 v236, v234, v236
	v_add_f32_e32 v236, v235, v236
	global_store_dwordx4 v247, v[130:133], s[38:39] sc1
	v_cvt_pk_bf16_f32 v232, v130, v131
	v_cvt_pk_bf16_f32 v233, v132, v133
	v_add_f32_dpp v236, v236, v236 quad_perm:[1,0,3,2] row_mask:0xf bank_mask:0xf
	global_store_dwordx2 v248, v[232:233], s[50:51] sc1
	s_add_u32 s38, s38, 0x4000
	s_addc_u32 s39, s39, 0
	v_add_f32_dpp v236, v236, v236 quad_perm:[2,3,0,1] row_mask:0xf bank_mask:0xf
	s_add_u32 s50, s50, 0x2000
	s_addc_u32 s51, s51, 0
	v_add_f32_dpp v236, v236, v236 row_half_mirror row_mask:0xf bank_mask:0xf
	s_nop 1
	v_add_f32_dpp v236, v236, v236 row_mirror row_mask:0xf bank_mask:0xf
	s_mov_b64 exec, s[48:49]
	global_store_dword v249, v236, s[34:35] offset:0
	s_mov_b64 exec, -1
	s_waitcnt vmcnt(33) lgkmcnt(1)
	v_pk_add_f32 v[134:135], v[238:239], v[134:135]
	v_pk_add_f32 v[136:137], v[240:241], v[136:137]
	v_pk_mul_f32 v[242:243], v[134:135], v[134:135]
	v_pk_mul_f32 v[244:245], v[136:137], v[136:137]
	ds_read_b128 v[238:241], v237 offset:3072
	v_add_f32_e32 v246, v242, v243
	v_add_f32_e32 v246, v244, v246
	v_add_f32_e32 v246, v245, v246
	global_store_dwordx4 v247, v[134:137], s[38:39] sc1
	v_cvt_pk_bf16_f32 v242, v134, v135
	v_cvt_pk_bf16_f32 v243, v136, v137
	v_add_f32_dpp v246, v246, v246 quad_perm:[1,0,3,2] row_mask:0xf bank_mask:0xf
	global_store_dwordx2 v248, v[242:243], s[50:51] sc1
	s_add_u32 s38, s38, 0x4000
	s_addc_u32 s39, s39, 0
	v_add_f32_dpp v246, v246, v246 quad_perm:[2,3,0,1] row_mask:0xf bank_mask:0xf
	s_add_u32 s50, s50, 0x2000
	s_addc_u32 s51, s51, 0
	v_add_f32_dpp v246, v246, v246 row_half_mirror row_mask:0xf bank_mask:0xf
	s_nop 1
	v_add_f32_dpp v246, v246, v246 row_mirror row_mask:0xf bank_mask:0xf
	s_mov_b64 exec, s[48:49]
	global_store_dword v249, v246, s[34:35] offset:256
	s_mov_b64 exec, -1
	s_waitcnt vmcnt(35) lgkmcnt(1)
	v_pk_add_f32 v[138:139], v[228:229], v[138:139]
	v_pk_add_f32 v[140:141], v[230:231], v[140:141]
	v_pk_mul_f32 v[232:233], v[138:139], v[138:139]
	v_pk_mul_f32 v[234:235], v[140:141], v[140:141]
	ds_read_b128 v[228:231], v210 offset:4096
	v_add_f32_e32 v236, v232, v233
	v_add_f32_e32 v236, v234, v236
	v_add_f32_e32 v236, v235, v236
	global_store_dwordx4 v247, v[138:141], s[38:39] sc1
	v_cvt_pk_bf16_f32 v232, v138, v139
	v_cvt_pk_bf16_f32 v233, v140, v141
	v_add_f32_dpp v236, v236, v236 quad_perm:[1,0,3,2] row_mask:0xf bank_mask:0xf
	global_store_dwordx2 v248, v[232:233], s[50:51] sc1
	s_add_u32 s38, s38, 0x4000
	s_addc_u32 s39, s39, 0
	v_add_f32_dpp v236, v236, v236 quad_perm:[2,3,0,1] row_mask:0xf bank_mask:0xf
	s_add_u32 s50, s50, 0x2000
	s_addc_u32 s51, s51, 0
	v_add_f32_dpp v236, v236, v236 row_half_mirror row_mask:0xf bank_mask:0xf
	s_nop 1
	v_add_f32_dpp v236, v236, v236 row_mirror row_mask:0xf bank_mask:0xf
	s_mov_b64 exec, s[48:49]
	global_store_dword v249, v236, s[34:35] offset:512
	s_mov_b64 exec, -1
	s_waitcnt vmcnt(37) lgkmcnt(1)
	v_pk_add_f32 v[142:143], v[238:239], v[142:143]
	v_pk_add_f32 v[144:145], v[240:241], v[144:145]
	v_pk_mul_f32 v[242:243], v[142:143], v[142:143]
	v_pk_mul_f32 v[244:245], v[144:145], v[144:145]
	ds_read_b128 v[238:241], v211 offset:5120
	v_add_f32_e32 v246, v242, v243
	v_add_f32_e32 v246, v244, v246
	v_add_f32_e32 v246, v245, v246
	global_store_dwordx4 v247, v[142:145], s[38:39] sc1
	v_cvt_pk_bf16_f32 v242, v142, v143
	v_cvt_pk_bf16_f32 v243, v144, v145
	v_add_f32_dpp v246, v246, v246 quad_perm:[1,0,3,2] row_mask:0xf bank_mask:0xf
	global_store_dwordx2 v248, v[242:243], s[50:51] sc1
	s_add_u32 s38, s38, 0x4000
	s_addc_u32 s39, s39, 0
	v_add_f32_dpp v246, v246, v246 quad_perm:[2,3,0,1] row_mask:0xf bank_mask:0xf
	s_add_u32 s50, s50, 0x2000
	s_addc_u32 s51, s51, 0
	v_add_f32_dpp v246, v246, v246 row_half_mirror row_mask:0xf bank_mask:0xf
	s_nop 1
	v_add_f32_dpp v246, v246, v246 row_mirror row_mask:0xf bank_mask:0xf
	s_mov_b64 exec, s[48:49]
	global_store_dword v249, v246, s[34:35] offset:768
	s_mov_b64 exec, -1
	s_waitcnt vmcnt(39) lgkmcnt(1)
	v_pk_add_f32 v[146:147], v[228:229], v[146:147]
	v_pk_add_f32 v[148:149], v[230:231], v[148:149]
	v_pk_mul_f32 v[232:233], v[146:147], v[146:147]
	v_pk_mul_f32 v[234:235], v[148:149], v[148:149]
	ds_read_b128 v[228:231], v215 offset:6144
	v_add_f32_e32 v236, v232, v233
	v_add_f32_e32 v236, v234, v236
	v_add_f32_e32 v236, v235, v236
	global_store_dwordx4 v247, v[146:149], s[38:39] sc1
	v_cvt_pk_bf16_f32 v232, v146, v147
	v_cvt_pk_bf16_f32 v233, v148, v149
	v_add_f32_dpp v236, v236, v236 quad_perm:[1,0,3,2] row_mask:0xf bank_mask:0xf
	global_store_dwordx2 v248, v[232:233], s[50:51] sc1
	s_add_u32 s38, s38, 0x4000
	s_addc_u32 s39, s39, 0
	v_add_f32_dpp v236, v236, v236 quad_perm:[2,3,0,1] row_mask:0xf bank_mask:0xf
	s_add_u32 s50, s50, 0x2000
	s_addc_u32 s51, s51, 0
	v_add_f32_dpp v236, v236, v236 row_half_mirror row_mask:0xf bank_mask:0xf
	s_nop 1
	v_add_f32_dpp v236, v236, v236 row_mirror row_mask:0xf bank_mask:0xf
	s_mov_b64 exec, s[48:49]
	global_store_dword v249, v236, s[34:35] offset:1024
	s_mov_b64 exec, -1
	s_waitcnt vmcnt(41) lgkmcnt(1)
	v_pk_add_f32 v[150:151], v[238:239], v[150:151]
	v_pk_add_f32 v[152:153], v[240:241], v[152:153]
	v_pk_mul_f32 v[242:243], v[150:151], v[150:151]
	v_pk_mul_f32 v[244:245], v[152:153], v[152:153]
	ds_read_b128 v[238:241], v237 offset:7168
	v_add_f32_e32 v246, v242, v243
	v_add_f32_e32 v246, v244, v246
	v_add_f32_e32 v246, v245, v246
	global_store_dwordx4 v247, v[150:153], s[38:39] sc1
	v_cvt_pk_bf16_f32 v242, v150, v151
	v_cvt_pk_bf16_f32 v243, v152, v153
	v_add_f32_dpp v246, v246, v246 quad_perm:[1,0,3,2] row_mask:0xf bank_mask:0xf
	global_store_dwordx2 v248, v[242:243], s[50:51] sc1
	s_add_u32 s38, s38, 0x4000
	s_addc_u32 s39, s39, 0
	v_add_f32_dpp v246, v246, v246 quad_perm:[2,3,0,1] row_mask:0xf bank_mask:0xf
	s_add_u32 s50, s50, 0x2000
	s_addc_u32 s51, s51, 0
	v_add_f32_dpp v246, v246, v246 row_half_mirror row_mask:0xf bank_mask:0xf
	s_nop 1
	v_add_f32_dpp v246, v246, v246 row_mirror row_mask:0xf bank_mask:0xf
	s_mov_b64 exec, s[48:49]
	global_store_dword v249, v246, s[34:35] offset:1280
	s_mov_b64 exec, -1
	s_waitcnt vmcnt(43) lgkmcnt(1)
	v_pk_add_f32 v[154:155], v[228:229], v[154:155]
	v_pk_add_f32 v[156:157], v[230:231], v[156:157]
	v_pk_mul_f32 v[232:233], v[154:155], v[154:155]
	v_pk_mul_f32 v[234:235], v[156:157], v[156:157]
	ds_read_b128 v[228:231], v210 offset:8192
	v_add_f32_e32 v236, v232, v233
	v_add_f32_e32 v236, v234, v236
	v_add_f32_e32 v236, v235, v236
	global_store_dwordx4 v247, v[154:157], s[38:39] sc1
	v_cvt_pk_bf16_f32 v232, v154, v155
	v_cvt_pk_bf16_f32 v233, v156, v157
	v_add_f32_dpp v236, v236, v236 quad_perm:[1,0,3,2] row_mask:0xf bank_mask:0xf
	global_store_dwordx2 v248, v[232:233], s[50:51] sc1
	s_add_u32 s38, s38, 0x4000
	s_addc_u32 s39, s39, 0
	v_add_f32_dpp v236, v236, v236 quad_perm:[2,3,0,1] row_mask:0xf bank_mask:0xf
	s_add_u32 s50, s50, 0x2000
	s_addc_u32 s51, s51, 0
	v_add_f32_dpp v236, v236, v236 row_half_mirror row_mask:0xf bank_mask:0xf
	s_nop 1
	v_add_f32_dpp v236, v236, v236 row_mirror row_mask:0xf bank_mask:0xf
	s_mov_b64 exec, s[48:49]
	global_store_dword v249, v236, s[34:35] offset:1536
	s_mov_b64 exec, -1
	s_waitcnt vmcnt(45) lgkmcnt(1)
	v_pk_add_f32 v[158:159], v[238:239], v[158:159]
	v_pk_add_f32 v[160:161], v[240:241], v[160:161]
	v_pk_mul_f32 v[242:243], v[158:159], v[158:159]
	v_pk_mul_f32 v[244:245], v[160:161], v[160:161]
	ds_read_b128 v[238:241], v211 offset:9216
	v_add_f32_e32 v246, v242, v243
	v_add_f32_e32 v246, v244, v246
	v_add_f32_e32 v246, v245, v246
	global_store_dwordx4 v247, v[158:161], s[38:39] sc1
	v_cvt_pk_bf16_f32 v242, v158, v159
	v_cvt_pk_bf16_f32 v243, v160, v161
	v_add_f32_dpp v246, v246, v246 quad_perm:[1,0,3,2] row_mask:0xf bank_mask:0xf
	global_store_dwordx2 v248, v[242:243], s[50:51] sc1
	s_add_u32 s38, s38, 0x4000
	s_addc_u32 s39, s39, 0
	v_add_f32_dpp v246, v246, v246 quad_perm:[2,3,0,1] row_mask:0xf bank_mask:0xf
	s_add_u32 s50, s50, 0x2000
	s_addc_u32 s51, s51, 0
	v_add_f32_dpp v246, v246, v246 row_half_mirror row_mask:0xf bank_mask:0xf
	s_nop 1
	v_add_f32_dpp v246, v246, v246 row_mirror row_mask:0xf bank_mask:0xf
	s_mov_b64 exec, s[48:49]
	global_store_dword v249, v246, s[34:35] offset:1792
	s_mov_b64 exec, -1
	s_waitcnt vmcnt(47) lgkmcnt(1)
	v_pk_add_f32 v[162:163], v[228:229], v[162:163]
	v_pk_add_f32 v[164:165], v[230:231], v[164:165]
	v_pk_mul_f32 v[232:233], v[162:163], v[162:163]
	v_pk_mul_f32 v[234:235], v[164:165], v[164:165]
	ds_read_b128 v[228:231], v215 offset:10240
	v_add_f32_e32 v236, v232, v233
	v_add_f32_e32 v236, v234, v236
	v_add_f32_e32 v236, v235, v236
	global_store_dwordx4 v247, v[162:165], s[38:39] sc1
	v_cvt_pk_bf16_f32 v232, v162, v163
	v_cvt_pk_bf16_f32 v233, v164, v165
	v_add_f32_dpp v236, v236, v236 quad_perm:[1,0,3,2] row_mask:0xf bank_mask:0xf
	global_store_dwordx2 v248, v[232:233], s[50:51] sc1
	s_add_u32 s38, s38, 0x4000
	s_addc_u32 s39, s39, 0
	v_add_f32_dpp v236, v236, v236 quad_perm:[2,3,0,1] row_mask:0xf bank_mask:0xf
	s_add_u32 s50, s50, 0x2000
	s_addc_u32 s51, s51, 0
	v_add_f32_dpp v236, v236, v236 row_half_mirror row_mask:0xf bank_mask:0xf
	s_nop 1
	v_add_f32_dpp v236, v236, v236 row_mirror row_mask:0xf bank_mask:0xf
	s_mov_b64 exec, s[48:49]
	global_store_dword v249, v236, s[34:35] offset:2048
	s_mov_b64 exec, -1
	s_waitcnt vmcnt(49) lgkmcnt(1)
	v_pk_add_f32 v[166:167], v[238:239], v[166:167]
	v_pk_add_f32 v[168:169], v[240:241], v[168:169]
	v_pk_mul_f32 v[242:243], v[166:167], v[166:167]
	v_pk_mul_f32 v[244:245], v[168:169], v[168:169]
	ds_read_b128 v[238:241], v237 offset:11264
	v_add_f32_e32 v246, v242, v243
	v_add_f32_e32 v246, v244, v246
	v_add_f32_e32 v246, v245, v246
	global_store_dwordx4 v247, v[166:169], s[38:39] sc1
	v_cvt_pk_bf16_f32 v242, v166, v167
	v_cvt_pk_bf16_f32 v243, v168, v169
	v_add_f32_dpp v246, v246, v246 quad_perm:[1,0,3,2] row_mask:0xf bank_mask:0xf
	global_store_dwordx2 v248, v[242:243], s[50:51] sc1
	s_add_u32 s38, s38, 0x4000
	s_addc_u32 s39, s39, 0
	v_add_f32_dpp v246, v246, v246 quad_perm:[2,3,0,1] row_mask:0xf bank_mask:0xf
	s_add_u32 s50, s50, 0x2000
	s_addc_u32 s51, s51, 0
	v_add_f32_dpp v246, v246, v246 row_half_mirror row_mask:0xf bank_mask:0xf
	s_nop 1
	v_add_f32_dpp v246, v246, v246 row_mirror row_mask:0xf bank_mask:0xf
	s_mov_b64 exec, s[48:49]
	global_store_dword v249, v246, s[34:35] offset:2304
	s_mov_b64 exec, -1
	s_waitcnt vmcnt(51) lgkmcnt(1)
	v_pk_add_f32 v[192:193], v[228:229], v[192:193]
	v_pk_add_f32 v[194:195], v[230:231], v[194:195]
	v_pk_mul_f32 v[232:233], v[192:193], v[192:193]
	v_pk_mul_f32 v[234:235], v[194:195], v[194:195]
	ds_read_b128 v[228:231], v210 offset:12288
	v_add_f32_e32 v236, v232, v233
	v_add_f32_e32 v236, v234, v236
	v_add_f32_e32 v236, v235, v236
	global_store_dwordx4 v247, v[192:195], s[38:39] sc1
	v_cvt_pk_bf16_f32 v232, v192, v193
	v_cvt_pk_bf16_f32 v233, v194, v195
	v_add_f32_dpp v236, v236, v236 quad_perm:[1,0,3,2] row_mask:0xf bank_mask:0xf
	global_store_dwordx2 v248, v[232:233], s[50:51] sc1
	s_add_u32 s38, s38, 0x4000
	s_addc_u32 s39, s39, 0
	v_add_f32_dpp v236, v236, v236 quad_perm:[2,3,0,1] row_mask:0xf bank_mask:0xf
	s_add_u32 s50, s50, 0x2000
	s_addc_u32 s51, s51, 0
	v_add_f32_dpp v236, v236, v236 row_half_mirror row_mask:0xf bank_mask:0xf
	s_nop 1
	v_add_f32_dpp v236, v236, v236 row_mirror row_mask:0xf bank_mask:0xf
	s_mov_b64 exec, s[48:49]
	global_store_dword v249, v236, s[34:35] offset:2560
	s_mov_b64 exec, -1
	s_waitcnt vmcnt(53) lgkmcnt(1)
	v_pk_add_f32 v[196:197], v[238:239], v[196:197]
	v_pk_add_f32 v[198:199], v[240:241], v[198:199]
	v_pk_mul_f32 v[242:243], v[196:197], v[196:197]
	v_pk_mul_f32 v[244:245], v[198:199], v[198:199]
	ds_read_b128 v[238:241], v211 offset:13312
	v_add_f32_e32 v246, v242, v243
	v_add_f32_e32 v246, v244, v246
	v_add_f32_e32 v246, v245, v246
	global_store_dwordx4 v247, v[196:199], s[38:39] sc1
	v_cvt_pk_bf16_f32 v242, v196, v197
	v_cvt_pk_bf16_f32 v243, v198, v199
	v_add_f32_dpp v246, v246, v246 quad_perm:[1,0,3,2] row_mask:0xf bank_mask:0xf
	global_store_dwordx2 v248, v[242:243], s[50:51] sc1
	s_add_u32 s38, s38, 0x4000
	s_addc_u32 s39, s39, 0
	v_add_f32_dpp v246, v246, v246 quad_perm:[2,3,0,1] row_mask:0xf bank_mask:0xf
	s_add_u32 s50, s50, 0x2000
	s_addc_u32 s51, s51, 0
	v_add_f32_dpp v246, v246, v246 row_half_mirror row_mask:0xf bank_mask:0xf
	s_nop 1
	v_add_f32_dpp v246, v246, v246 row_mirror row_mask:0xf bank_mask:0xf
	s_mov_b64 exec, s[48:49]
	global_store_dword v249, v246, s[34:35] offset:2816
	s_mov_b64 exec, -1
	s_waitcnt vmcnt(55) lgkmcnt(1)
	v_pk_add_f32 v[200:201], v[228:229], v[200:201]
	v_pk_add_f32 v[202:203], v[230:231], v[202:203]
	v_pk_mul_f32 v[232:233], v[200:201], v[200:201]
	v_pk_mul_f32 v[234:235], v[202:203], v[202:203]
	ds_read_b128 v[228:231], v215 offset:14336
	v_add_f32_e32 v236, v232, v233
	v_add_f32_e32 v236, v234, v236
	v_add_f32_e32 v236, v235, v236
	global_store_dwordx4 v247, v[200:203], s[38:39] sc1
	v_cvt_pk_bf16_f32 v232, v200, v201
	v_cvt_pk_bf16_f32 v233, v202, v203
	v_add_f32_dpp v236, v236, v236 quad_perm:[1,0,3,2] row_mask:0xf bank_mask:0xf
	global_store_dwordx2 v248, v[232:233], s[50:51] sc1
	s_add_u32 s38, s38, 0x4000
	s_addc_u32 s39, s39, 0
	v_add_f32_dpp v236, v236, v236 quad_perm:[2,3,0,1] row_mask:0xf bank_mask:0xf
	s_add_u32 s50, s50, 0x2000
	s_addc_u32 s51, s51, 0
	v_add_f32_dpp v236, v236, v236 row_half_mirror row_mask:0xf bank_mask:0xf
	s_nop 1
	v_add_f32_dpp v236, v236, v236 row_mirror row_mask:0xf bank_mask:0xf
	s_mov_b64 exec, s[48:49]
	global_store_dword v249, v236, s[34:35] offset:3072
	s_mov_b64 exec, -1
	s_waitcnt vmcnt(57) lgkmcnt(1)
	v_pk_add_f32 v[216:217], v[238:239], v[216:217]
	v_pk_add_f32 v[218:219], v[240:241], v[218:219]
	v_pk_mul_f32 v[242:243], v[216:217], v[216:217]
	v_pk_mul_f32 v[244:245], v[218:219], v[218:219]
	ds_read_b128 v[238:241], v237 offset:15360
	v_add_f32_e32 v246, v242, v243
	v_add_f32_e32 v246, v244, v246
	v_add_f32_e32 v246, v245, v246
	global_store_dwordx4 v247, v[216:219], s[38:39] sc1
	v_cvt_pk_bf16_f32 v242, v216, v217
	v_cvt_pk_bf16_f32 v243, v218, v219
	v_add_f32_dpp v246, v246, v246 quad_perm:[1,0,3,2] row_mask:0xf bank_mask:0xf
	global_store_dwordx2 v248, v[242:243], s[50:51] sc1
	s_add_u32 s38, s38, 0x4000
	s_addc_u32 s39, s39, 0
	v_add_f32_dpp v246, v246, v246 quad_perm:[2,3,0,1] row_mask:0xf bank_mask:0xf
	s_add_u32 s50, s50, 0x2000
	s_addc_u32 s51, s51, 0
	v_add_f32_dpp v246, v246, v246 row_half_mirror row_mask:0xf bank_mask:0xf
	s_nop 1
	v_add_f32_dpp v246, v246, v246 row_mirror row_mask:0xf bank_mask:0xf
	s_mov_b64 exec, s[48:49]
	global_store_dword v249, v246, s[34:35] offset:3328
	s_mov_b64 exec, -1
	s_waitcnt vmcnt(59) lgkmcnt(1)
	v_pk_add_f32 v[220:221], v[228:229], v[220:221]
	v_pk_add_f32 v[222:223], v[230:231], v[222:223]
	v_pk_mul_f32 v[232:233], v[220:221], v[220:221]
	v_pk_mul_f32 v[234:235], v[222:223], v[222:223]
	v_add_f32_e32 v236, v232, v233
	v_add_f32_e32 v236, v234, v236
	v_add_f32_e32 v236, v235, v236
	global_store_dwordx4 v247, v[220:223], s[38:39] sc1
	v_cvt_pk_bf16_f32 v232, v220, v221
	v_cvt_pk_bf16_f32 v233, v222, v223
	v_add_f32_dpp v236, v236, v236 quad_perm:[1,0,3,2] row_mask:0xf bank_mask:0xf
	global_store_dwordx2 v248, v[232:233], s[50:51] sc1
	s_add_u32 s38, s38, 0x4000
	s_addc_u32 s39, s39, 0
	v_add_f32_dpp v236, v236, v236 quad_perm:[2,3,0,1] row_mask:0xf bank_mask:0xf
	s_add_u32 s50, s50, 0x2000
	s_addc_u32 s51, s51, 0
	v_add_f32_dpp v236, v236, v236 row_half_mirror row_mask:0xf bank_mask:0xf
	s_nop 1
	v_add_f32_dpp v236, v236, v236 row_mirror row_mask:0xf bank_mask:0xf
	s_mov_b64 exec, s[48:49]
	global_store_dword v249, v236, s[34:35] offset:3584
	s_mov_b64 exec, -1
	s_waitcnt vmcnt(61) lgkmcnt(0)
	v_pk_add_f32 v[224:225], v[238:239], v[224:225]
	v_pk_add_f32 v[226:227], v[240:241], v[226:227]
	v_pk_mul_f32 v[242:243], v[224:225], v[224:225]
	v_pk_mul_f32 v[244:245], v[226:227], v[226:227]
	v_add_f32_e32 v246, v242, v243
	v_add_f32_e32 v246, v244, v246
	v_add_f32_e32 v246, v245, v246
	global_store_dwordx4 v247, v[224:227], s[38:39] sc1
	v_cvt_pk_bf16_f32 v242, v224, v225
	v_cvt_pk_bf16_f32 v243, v226, v227
	v_add_f32_dpp v246, v246, v246 quad_perm:[1,0,3,2] row_mask:0xf bank_mask:0xf
	global_store_dwordx2 v248, v[242:243], s[50:51] sc1
	s_add_u32 s38, s38, 0x4000
	s_addc_u32 s39, s39, 0
	v_add_f32_dpp v246, v246, v246 quad_perm:[2,3,0,1] row_mask:0xf bank_mask:0xf
	s_add_u32 s50, s50, 0x2000
	s_addc_u32 s51, s51, 0
	v_add_f32_dpp v246, v246, v246 row_half_mirror row_mask:0xf bank_mask:0xf
	s_nop 1
	v_add_f32_dpp v246, v246, v246 row_mirror row_mask:0xf bank_mask:0xf
	s_mov_b64 exec, s[48:49]
	global_store_dword v249, v246, s[34:35] offset:3840
	s_mov_b64 exec, -1
	s_add_u32 s34, s34, 0x1000
	s_addc_u32 s35, s35, 0
	v_and_b32_e32 v238, 15, v170
	v_xor_b32_e32 v238, v238, v171
	v_lshl_add_u32 v239, v170, 8, s40
	v_xor_b32_e32 v228, 0, v238
	v_lshl_add_u32 v228, v228, 4, v239
	v_xor_b32_e32 v229, 2, v238
	v_lshl_add_u32 v229, v229, 4, v239
	v_xor_b32_e32 v230, 4, v238
	v_lshl_add_u32 v230, v230, 4, v239
	v_xor_b32_e32 v231, 6, v238
	v_lshl_add_u32 v231, v231, 4, v239
	v_xor_b32_e32 v232, 8, v238
	v_lshl_add_u32 v232, v232, 4, v239
	v_xor_b32_e32 v233, 10, v238
	v_lshl_add_u32 v233, v233, 4, v239
	v_xor_b32_e32 v234, 12, v238
	v_lshl_add_u32 v234, v234, 4, v239
	v_xor_b32_e32 v235, 14, v238
	v_lshl_add_u32 v235, v235, 4, v239
	ds_write_b128 v228, v[18:21]
	ds_write_b128 v229, v[22:25]
	ds_write_b128 v230, v[26:29]
	ds_write_b128 v231, v[30:33]
	ds_write_b128 v232, v[50:53]
	ds_write_b128 v233, v[54:57]
	ds_write_b128 v234, v[58:61]
	ds_write_b128 v235, v[62:65]
	ds_write_b128 v228, v[2:5] offset:8192
	ds_write_b128 v229, v[6:9] offset:8192
	ds_write_b128 v230, v[10:13] offset:8192
	ds_write_b128 v231, v[14:17] offset:8192
	ds_write_b128 v232, v[34:37] offset:8192
	ds_write_b128 v233, v[38:41] offset:8192
	ds_write_b128 v234, v[42:45] offset:8192
	ds_write_b128 v235, v[46:49] offset:8192
	s_waitcnt lgkmcnt(0)
	ds_read_b128 v[228:231], v210 offset:0
	ds_read_b128 v[238:241], v211 offset:1024
	s_waitcnt vmcnt(63) lgkmcnt(1)
	v_pk_add_f32 v[66:67], v[228:229], v[66:67]
	v_pk_add_f32 v[68:69], v[230:231], v[68:69]
	v_pk_mul_f32 v[232:233], v[66:67], v[66:67]
	v_pk_mul_f32 v[234:235], v[68:69], v[68:69]
	ds_read_b128 v[228:231], v215 offset:2048
	v_add_f32_e32 v236, v232, v233
	v_add_f32_e32 v236, v234, v236
	v_add_f32_e32 v236, v235, v236
	global_store_dwordx4 v247, v[66:69], s[38:39] sc1
	v_cvt_pk_bf16_f32 v232, v66, v67
	v_cvt_pk_bf16_f32 v233, v68, v69
	v_add_f32_dpp v236, v236, v236 quad_perm:[1,0,3,2] row_mask:0xf bank_mask:0xf
	global_store_dwordx2 v248, v[232:233], s[50:51] sc1
	s_add_u32 s38, s38, 0x4000
	s_addc_u32 s39, s39, 0
	v_add_f32_dpp v236, v236, v236 quad_perm:[2,3,0,1] row_mask:0xf bank_mask:0xf
	s_add_u32 s50, s50, 0x2000
	s_addc_u32 s51, s51, 0
	v_add_f32_dpp v236, v236, v236 row_half_mirror row_mask:0xf bank_mask:0xf
	s_nop 1
	v_add_f32_dpp v236, v236, v236 row_mirror row_mask:0xf bank_mask:0xf
	s_mov_b64 exec, s[48:49]
	global_store_dword v249, v236, s[34:35] offset:0
	s_mov_b64 exec, -1
	s_waitcnt vmcnt(63) lgkmcnt(1)
	v_pk_add_f32 v[70:71], v[238:239], v[70:71]
	v_pk_add_f32 v[72:73], v[240:241], v[72:73]
	v_pk_mul_f32 v[242:243], v[70:71], v[70:71]
	v_pk_mul_f32 v[244:245], v[72:73], v[72:73]
	ds_read_b128 v[238:241], v237 offset:3072
	v_add_f32_e32 v246, v242, v243
	v_add_f32_e32 v246, v244, v246
	v_add_f32_e32 v246, v245, v246
	global_store_dwordx4 v247, v[70:73], s[38:39] sc1
	v_cvt_pk_bf16_f32 v242, v70, v71
	v_cvt_pk_bf16_f32 v243, v72, v73
	v_add_f32_dpp v246, v246, v246 quad_perm:[1,0,3,2] row_mask:0xf bank_mask:0xf
	global_store_dwordx2 v248, v[242:243], s[50:51] sc1
	s_add_u32 s38, s38, 0x4000
	s_addc_u32 s39, s39, 0
	v_add_f32_dpp v246, v246, v246 quad_perm:[2,3,0,1] row_mask:0xf bank_mask:0xf
	s_add_u32 s50, s50, 0x2000
	s_addc_u32 s51, s51, 0
	v_add_f32_dpp v246, v246, v246 row_half_mirror row_mask:0xf bank_mask:0xf
	s_nop 1
	v_add_f32_dpp v246, v246, v246 row_mirror row_mask:0xf bank_mask:0xf
	s_mov_b64 exec, s[48:49]
	global_store_dword v249, v246, s[34:35] offset:256
	s_mov_b64 exec, -1
	s_waitcnt vmcnt(63) lgkmcnt(1)
	v_pk_add_f32 v[74:75], v[228:229], v[74:75]
	v_pk_add_f32 v[76:77], v[230:231], v[76:77]
	v_pk_mul_f32 v[232:233], v[74:75], v[74:75]
	v_pk_mul_f32 v[234:235], v[76:77], v[76:77]
	ds_read_b128 v[228:231], v210 offset:4096
	v_add_f32_e32 v236, v232, v233
	v_add_f32_e32 v236, v234, v236
	v_add_f32_e32 v236, v235, v236
	global_store_dwordx4 v247, v[74:77], s[38:39] sc1
	v_cvt_pk_bf16_f32 v232, v74, v75
	v_cvt_pk_bf16_f32 v233, v76, v77
	v_add_f32_dpp v236, v236, v236 quad_perm:[1,0,3,2] row_mask:0xf bank_mask:0xf
	global_store_dwordx2 v248, v[232:233], s[50:51] sc1
	s_add_u32 s38, s38, 0x4000
	s_addc_u32 s39, s39, 0
	v_add_f32_dpp v236, v236, v236 quad_perm:[2,3,0,1] row_mask:0xf bank_mask:0xf
	s_add_u32 s50, s50, 0x2000
	s_addc_u32 s51, s51, 0
	v_add_f32_dpp v236, v236, v236 row_half_mirror row_mask:0xf bank_mask:0xf
	s_nop 1
	v_add_f32_dpp v236, v236, v236 row_mirror row_mask:0xf bank_mask:0xf
	s_mov_b64 exec, s[48:49]
	global_store_dword v249, v236, s[34:35] offset:512
	s_mov_b64 exec, -1
	s_waitcnt vmcnt(63) lgkmcnt(1)
	v_pk_add_f32 v[78:79], v[238:239], v[78:79]
	v_pk_add_f32 v[80:81], v[240:241], v[80:81]
	v_pk_mul_f32 v[242:243], v[78:79], v[78:79]
	v_pk_mul_f32 v[244:245], v[80:81], v[80:81]
	ds_read_b128 v[238:241], v211 offset:5120
	v_add_f32_e32 v246, v242, v243
	v_add_f32_e32 v246, v244, v246
	v_add_f32_e32 v246, v245, v246
	global_store_dwordx4 v247, v[78:81], s[38:39] sc1
	v_cvt_pk_bf16_f32 v242, v78, v79
	v_cvt_pk_bf16_f32 v243, v80, v81
	v_add_f32_dpp v246, v246, v246 quad_perm:[1,0,3,2] row_mask:0xf bank_mask:0xf
	global_store_dwordx2 v248, v[242:243], s[50:51] sc1
	s_add_u32 s38, s38, 0x4000
	s_addc_u32 s39, s39, 0
	v_add_f32_dpp v246, v246, v246 quad_perm:[2,3,0,1] row_mask:0xf bank_mask:0xf
	s_add_u32 s50, s50, 0x2000
	s_addc_u32 s51, s51, 0
	v_add_f32_dpp v246, v246, v246 row_half_mirror row_mask:0xf bank_mask:0xf
	s_nop 1
	v_add_f32_dpp v246, v246, v246 row_mirror row_mask:0xf bank_mask:0xf
	s_mov_b64 exec, s[48:49]
	global_store_dword v249, v246, s[34:35] offset:768
	s_mov_b64 exec, -1
	s_waitcnt vmcnt(63) lgkmcnt(1)
	v_pk_add_f32 v[114:115], v[228:229], v[114:115]
	v_pk_add_f32 v[116:117], v[230:231], v[116:117]
	v_pk_mul_f32 v[232:233], v[114:115], v[114:115]
	v_pk_mul_f32 v[234:235], v[116:117], v[116:117]
	ds_read_b128 v[228:231], v215 offset:6144
	v_add_f32_e32 v236, v232, v233
	v_add_f32_e32 v236, v234, v236
	v_add_f32_e32 v236, v235, v236
	global_store_dwordx4 v247, v[114:117], s[38:39] sc1
	v_cvt_pk_bf16_f32 v232, v114, v115
	v_cvt_pk_bf16_f32 v233, v116, v117
	v_add_f32_dpp v236, v236, v236 quad_perm:[1,0,3,2] row_mask:0xf bank_mask:0xf
	global_store_dwordx2 v248, v[232:233], s[50:51] sc1
	s_add_u32 s38, s38, 0x4000
	s_addc_u32 s39, s39, 0
	v_add_f32_dpp v236, v236, v236 quad_perm:[2,3,0,1] row_mask:0xf bank_mask:0xf
	s_add_u32 s50, s50, 0x2000
	s_addc_u32 s51, s51, 0
	v_add_f32_dpp v236, v236, v236 row_half_mirror row_mask:0xf bank_mask:0xf
	s_nop 1
	v_add_f32_dpp v236, v236, v236 row_mirror row_mask:0xf bank_mask:0xf
	s_mov_b64 exec, s[48:49]
	global_store_dword v249, v236, s[34:35] offset:1024
	s_mov_b64 exec, -1
	s_waitcnt vmcnt(63) lgkmcnt(1)
	v_pk_add_f32 v[118:119], v[238:239], v[118:119]
	v_pk_add_f32 v[120:121], v[240:241], v[120:121]
	v_pk_mul_f32 v[242:243], v[118:119], v[118:119]
	v_pk_mul_f32 v[244:245], v[120:121], v[120:121]
	ds_read_b128 v[238:241], v237 offset:7168
	v_add_f32_e32 v246, v242, v243
	v_add_f32_e32 v246, v244, v246
	v_add_f32_e32 v246, v245, v246
	global_store_dwordx4 v247, v[118:121], s[38:39] sc1
	v_cvt_pk_bf16_f32 v242, v118, v119
	v_cvt_pk_bf16_f32 v243, v120, v121
	v_add_f32_dpp v246, v246, v246 quad_perm:[1,0,3,2] row_mask:0xf bank_mask:0xf
	global_store_dwordx2 v248, v[242:243], s[50:51] sc1
	s_add_u32 s38, s38, 0x4000
	s_addc_u32 s39, s39, 0
	v_add_f32_dpp v246, v246, v246 quad_perm:[2,3,0,1] row_mask:0xf bank_mask:0xf
	s_add_u32 s50, s50, 0x2000
	s_addc_u32 s51, s51, 0
	v_add_f32_dpp v246, v246, v246 row_half_mirror row_mask:0xf bank_mask:0xf
	s_nop 1
	v_add_f32_dpp v246, v246, v246 row_mirror row_mask:0xf bank_mask:0xf
	s_mov_b64 exec, s[48:49]
	global_store_dword v249, v246, s[34:35] offset:1280
	s_mov_b64 exec, -1
	s_waitcnt vmcnt(63) lgkmcnt(1)
	v_pk_add_f32 v[122:123], v[228:229], v[122:123]
	v_pk_add_f32 v[124:125], v[230:231], v[124:125]
	v_pk_mul_f32 v[232:233], v[122:123], v[122:123]
	v_pk_mul_f32 v[234:235], v[124:125], v[124:125]
	ds_read_b128 v[228:231], v210 offset:8192
	v_add_f32_e32 v236, v232, v233
	v_add_f32_e32 v236, v234, v236
	v_add_f32_e32 v236, v235, v236
	global_store_dwordx4 v247, v[122:125], s[38:39] sc1
	v_cvt_pk_bf16_f32 v232, v122, v123
	v_cvt_pk_bf16_f32 v233, v124, v125
	v_add_f32_dpp v236, v236, v236 quad_perm:[1,0,3,2] row_mask:0xf bank_mask:0xf
	global_store_dwordx2 v248, v[232:233], s[50:51] sc1
	s_add_u32 s38, s38, 0x4000
	s_addc_u32 s39, s39, 0
	v_add_f32_dpp v236, v236, v236 quad_perm:[2,3,0,1] row_mask:0xf bank_mask:0xf
	s_add_u32 s50, s50, 0x2000
	s_addc_u32 s51, s51, 0
	v_add_f32_dpp v236, v236, v236 row_half_mirror row_mask:0xf bank_mask:0xf
	s_nop 1
	v_add_f32_dpp v236, v236, v236 row_mirror row_mask:0xf bank_mask:0xf
	s_mov_b64 exec, s[48:49]
	global_store_dword v249, v236, s[34:35] offset:1536
	s_mov_b64 exec, -1
	s_waitcnt vmcnt(63) lgkmcnt(1)
	v_pk_add_f32 v[126:127], v[238:239], v[126:127]
	v_pk_add_f32 v[128:129], v[240:241], v[128:129]
	v_pk_mul_f32 v[242:243], v[126:127], v[126:127]
	v_pk_mul_f32 v[244:245], v[128:129], v[128:129]
	ds_read_b128 v[238:241], v211 offset:9216
	v_add_f32_e32 v246, v242, v243
	v_add_f32_e32 v246, v244, v246
	v_add_f32_e32 v246, v245, v246
	global_store_dwordx4 v247, v[126:129], s[38:39] sc1
	v_cvt_pk_bf16_f32 v242, v126, v127
	v_cvt_pk_bf16_f32 v243, v128, v129
	v_add_f32_dpp v246, v246, v246 quad_perm:[1,0,3,2] row_mask:0xf bank_mask:0xf
	global_store_dwordx2 v248, v[242:243], s[50:51] sc1
	s_add_u32 s38, s38, 0x4000
	s_addc_u32 s39, s39, 0
	v_add_f32_dpp v246, v246, v246 quad_perm:[2,3,0,1] row_mask:0xf bank_mask:0xf
	s_add_u32 s50, s50, 0x2000
	s_addc_u32 s51, s51, 0
	v_add_f32_dpp v246, v246, v246 row_half_mirror row_mask:0xf bank_mask:0xf
	s_nop 1
	v_add_f32_dpp v246, v246, v246 row_mirror row_mask:0xf bank_mask:0xf
	s_mov_b64 exec, s[48:49]
	global_store_dword v249, v246, s[34:35] offset:1792
	s_mov_b64 exec, -1
	s_waitcnt vmcnt(63) lgkmcnt(1)
	v_pk_add_f32 v[82:83], v[228:229], v[82:83]
	v_pk_add_f32 v[84:85], v[230:231], v[84:85]
	v_pk_mul_f32 v[232:233], v[82:83], v[82:83]
	v_pk_mul_f32 v[234:235], v[84:85], v[84:85]
	ds_read_b128 v[228:231], v215 offset:10240
	v_add_f32_e32 v236, v232, v233
	v_add_f32_e32 v236, v234, v236
	v_add_f32_e32 v236, v235, v236
	global_store_dwordx4 v247, v[82:85], s[38:39] sc1
	v_cvt_pk_bf16_f32 v232, v82, v83
	v_cvt_pk_bf16_f32 v233, v84, v85
	v_add_f32_dpp v236, v236, v236 quad_perm:[1,0,3,2] row_mask:0xf bank_mask:0xf
	global_store_dwordx2 v248, v[232:233], s[50:51] sc1
	s_add_u32 s38, s38, 0x4000
	s_addc_u32 s39, s39, 0
	v_add_f32_dpp v236, v236, v236 quad_perm:[2,3,0,1] row_mask:0xf bank_mask:0xf
	s_add_u32 s50, s50, 0x2000
	s_addc_u32 s51, s51, 0
	v_add_f32_dpp v236, v236, v236 row_half_mirror row_mask:0xf bank_mask:0xf
	s_nop 1
	v_add_f32_dpp v236, v236, v236 row_mirror row_mask:0xf bank_mask:0xf
	s_mov_b64 exec, s[48:49]
	global_store_dword v249, v236, s[34:35] offset:2048
	s_mov_b64 exec, -1
	s_waitcnt vmcnt(63) lgkmcnt(1)
	v_pk_add_f32 v[86:87], v[238:239], v[86:87]
	v_pk_add_f32 v[88:89], v[240:241], v[88:89]
	v_pk_mul_f32 v[242:243], v[86:87], v[86:87]
	v_pk_mul_f32 v[244:245], v[88:89], v[88:89]
	ds_read_b128 v[238:241], v237 offset:11264
	v_add_f32_e32 v246, v242, v243
	v_add_f32_e32 v246, v244, v246
	v_add_f32_e32 v246, v245, v246
	global_store_dwordx4 v247, v[86:89], s[38:39] sc1
	v_cvt_pk_bf16_f32 v242, v86, v87
	v_cvt_pk_bf16_f32 v243, v88, v89
	v_add_f32_dpp v246, v246, v246 quad_perm:[1,0,3,2] row_mask:0xf bank_mask:0xf
	global_store_dwordx2 v248, v[242:243], s[50:51] sc1
	s_add_u32 s38, s38, 0x4000
	s_addc_u32 s39, s39, 0
	v_add_f32_dpp v246, v246, v246 quad_perm:[2,3,0,1] row_mask:0xf bank_mask:0xf
	s_add_u32 s50, s50, 0x2000
	s_addc_u32 s51, s51, 0
	v_add_f32_dpp v246, v246, v246 row_half_mirror row_mask:0xf bank_mask:0xf
	s_nop 1
	v_add_f32_dpp v246, v246, v246 row_mirror row_mask:0xf bank_mask:0xf
	s_mov_b64 exec, s[48:49]
	global_store_dword v249, v246, s[34:35] offset:2304
	s_mov_b64 exec, -1
	s_waitcnt vmcnt(63) lgkmcnt(1)
	v_pk_add_f32 v[90:91], v[228:229], v[90:91]
	v_pk_add_f32 v[92:93], v[230:231], v[92:93]
	v_pk_mul_f32 v[232:233], v[90:91], v[90:91]
	v_pk_mul_f32 v[234:235], v[92:93], v[92:93]
	ds_read_b128 v[228:231], v210 offset:12288
	v_add_f32_e32 v236, v232, v233
	v_add_f32_e32 v236, v234, v236
	v_add_f32_e32 v236, v235, v236
	global_store_dwordx4 v247, v[90:93], s[38:39] sc1
	v_cvt_pk_bf16_f32 v232, v90, v91
	v_cvt_pk_bf16_f32 v233, v92, v93
	v_add_f32_dpp v236, v236, v236 quad_perm:[1,0,3,2] row_mask:0xf bank_mask:0xf
	global_store_dwordx2 v248, v[232:233], s[50:51] sc1
	s_add_u32 s38, s38, 0x4000
	s_addc_u32 s39, s39, 0
	v_add_f32_dpp v236, v236, v236 quad_perm:[2,3,0,1] row_mask:0xf bank_mask:0xf
	s_add_u32 s50, s50, 0x2000
	s_addc_u32 s51, s51, 0
	v_add_f32_dpp v236, v236, v236 row_half_mirror row_mask:0xf bank_mask:0xf
	s_nop 1
	v_add_f32_dpp v236, v236, v236 row_mirror row_mask:0xf bank_mask:0xf
	s_mov_b64 exec, s[48:49]
	global_store_dword v249, v236, s[34:35] offset:2560
	s_mov_b64 exec, -1
	s_waitcnt vmcnt(63) lgkmcnt(1)
	v_pk_add_f32 v[94:95], v[238:239], v[94:95]
	v_pk_add_f32 v[96:97], v[240:241], v[96:97]
	v_pk_mul_f32 v[242:243], v[94:95], v[94:95]
	v_pk_mul_f32 v[244:245], v[96:97], v[96:97]
	ds_read_b128 v[238:241], v211 offset:13312
	v_add_f32_e32 v246, v242, v243
	v_add_f32_e32 v246, v244, v246
	v_add_f32_e32 v246, v245, v246
	global_store_dwordx4 v247, v[94:97], s[38:39] sc1
	v_cvt_pk_bf16_f32 v242, v94, v95
	v_cvt_pk_bf16_f32 v243, v96, v97
	v_add_f32_dpp v246, v246, v246 quad_perm:[1,0,3,2] row_mask:0xf bank_mask:0xf
	global_store_dwordx2 v248, v[242:243], s[50:51] sc1
	s_add_u32 s38, s38, 0x4000
	s_addc_u32 s39, s39, 0
	v_add_f32_dpp v246, v246, v246 quad_perm:[2,3,0,1] row_mask:0xf bank_mask:0xf
	s_add_u32 s50, s50, 0x2000
	s_addc_u32 s51, s51, 0
	v_add_f32_dpp v246, v246, v246 row_half_mirror row_mask:0xf bank_mask:0xf
	s_nop 1
	v_add_f32_dpp v246, v246, v246 row_mirror row_mask:0xf bank_mask:0xf
	s_mov_b64 exec, s[48:49]
	global_store_dword v249, v246, s[34:35] offset:2816
	s_mov_b64 exec, -1
	s_waitcnt vmcnt(63) lgkmcnt(1)
	v_pk_add_f32 v[98:99], v[228:229], v[98:99]
	v_pk_add_f32 v[100:101], v[230:231], v[100:101]
	v_pk_mul_f32 v[232:233], v[98:99], v[98:99]
	v_pk_mul_f32 v[234:235], v[100:101], v[100:101]
	ds_read_b128 v[228:231], v215 offset:14336
	v_add_f32_e32 v236, v232, v233
	v_add_f32_e32 v236, v234, v236
	v_add_f32_e32 v236, v235, v236
	global_store_dwordx4 v247, v[98:101], s[38:39] sc1
	v_cvt_pk_bf16_f32 v232, v98, v99
	v_cvt_pk_bf16_f32 v233, v100, v101
	v_add_f32_dpp v236, v236, v236 quad_perm:[1,0,3,2] row_mask:0xf bank_mask:0xf
	global_store_dwordx2 v248, v[232:233], s[50:51] sc1
	s_add_u32 s38, s38, 0x4000
	s_addc_u32 s39, s39, 0
	v_add_f32_dpp v236, v236, v236 quad_perm:[2,3,0,1] row_mask:0xf bank_mask:0xf
	s_add_u32 s50, s50, 0x2000
	s_addc_u32 s51, s51, 0
	v_add_f32_dpp v236, v236, v236 row_half_mirror row_mask:0xf bank_mask:0xf
	s_nop 1
	v_add_f32_dpp v236, v236, v236 row_mirror row_mask:0xf bank_mask:0xf
	s_mov_b64 exec, s[48:49]
	global_store_dword v249, v236, s[34:35] offset:3072
	s_mov_b64 exec, -1
	s_waitcnt vmcnt(63) lgkmcnt(1)
	v_pk_add_f32 v[102:103], v[238:239], v[102:103]
	v_pk_add_f32 v[104:105], v[240:241], v[104:105]
	v_pk_mul_f32 v[242:243], v[102:103], v[102:103]
	v_pk_mul_f32 v[244:245], v[104:105], v[104:105]
	ds_read_b128 v[238:241], v237 offset:15360
	v_add_f32_e32 v246, v242, v243
	v_add_f32_e32 v246, v244, v246
	v_add_f32_e32 v246, v245, v246
	global_store_dwordx4 v247, v[102:105], s[38:39] sc1
	v_cvt_pk_bf16_f32 v242, v102, v103
	v_cvt_pk_bf16_f32 v243, v104, v105
	v_add_f32_dpp v246, v246, v246 quad_perm:[1,0,3,2] row_mask:0xf bank_mask:0xf
	global_store_dwordx2 v248, v[242:243], s[50:51] sc1
	s_add_u32 s38, s38, 0x4000
	s_addc_u32 s39, s39, 0
	v_add_f32_dpp v246, v246, v246 quad_perm:[2,3,0,1] row_mask:0xf bank_mask:0xf
	s_add_u32 s50, s50, 0x2000
	s_addc_u32 s51, s51, 0
	v_add_f32_dpp v246, v246, v246 row_half_mirror row_mask:0xf bank_mask:0xf
	s_nop 1
	v_add_f32_dpp v246, v246, v246 row_mirror row_mask:0xf bank_mask:0xf
	s_mov_b64 exec, s[48:49]
	global_store_dword v249, v246, s[34:35] offset:3328
	s_mov_b64 exec, -1
	s_waitcnt vmcnt(63) lgkmcnt(1)
	v_pk_add_f32 v[106:107], v[228:229], v[106:107]
	v_pk_add_f32 v[108:109], v[230:231], v[108:109]
	v_pk_mul_f32 v[232:233], v[106:107], v[106:107]
	v_pk_mul_f32 v[234:235], v[108:109], v[108:109]
	v_add_f32_e32 v236, v232, v233
	v_add_f32_e32 v236, v234, v236
	v_add_f32_e32 v236, v235, v236
	global_store_dwordx4 v247, v[106:109], s[38:39] sc1
	v_cvt_pk_bf16_f32 v232, v106, v107
	v_cvt_pk_bf16_f32 v233, v108, v109
	v_add_f32_dpp v236, v236, v236 quad_perm:[1,0,3,2] row_mask:0xf bank_mask:0xf
	global_store_dwordx2 v248, v[232:233], s[50:51] sc1
	s_add_u32 s38, s38, 0x4000
	s_addc_u32 s39, s39, 0
	v_add_f32_dpp v236, v236, v236 quad_perm:[2,3,0,1] row_mask:0xf bank_mask:0xf
	s_add_u32 s50, s50, 0x2000
	s_addc_u32 s51, s51, 0
	v_add_f32_dpp v236, v236, v236 row_half_mirror row_mask:0xf bank_mask:0xf
	s_nop 1
	v_add_f32_dpp v236, v236, v236 row_mirror row_mask:0xf bank_mask:0xf
	s_mov_b64 exec, s[48:49]
	global_store_dword v249, v236, s[34:35] offset:3584
	s_mov_b64 exec, -1
	s_waitcnt vmcnt(63) lgkmcnt(0)
	v_pk_add_f32 v[110:111], v[238:239], v[110:111]
	v_pk_add_f32 v[112:113], v[240:241], v[112:113]
	v_pk_mul_f32 v[242:243], v[110:111], v[110:111]
	v_pk_mul_f32 v[244:245], v[112:113], v[112:113]
	v_add_f32_e32 v246, v242, v243
	v_add_f32_e32 v246, v244, v246
	v_add_f32_e32 v246, v245, v246
	global_store_dwordx4 v247, v[110:113], s[38:39] sc1
	v_cvt_pk_bf16_f32 v242, v110, v111
	v_cvt_pk_bf16_f32 v243, v112, v113
	v_add_f32_dpp v246, v246, v246 quad_perm:[1,0,3,2] row_mask:0xf bank_mask:0xf
	global_store_dwordx2 v248, v[242:243], s[50:51] sc1
	s_add_u32 s38, s38, 0x4000
	s_addc_u32 s39, s39, 0
	v_add_f32_dpp v246, v246, v246 quad_perm:[2,3,0,1] row_mask:0xf bank_mask:0xf
	s_add_u32 s50, s50, 0x2000
	s_addc_u32 s51, s51, 0
	v_add_f32_dpp v246, v246, v246 row_half_mirror row_mask:0xf bank_mask:0xf
	s_nop 1
	v_add_f32_dpp v246, v246, v246 row_mirror row_mask:0xf bank_mask:0xf
	s_mov_b64 exec, s[48:49]
	global_store_dword v249, v246, s[34:35] offset:3840
	s_mov_b64 exec, -1
	s_waitcnt lgkmcnt(0)
	s_branch .LBB0_1677
